# GEMM K-loops: redundant back-to-back s_setprio 0/1 pair inside each 32-MFMA run removed
# speedup vs baseline: 1.0090x; 1.0090x over previous
.LBB0_270:
	s_ashr_i32 s25, s24, 31
	s_lshl_b64 s[22:23], s[24:25], 19
	s_add_u32 s26, s16, s22
	s_addc_u32 s27, s17, s23
	s_and_b64 s[22:23], s[4:5], exec
	s_cselect_b32 s25, s27, s15
	s_cselect_b32 s56, s26, s14
	s_ashr_i32 s21, s20, 31
	s_lshl_b64 s[22:23], s[20:21], 19
	s_add_u32 s28, s34, s22
	s_addc_u32 s29, s35, s23
	s_and_b64 s[22:23], s[4:5], exec
	s_cselect_b32 s21, s29, s3
	s_cselect_b32 s57, s28, s2
	s_add_u32 s14, s14, 0x40080
	s_addc_u32 s15, s15, 0
	s_add_u32 s58, s2, 0x100
	s_addc_u32 s59, s3, 0
	s_mov_b32 s64, -2
	s_waitcnt lgkmcnt(0)
	s_waitcnt vmcnt(0)
	ds_read_b128 v[136:139], v159
	ds_read_b128 v[164:167], v159 offset:1024
	ds_read_b128 v[180:183], v159 offset:2048
	ds_read_b128 v[184:187], v159 offset:3072
	ds_read_b128 v[188:191], v160
	ds_read_b128 v[196:199], v160 offset:1024
	ds_read_b128 v[200:203], v160 offset:2048
	ds_read_b128 v[204:207], v160 offset:3072
	s_add_u32 s2, s14, 0xfffc0080
	s_addc_u32 s3, s15, -1
	s_cmp_eq_u32 s64, 12
	s_cselect_b32 s23, s25, s3
	s_cselect_b32 s22, s56, s2
	s_cselect_b32 s3, s21, s59
	s_cselect_b32 s2, s57, s58
	v_lshl_add_u64 v[168:169], s[14:15], 0, v[128:129]
	s_add_i32 m0, s31, 0xc000
	ds_read_b128 v[208:211], v161
	ds_read_b128 v[212:215], v161 offset:1024
	ds_read_b128 v[216:219], v161 offset:2048
	ds_read_b128 v[220:223], v161 offset:3072
	ds_read_b128 v[224:227], v161 offset:4096
	ds_read_b128 v[228:231], v161 offset:5120
	ds_read_b128 v[232:235], v161 offset:6144
	ds_read_b128 v[236:239], v161 offset:7168
	global_load_lds_dwordx4 v[168:169], off
	v_lshl_add_u64 v[168:169], s[14:15], 0, v[130:131]
	s_add_i32 m0, s31, 0xe000
	s_nop 0
	global_load_lds_dwordx4 v[168:169], off
	s_waitcnt vmcnt(8)
	s_waitcnt lgkmcnt(0)
	s_barrier
	s_setprio 1
	s_waitcnt lgkmcnt(0)
	v_mfma_f32_16x16x32_bf16 v[116:119], v[136:139], v[208:211], 0
	v_mfma_f32_16x16x32_bf16 v[112:115], v[180:183], v[208:211], 0
	v_mfma_f32_16x16x32_bf16 v[108:111], v[136:139], v[216:219], 0
	v_mfma_f32_16x16x32_bf16 v[104:107], v[180:183], v[216:219], 0
	v_mfma_f32_16x16x32_bf16 v[92:95], v[136:139], v[224:227], 0
	v_mfma_f32_16x16x32_bf16 v[88:91], v[180:183], v[224:227], 0
	v_mfma_f32_16x16x32_bf16 v[76:79], v[136:139], v[232:235], 0
	v_mfma_f32_16x16x32_bf16 v[72:75], v[180:183], v[232:235], 0
	v_mfma_f32_16x16x32_bf16 v[116:119], v[164:167], v[212:215], v[116:119]
	v_mfma_f32_16x16x32_bf16 v[112:115], v[184:187], v[212:215], v[112:115]
	v_mfma_f32_16x16x32_bf16 v[108:111], v[164:167], v[220:223], v[108:111]
	v_mfma_f32_16x16x32_bf16 v[104:107], v[184:187], v[220:223], v[104:107]
	v_mfma_f32_16x16x32_bf16 v[92:95], v[164:167], v[228:231], v[92:95]
	v_mfma_f32_16x16x32_bf16 v[88:91], v[184:187], v[228:231], v[88:91]
	v_mfma_f32_16x16x32_bf16 v[76:79], v[164:167], v[236:239], v[76:79]
	v_mfma_f32_16x16x32_bf16 v[72:75], v[184:187], v[236:239], v[72:75]
	v_mfma_f32_16x16x32_bf16 v[124:127], v[188:191], v[208:211], 0
	v_mfma_f32_16x16x32_bf16 v[120:123], v[200:203], v[208:211], 0
	v_mfma_f32_16x16x32_bf16 v[100:103], v[188:191], v[216:219], 0
	v_mfma_f32_16x16x32_bf16 v[96:99], v[200:203], v[216:219], 0
	v_mfma_f32_16x16x32_bf16 v[84:87], v[188:191], v[224:227], 0
	v_mfma_f32_16x16x32_bf16 v[80:83], v[200:203], v[224:227], 0
	v_mfma_f32_16x16x32_bf16 v[68:71], v[188:191], v[232:235], 0
	v_mfma_f32_16x16x32_bf16 v[64:67], v[200:203], v[232:235], 0
	v_mfma_f32_16x16x32_bf16 v[124:127], v[196:199], v[212:215], v[124:127]
	v_mfma_f32_16x16x32_bf16 v[120:123], v[204:207], v[212:215], v[120:123]
	v_mfma_f32_16x16x32_bf16 v[100:103], v[196:199], v[220:223], v[100:103]
	v_mfma_f32_16x16x32_bf16 v[96:99], v[204:207], v[220:223], v[96:99]
	v_mfma_f32_16x16x32_bf16 v[84:87], v[196:199], v[228:231], v[84:87]
	v_mfma_f32_16x16x32_bf16 v[80:83], v[204:207], v[228:231], v[80:83]
	v_mfma_f32_16x16x32_bf16 v[68:71], v[196:199], v[236:239], v[68:71]
	v_mfma_f32_16x16x32_bf16 v[64:67], v[204:207], v[236:239], v[64:67]
	s_setprio 0
	s_barrier
	s_add_i32 s65, s49, s37
	v_lshl_add_u64 v[168:169], s[2:3], 0, v[142:143]
	s_mov_b32 m0, s65
	ds_read_b128 v[208:211], v161 offset:16384
	ds_read_b128 v[212:215], v161 offset:17408
	ds_read_b128 v[216:219], v161 offset:18432
	ds_read_b128 v[220:223], v161 offset:19456
	ds_read_b128 v[224:227], v161 offset:20480
	ds_read_b128 v[228:231], v161 offset:21504
	ds_read_b128 v[232:235], v161 offset:22528
	ds_read_b128 v[236:239], v161 offset:23552
	global_load_lds_dwordx4 v[168:169], off
	s_add_i32 m0, s65, 0x2000
	s_add_u32 s66, s2, 0x40000
	v_lshl_add_u64 v[192:193], s[2:3], 0, v[146:147]
	s_addc_u32 s67, s3, 0
	s_add_i32 s65, s50, s37
	global_load_lds_dwordx4 v[192:193], off
	v_lshl_add_u64 v[240:241], s[66:67], 0, v[142:143]
	s_mov_b32 m0, s65
	v_lshl_add_u64 v[242:243], s[22:23], 0, v[144:145]
	global_load_lds_dwordx4 v[240:241], off
	v_lshl_add_u64 v[240:241], s[66:67], 0, v[146:147]
	s_add_i32 m0, s65, 0x2000
	s_nop 0
	global_load_lds_dwordx4 v[240:241], off
	v_lshl_add_u64 v[240:241], s[22:23], 0, v[140:141]
	s_mov_b32 m0, s31
	s_nop 0
	global_load_lds_dwordx4 v[240:241], off
	s_mov_b32 m0, s38
	s_nop 0
	global_load_lds_dwordx4 v[242:243], off
	s_waitcnt vmcnt(8)
	s_waitcnt lgkmcnt(0)
	s_barrier
	s_setprio 1
	s_waitcnt lgkmcnt(0)
	v_mfma_f32_16x16x32_bf16 v[52:55], v[136:139], v[208:211], 0
	v_mfma_f32_16x16x32_bf16 v[48:51], v[180:183], v[208:211], 0
	v_mfma_f32_16x16x32_bf16 v[44:47], v[136:139], v[216:219], 0
	v_mfma_f32_16x16x32_bf16 v[40:43], v[180:183], v[216:219], 0
	v_mfma_f32_16x16x32_bf16 v[28:31], v[136:139], v[224:227], 0
	v_mfma_f32_16x16x32_bf16 v[24:27], v[180:183], v[224:227], 0
	v_mfma_f32_16x16x32_bf16 v[12:15], v[136:139], v[232:235], 0
	v_mfma_f32_16x16x32_bf16 v[8:11], v[180:183], v[232:235], 0
	v_mfma_f32_16x16x32_bf16 v[52:55], v[164:167], v[212:215], v[52:55]
	v_mfma_f32_16x16x32_bf16 v[48:51], v[184:187], v[212:215], v[48:51]
	v_mfma_f32_16x16x32_bf16 v[44:47], v[164:167], v[220:223], v[44:47]
	v_mfma_f32_16x16x32_bf16 v[40:43], v[184:187], v[220:223], v[40:43]
	v_mfma_f32_16x16x32_bf16 v[28:31], v[164:167], v[228:231], v[28:31]
	v_mfma_f32_16x16x32_bf16 v[24:27], v[184:187], v[228:231], v[24:27]
	v_mfma_f32_16x16x32_bf16 v[12:15], v[164:167], v[236:239], v[12:15]
	v_mfma_f32_16x16x32_bf16 v[8:11], v[184:187], v[236:239], v[8:11]
	v_mfma_f32_16x16x32_bf16 v[60:63], v[188:191], v[208:211], 0
	v_mfma_f32_16x16x32_bf16 v[56:59], v[200:203], v[208:211], 0
	v_mfma_f32_16x16x32_bf16 v[36:39], v[188:191], v[216:219], 0
	v_mfma_f32_16x16x32_bf16 v[32:35], v[200:203], v[216:219], 0
	v_mfma_f32_16x16x32_bf16 v[20:23], v[188:191], v[224:227], 0
	v_mfma_f32_16x16x32_bf16 v[16:19], v[200:203], v[224:227], 0
	v_mfma_f32_16x16x32_bf16 v[4:7], v[188:191], v[232:235], 0
	v_mfma_f32_16x16x32_bf16 v[0:3], v[200:203], v[232:235], 0
	v_mfma_f32_16x16x32_bf16 v[60:63], v[196:199], v[212:215], v[60:63]
	v_mfma_f32_16x16x32_bf16 v[56:59], v[204:207], v[212:215], v[56:59]
	v_mfma_f32_16x16x32_bf16 v[36:39], v[196:199], v[220:223], v[36:39]
	v_mfma_f32_16x16x32_bf16 v[32:35], v[204:207], v[220:223], v[32:35]
	v_mfma_f32_16x16x32_bf16 v[20:23], v[196:199], v[228:231], v[20:23]
	v_mfma_f32_16x16x32_bf16 v[16:19], v[204:207], v[228:231], v[16:19]
	v_mfma_f32_16x16x32_bf16 v[4:7], v[196:199], v[236:239], v[4:7]
	v_mfma_f32_16x16x32_bf16 v[0:3], v[204:207], v[236:239], v[0:3]
	s_setprio 0
	s_barrier
	s_add_i32 s65, 0, 0x18000
	v_add_u32_e32 v163, s65, v156
	s_add_i32 s66, 0, 0x1c000
	ds_read_b128 v[136:139], v163
	ds_read_b128 v[164:167], v163 offset:1024
	ds_read_b128 v[180:183], v163 offset:2048
	ds_read_b128 v[184:187], v163 offset:3072
	v_add_u32_e32 v163, s66, v156
	ds_read_b128 v[188:191], v163
	ds_read_b128 v[196:199], v163 offset:1024
	ds_read_b128 v[200:203], v163 offset:2048
	ds_read_b128 v[204:207], v163 offset:3072
	s_add_u32 s22, s22, 0x40000
	s_addc_u32 s23, s23, 0
	s_mov_b32 m0, s39
	v_lshl_add_u64 v[244:245], s[22:23], 0, v[140:141]
	ds_read_b128 v[208:211], v161 offset:32768
	ds_read_b128 v[212:215], v161 offset:33792
	ds_read_b128 v[216:219], v161 offset:34816
	ds_read_b128 v[220:223], v161 offset:35840
	ds_read_b128 v[224:227], v161 offset:36864
	ds_read_b128 v[228:231], v161 offset:37888
	ds_read_b128 v[232:235], v161 offset:38912
	ds_read_b128 v[236:239], v161 offset:39936
	global_load_lds_dwordx4 v[244:245], off
	v_lshl_add_u64 v[244:245], s[22:23], 0, v[144:145]
	s_mov_b32 m0, s40
	s_nop 0
	global_load_lds_dwordx4 v[244:245], off
	s_waitcnt vmcnt(8)
	s_waitcnt lgkmcnt(0)
	s_barrier
	s_setprio 1
	s_waitcnt lgkmcnt(0)
	v_mfma_f32_16x16x32_bf16 v[116:119], v[136:139], v[208:211], v[116:119]
	v_mfma_f32_16x16x32_bf16 v[112:115], v[180:183], v[208:211], v[112:115]
	v_mfma_f32_16x16x32_bf16 v[108:111], v[136:139], v[216:219], v[108:111]
	v_mfma_f32_16x16x32_bf16 v[104:107], v[180:183], v[216:219], v[104:107]
	v_mfma_f32_16x16x32_bf16 v[92:95], v[136:139], v[224:227], v[92:95]
	v_mfma_f32_16x16x32_bf16 v[88:91], v[180:183], v[224:227], v[88:91]
	v_mfma_f32_16x16x32_bf16 v[76:79], v[136:139], v[232:235], v[76:79]
	v_mfma_f32_16x16x32_bf16 v[72:75], v[180:183], v[232:235], v[72:75]
	v_mfma_f32_16x16x32_bf16 v[116:119], v[164:167], v[212:215], v[116:119]
	v_mfma_f32_16x16x32_bf16 v[112:115], v[184:187], v[212:215], v[112:115]
	v_mfma_f32_16x16x32_bf16 v[108:111], v[164:167], v[220:223], v[108:111]
	v_mfma_f32_16x16x32_bf16 v[104:107], v[184:187], v[220:223], v[104:107]
	v_mfma_f32_16x16x32_bf16 v[92:95], v[164:167], v[228:231], v[92:95]
	v_mfma_f32_16x16x32_bf16 v[88:91], v[184:187], v[228:231], v[88:91]
	v_mfma_f32_16x16x32_bf16 v[76:79], v[164:167], v[236:239], v[76:79]
	v_mfma_f32_16x16x32_bf16 v[72:75], v[184:187], v[236:239], v[72:75]
	v_mfma_f32_16x16x32_bf16 v[124:127], v[188:191], v[208:211], v[124:127]
	v_mfma_f32_16x16x32_bf16 v[120:123], v[200:203], v[208:211], v[120:123]
	v_mfma_f32_16x16x32_bf16 v[100:103], v[188:191], v[216:219], v[100:103]
	v_mfma_f32_16x16x32_bf16 v[96:99], v[200:203], v[216:219], v[96:99]
	v_mfma_f32_16x16x32_bf16 v[84:87], v[188:191], v[224:227], v[84:87]
	v_mfma_f32_16x16x32_bf16 v[80:83], v[200:203], v[224:227], v[80:83]
	v_mfma_f32_16x16x32_bf16 v[68:71], v[188:191], v[232:235], v[68:71]
	v_mfma_f32_16x16x32_bf16 v[64:67], v[200:203], v[232:235], v[64:67]
	v_mfma_f32_16x16x32_bf16 v[124:127], v[196:199], v[212:215], v[124:127]
	v_mfma_f32_16x16x32_bf16 v[120:123], v[204:207], v[212:215], v[120:123]
	v_mfma_f32_16x16x32_bf16 v[100:103], v[196:199], v[220:223], v[100:103]
	v_mfma_f32_16x16x32_bf16 v[96:99], v[204:207], v[220:223], v[96:99]
	v_mfma_f32_16x16x32_bf16 v[84:87], v[196:199], v[228:231], v[84:87]
	v_mfma_f32_16x16x32_bf16 v[80:83], v[204:207], v[228:231], v[80:83]
	v_mfma_f32_16x16x32_bf16 v[68:71], v[196:199], v[236:239], v[68:71]
	v_mfma_f32_16x16x32_bf16 v[64:67], v[204:207], v[236:239], v[64:67]
	s_setprio 0
	s_barrier
	s_add_i32 s22, s65, s37
	v_lshl_add_u64 v[168:169], v[168:169], 0, s[10:11]
	s_mov_b32 m0, s22
	ds_read_b128 v[208:211], v161 offset:49152
	ds_read_b128 v[212:215], v161 offset:50176
	ds_read_b128 v[216:219], v161 offset:51200
	ds_read_b128 v[220:223], v161 offset:52224
	ds_read_b128 v[224:227], v161 offset:53248
	ds_read_b128 v[228:231], v161 offset:54272
	ds_read_b128 v[232:235], v161 offset:55296
	ds_read_b128 v[236:239], v161 offset:56320
	global_load_lds_dwordx4 v[168:169], off
	s_add_i32 m0, s22, 0x2000
	s_add_u32 s2, s2, 0x40080
	v_lshl_add_u64 v[168:169], v[192:193], 0, s[10:11]
	s_addc_u32 s3, s3, 0
	s_add_i32 s22, s66, s37
	global_load_lds_dwordx4 v[168:169], off
	v_lshl_add_u64 v[168:169], s[2:3], 0, v[142:143]
	s_mov_b32 m0, s22
	s_nop 0
	global_load_lds_dwordx4 v[168:169], off
	v_lshl_add_u64 v[168:169], s[2:3], 0, v[146:147]
	s_add_i32 m0, s22, 0x2000
	s_nop 0
	global_load_lds_dwordx4 v[168:169], off
	v_lshl_add_u64 v[168:169], v[240:241], 0, s[10:11]
	s_mov_b32 m0, s43
	s_nop 0
	global_load_lds_dwordx4 v[168:169], off
	v_lshl_add_u64 v[168:169], v[242:243], 0, s[10:11]
	s_mov_b32 m0, s44
	s_nop 0
	global_load_lds_dwordx4 v[168:169], off
	s_waitcnt vmcnt(8)
	s_waitcnt lgkmcnt(0)
	s_barrier
	s_setprio 1
	s_waitcnt lgkmcnt(0)
	v_mfma_f32_16x16x32_bf16 v[52:55], v[136:139], v[208:211], v[52:55]
	v_mfma_f32_16x16x32_bf16 v[48:51], v[180:183], v[208:211], v[48:51]
	v_mfma_f32_16x16x32_bf16 v[44:47], v[136:139], v[216:219], v[44:47]
	v_mfma_f32_16x16x32_bf16 v[40:43], v[180:183], v[216:219], v[40:43]
	v_mfma_f32_16x16x32_bf16 v[28:31], v[136:139], v[224:227], v[28:31]
	v_mfma_f32_16x16x32_bf16 v[24:27], v[180:183], v[224:227], v[24:27]
	v_mfma_f32_16x16x32_bf16 v[12:15], v[136:139], v[232:235], v[12:15]
	v_mfma_f32_16x16x32_bf16 v[8:11], v[180:183], v[232:235], v[8:11]
	v_mfma_f32_16x16x32_bf16 v[52:55], v[164:167], v[212:215], v[52:55]
	v_mfma_f32_16x16x32_bf16 v[48:51], v[184:187], v[212:215], v[48:51]
	v_mfma_f32_16x16x32_bf16 v[44:47], v[164:167], v[220:223], v[44:47]
	v_mfma_f32_16x16x32_bf16 v[40:43], v[184:187], v[220:223], v[40:43]
	v_mfma_f32_16x16x32_bf16 v[28:31], v[164:167], v[228:231], v[28:31]
	v_mfma_f32_16x16x32_bf16 v[24:27], v[184:187], v[228:231], v[24:27]
	v_mfma_f32_16x16x32_bf16 v[12:15], v[164:167], v[236:239], v[12:15]
	v_mfma_f32_16x16x32_bf16 v[8:11], v[184:187], v[236:239], v[8:11]
	v_mfma_f32_16x16x32_bf16 v[60:63], v[188:191], v[208:211], v[60:63]
	v_mfma_f32_16x16x32_bf16 v[56:59], v[200:203], v[208:211], v[56:59]
	v_mfma_f32_16x16x32_bf16 v[36:39], v[188:191], v[216:219], v[36:39]
	v_mfma_f32_16x16x32_bf16 v[32:35], v[200:203], v[216:219], v[32:35]
	v_mfma_f32_16x16x32_bf16 v[20:23], v[188:191], v[224:227], v[20:23]
	v_mfma_f32_16x16x32_bf16 v[16:19], v[200:203], v[224:227], v[16:19]
	v_mfma_f32_16x16x32_bf16 v[4:7], v[188:191], v[232:235], v[4:7]
	v_mfma_f32_16x16x32_bf16 v[0:3], v[200:203], v[232:235], v[0:3]
	v_mfma_f32_16x16x32_bf16 v[60:63], v[196:199], v[212:215], v[60:63]
	v_mfma_f32_16x16x32_bf16 v[56:59], v[204:207], v[212:215], v[56:59]
	v_mfma_f32_16x16x32_bf16 v[36:39], v[196:199], v[220:223], v[36:39]
	v_mfma_f32_16x16x32_bf16 v[32:35], v[204:207], v[220:223], v[32:35]
	v_mfma_f32_16x16x32_bf16 v[20:23], v[196:199], v[228:231], v[20:23]
	v_mfma_f32_16x16x32_bf16 v[16:19], v[204:207], v[228:231], v[16:19]
	v_mfma_f32_16x16x32_bf16 v[4:7], v[196:199], v[236:239], v[4:7]
	v_mfma_f32_16x16x32_bf16 v[0:3], v[204:207], v[236:239], v[0:3]
	s_setprio 0
	s_barrier
	s_add_i32 s64, s64, 2
	s_add_u32 s14, s14, 0x100
	s_addc_u32 s15, s15, 0
	s_add_u32 s58, s58, 0x100
	s_addc_u32 s59, s59, 0
	s_cmp_gt_u32 s64, 13
	s_cbranch_scc1 .Lgemm_kdone_0
.LBB0_271:
	ds_read_b128 v[136:139], v159
	ds_read_b128 v[164:167], v159 offset:1024
	ds_read_b128 v[180:183], v159 offset:2048
	ds_read_b128 v[184:187], v159 offset:3072
	ds_read_b128 v[188:191], v160
	ds_read_b128 v[196:199], v160 offset:1024
	ds_read_b128 v[200:203], v160 offset:2048
	ds_read_b128 v[204:207], v160 offset:3072
	s_add_u32 s2, s14, 0xfffc0080
	s_addc_u32 s3, s15, -1
	s_cmp_eq_u32 s64, 12
	s_cselect_b32 s23, s25, s3
	s_cselect_b32 s22, s56, s2
	s_cselect_b32 s3, s21, s59
	s_cselect_b32 s2, s57, s58
	v_lshl_add_u64 v[168:169], s[14:15], 0, v[128:129]
	s_add_i32 m0, s31, 0xc000
	ds_read_b128 v[208:211], v161
	ds_read_b128 v[212:215], v161 offset:1024
	ds_read_b128 v[216:219], v161 offset:2048
	ds_read_b128 v[220:223], v161 offset:3072
	ds_read_b128 v[224:227], v161 offset:4096
	ds_read_b128 v[228:231], v161 offset:5120
	ds_read_b128 v[232:235], v161 offset:6144
	ds_read_b128 v[236:239], v161 offset:7168
	global_load_lds_dwordx4 v[168:169], off
	v_lshl_add_u64 v[168:169], s[14:15], 0, v[130:131]
	s_add_i32 m0, s31, 0xe000
	s_nop 0
	global_load_lds_dwordx4 v[168:169], off
	s_waitcnt vmcnt(8)
	s_waitcnt lgkmcnt(0)
	s_barrier
	s_setprio 1
	s_waitcnt lgkmcnt(0)
	v_mfma_f32_16x16x32_bf16 v[116:119], v[136:139], v[208:211], v[116:119]
	v_mfma_f32_16x16x32_bf16 v[112:115], v[180:183], v[208:211], v[112:115]
	v_mfma_f32_16x16x32_bf16 v[108:111], v[136:139], v[216:219], v[108:111]
	v_mfma_f32_16x16x32_bf16 v[104:107], v[180:183], v[216:219], v[104:107]
	v_mfma_f32_16x16x32_bf16 v[92:95], v[136:139], v[224:227], v[92:95]
	v_mfma_f32_16x16x32_bf16 v[88:91], v[180:183], v[224:227], v[88:91]
	v_mfma_f32_16x16x32_bf16 v[76:79], v[136:139], v[232:235], v[76:79]
	v_mfma_f32_16x16x32_bf16 v[72:75], v[180:183], v[232:235], v[72:75]
	v_mfma_f32_16x16x32_bf16 v[116:119], v[164:167], v[212:215], v[116:119]
	v_mfma_f32_16x16x32_bf16 v[112:115], v[184:187], v[212:215], v[112:115]
	v_mfma_f32_16x16x32_bf16 v[108:111], v[164:167], v[220:223], v[108:111]
	v_mfma_f32_16x16x32_bf16 v[104:107], v[184:187], v[220:223], v[104:107]
	v_mfma_f32_16x16x32_bf16 v[92:95], v[164:167], v[228:231], v[92:95]
	v_mfma_f32_16x16x32_bf16 v[88:91], v[184:187], v[228:231], v[88:91]
	v_mfma_f32_16x16x32_bf16 v[76:79], v[164:167], v[236:239], v[76:79]
	v_mfma_f32_16x16x32_bf16 v[72:75], v[184:187], v[236:239], v[72:75]
	v_mfma_f32_16x16x32_bf16 v[124:127], v[188:191], v[208:211], v[124:127]
	v_mfma_f32_16x16x32_bf16 v[120:123], v[200:203], v[208:211], v[120:123]
	v_mfma_f32_16x16x32_bf16 v[100:103], v[188:191], v[216:219], v[100:103]
	v_mfma_f32_16x16x32_bf16 v[96:99], v[200:203], v[216:219], v[96:99]
	v_mfma_f32_16x16x32_bf16 v[84:87], v[188:191], v[224:227], v[84:87]
	v_mfma_f32_16x16x32_bf16 v[80:83], v[200:203], v[224:227], v[80:83]
	v_mfma_f32_16x16x32_bf16 v[68:71], v[188:191], v[232:235], v[68:71]
	v_mfma_f32_16x16x32_bf16 v[64:67], v[200:203], v[232:235], v[64:67]
	v_mfma_f32_16x16x32_bf16 v[124:127], v[196:199], v[212:215], v[124:127]
	v_mfma_f32_16x16x32_bf16 v[120:123], v[204:207], v[212:215], v[120:123]
	v_mfma_f32_16x16x32_bf16 v[100:103], v[196:199], v[220:223], v[100:103]
	v_mfma_f32_16x16x32_bf16 v[96:99], v[204:207], v[220:223], v[96:99]
	v_mfma_f32_16x16x32_bf16 v[84:87], v[196:199], v[228:231], v[84:87]
	v_mfma_f32_16x16x32_bf16 v[80:83], v[204:207], v[228:231], v[80:83]
	v_mfma_f32_16x16x32_bf16 v[68:71], v[196:199], v[236:239], v[68:71]
	v_mfma_f32_16x16x32_bf16 v[64:67], v[204:207], v[236:239], v[64:67]
	s_setprio 0
	s_barrier
	s_add_i32 s65, s49, s37
	v_lshl_add_u64 v[168:169], s[2:3], 0, v[142:143]
	s_mov_b32 m0, s65
	ds_read_b128 v[208:211], v161 offset:16384
	ds_read_b128 v[212:215], v161 offset:17408
	ds_read_b128 v[216:219], v161 offset:18432
	ds_read_b128 v[220:223], v161 offset:19456
	ds_read_b128 v[224:227], v161 offset:20480
	ds_read_b128 v[228:231], v161 offset:21504
	ds_read_b128 v[232:235], v161 offset:22528
	ds_read_b128 v[236:239], v161 offset:23552
	global_load_lds_dwordx4 v[168:169], off
	s_add_i32 m0, s65, 0x2000
	s_add_u32 s66, s2, 0x40000
	v_lshl_add_u64 v[192:193], s[2:3], 0, v[146:147]
	s_addc_u32 s67, s3, 0
	s_add_i32 s65, s50, s37
	global_load_lds_dwordx4 v[192:193], off
	v_lshl_add_u64 v[240:241], s[66:67], 0, v[142:143]
	s_mov_b32 m0, s65
	v_lshl_add_u64 v[242:243], s[22:23], 0, v[144:145]
	global_load_lds_dwordx4 v[240:241], off
	v_lshl_add_u64 v[240:241], s[66:67], 0, v[146:147]
	s_add_i32 m0, s65, 0x2000
	s_nop 0
	global_load_lds_dwordx4 v[240:241], off
	v_lshl_add_u64 v[240:241], s[22:23], 0, v[140:141]
	s_mov_b32 m0, s31
	s_nop 0
	global_load_lds_dwordx4 v[240:241], off
	s_mov_b32 m0, s38
	s_nop 0
	global_load_lds_dwordx4 v[242:243], off
	s_waitcnt vmcnt(8)
	s_waitcnt lgkmcnt(0)
	s_barrier
	s_setprio 1
	s_waitcnt lgkmcnt(0)
	v_mfma_f32_16x16x32_bf16 v[52:55], v[136:139], v[208:211], v[52:55]
	v_mfma_f32_16x16x32_bf16 v[48:51], v[180:183], v[208:211], v[48:51]
	v_mfma_f32_16x16x32_bf16 v[44:47], v[136:139], v[216:219], v[44:47]
	v_mfma_f32_16x16x32_bf16 v[40:43], v[180:183], v[216:219], v[40:43]
	v_mfma_f32_16x16x32_bf16 v[28:31], v[136:139], v[224:227], v[28:31]
	v_mfma_f32_16x16x32_bf16 v[24:27], v[180:183], v[224:227], v[24:27]
	v_mfma_f32_16x16x32_bf16 v[12:15], v[136:139], v[232:235], v[12:15]
	v_mfma_f32_16x16x32_bf16 v[8:11], v[180:183], v[232:235], v[8:11]
	v_mfma_f32_16x16x32_bf16 v[52:55], v[164:167], v[212:215], v[52:55]
	v_mfma_f32_16x16x32_bf16 v[48:51], v[184:187], v[212:215], v[48:51]
	v_mfma_f32_16x16x32_bf16 v[44:47], v[164:167], v[220:223], v[44:47]
	v_mfma_f32_16x16x32_bf16 v[40:43], v[184:187], v[220:223], v[40:43]
	v_mfma_f32_16x16x32_bf16 v[28:31], v[164:167], v[228:231], v[28:31]
	v_mfma_f32_16x16x32_bf16 v[24:27], v[184:187], v[228:231], v[24:27]
	v_mfma_f32_16x16x32_bf16 v[12:15], v[164:167], v[236:239], v[12:15]
	v_mfma_f32_16x16x32_bf16 v[8:11], v[184:187], v[236:239], v[8:11]
	v_mfma_f32_16x16x32_bf16 v[60:63], v[188:191], v[208:211], v[60:63]
	v_mfma_f32_16x16x32_bf16 v[56:59], v[200:203], v[208:211], v[56:59]
	v_mfma_f32_16x16x32_bf16 v[36:39], v[188:191], v[216:219], v[36:39]
	v_mfma_f32_16x16x32_bf16 v[32:35], v[200:203], v[216:219], v[32:35]
	v_mfma_f32_16x16x32_bf16 v[20:23], v[188:191], v[224:227], v[20:23]
	v_mfma_f32_16x16x32_bf16 v[16:19], v[200:203], v[224:227], v[16:19]
	v_mfma_f32_16x16x32_bf16 v[4:7], v[188:191], v[232:235], v[4:7]
	v_mfma_f32_16x16x32_bf16 v[0:3], v[200:203], v[232:235], v[0:3]
	v_mfma_f32_16x16x32_bf16 v[60:63], v[196:199], v[212:215], v[60:63]
	v_mfma_f32_16x16x32_bf16 v[56:59], v[204:207], v[212:215], v[56:59]
	v_mfma_f32_16x16x32_bf16 v[36:39], v[196:199], v[220:223], v[36:39]
	v_mfma_f32_16x16x32_bf16 v[32:35], v[204:207], v[220:223], v[32:35]
	v_mfma_f32_16x16x32_bf16 v[20:23], v[196:199], v[228:231], v[20:23]
	v_mfma_f32_16x16x32_bf16 v[16:19], v[204:207], v[228:231], v[16:19]
	v_mfma_f32_16x16x32_bf16 v[4:7], v[196:199], v[236:239], v[4:7]
	v_mfma_f32_16x16x32_bf16 v[0:3], v[204:207], v[236:239], v[0:3]
	s_setprio 0
	s_barrier
	s_add_i32 s65, 0, 0x18000
	v_add_u32_e32 v163, s65, v156
	s_add_i32 s66, 0, 0x1c000
	ds_read_b128 v[136:139], v163
	ds_read_b128 v[164:167], v163 offset:1024
	ds_read_b128 v[180:183], v163 offset:2048
	ds_read_b128 v[184:187], v163 offset:3072
	v_add_u32_e32 v163, s66, v156
	ds_read_b128 v[188:191], v163
	ds_read_b128 v[196:199], v163 offset:1024
	ds_read_b128 v[200:203], v163 offset:2048
	ds_read_b128 v[204:207], v163 offset:3072
	s_add_u32 s22, s22, 0x40000
	s_addc_u32 s23, s23, 0
	s_mov_b32 m0, s39
	v_lshl_add_u64 v[244:245], s[22:23], 0, v[140:141]
	ds_read_b128 v[208:211], v161 offset:32768
	ds_read_b128 v[212:215], v161 offset:33792
	ds_read_b128 v[216:219], v161 offset:34816
	ds_read_b128 v[220:223], v161 offset:35840
	ds_read_b128 v[224:227], v161 offset:36864
	ds_read_b128 v[228:231], v161 offset:37888
	ds_read_b128 v[232:235], v161 offset:38912
	ds_read_b128 v[236:239], v161 offset:39936
	global_load_lds_dwordx4 v[244:245], off
	v_lshl_add_u64 v[244:245], s[22:23], 0, v[144:145]
	s_mov_b32 m0, s40
	s_nop 0
	global_load_lds_dwordx4 v[244:245], off
	s_waitcnt vmcnt(8)
	s_waitcnt lgkmcnt(0)
	s_barrier
	s_setprio 1
	s_waitcnt lgkmcnt(0)
	v_mfma_f32_16x16x32_bf16 v[116:119], v[136:139], v[208:211], v[116:119]
	v_mfma_f32_16x16x32_bf16 v[112:115], v[180:183], v[208:211], v[112:115]
	v_mfma_f32_16x16x32_bf16 v[108:111], v[136:139], v[216:219], v[108:111]
	v_mfma_f32_16x16x32_bf16 v[104:107], v[180:183], v[216:219], v[104:107]
	v_mfma_f32_16x16x32_bf16 v[92:95], v[136:139], v[224:227], v[92:95]
	v_mfma_f32_16x16x32_bf16 v[88:91], v[180:183], v[224:227], v[88:91]
	v_mfma_f32_16x16x32_bf16 v[76:79], v[136:139], v[232:235], v[76:79]
	v_mfma_f32_16x16x32_bf16 v[72:75], v[180:183], v[232:235], v[72:75]
	v_mfma_f32_16x16x32_bf16 v[116:119], v[164:167], v[212:215], v[116:119]
	v_mfma_f32_16x16x32_bf16 v[112:115], v[184:187], v[212:215], v[112:115]
	v_mfma_f32_16x16x32_bf16 v[108:111], v[164:167], v[220:223], v[108:111]
	v_mfma_f32_16x16x32_bf16 v[104:107], v[184:187], v[220:223], v[104:107]
	v_mfma_f32_16x16x32_bf16 v[92:95], v[164:167], v[228:231], v[92:95]
	v_mfma_f32_16x16x32_bf16 v[88:91], v[184:187], v[228:231], v[88:91]
	v_mfma_f32_16x16x32_bf16 v[76:79], v[164:167], v[236:239], v[76:79]
	v_mfma_f32_16x16x32_bf16 v[72:75], v[184:187], v[236:239], v[72:75]
	v_mfma_f32_16x16x32_bf16 v[124:127], v[188:191], v[208:211], v[124:127]
	v_mfma_f32_16x16x32_bf16 v[120:123], v[200:203], v[208:211], v[120:123]
	v_mfma_f32_16x16x32_bf16 v[100:103], v[188:191], v[216:219], v[100:103]
	v_mfma_f32_16x16x32_bf16 v[96:99], v[200:203], v[216:219], v[96:99]
	v_mfma_f32_16x16x32_bf16 v[84:87], v[188:191], v[224:227], v[84:87]
	v_mfma_f32_16x16x32_bf16 v[80:83], v[200:203], v[224:227], v[80:83]
	v_mfma_f32_16x16x32_bf16 v[68:71], v[188:191], v[232:235], v[68:71]
	v_mfma_f32_16x16x32_bf16 v[64:67], v[200:203], v[232:235], v[64:67]
	v_mfma_f32_16x16x32_bf16 v[124:127], v[196:199], v[212:215], v[124:127]
	v_mfma_f32_16x16x32_bf16 v[120:123], v[204:207], v[212:215], v[120:123]
	v_mfma_f32_16x16x32_bf16 v[100:103], v[196:199], v[220:223], v[100:103]
	v_mfma_f32_16x16x32_bf16 v[96:99], v[204:207], v[220:223], v[96:99]
	v_mfma_f32_16x16x32_bf16 v[84:87], v[196:199], v[228:231], v[84:87]
	v_mfma_f32_16x16x32_bf16 v[80:83], v[204:207], v[228:231], v[80:83]
	v_mfma_f32_16x16x32_bf16 v[68:71], v[196:199], v[236:239], v[68:71]
	v_mfma_f32_16x16x32_bf16 v[64:67], v[204:207], v[236:239], v[64:67]
	s_setprio 0
	s_barrier
	s_add_i32 s22, s65, s37
	v_lshl_add_u64 v[168:169], v[168:169], 0, s[10:11]
	s_mov_b32 m0, s22
	ds_read_b128 v[208:211], v161 offset:49152
	ds_read_b128 v[212:215], v161 offset:50176
	ds_read_b128 v[216:219], v161 offset:51200
	ds_read_b128 v[220:223], v161 offset:52224
	ds_read_b128 v[224:227], v161 offset:53248
	ds_read_b128 v[228:231], v161 offset:54272
	ds_read_b128 v[232:235], v161 offset:55296
	ds_read_b128 v[236:239], v161 offset:56320
	global_load_lds_dwordx4 v[168:169], off
	s_add_i32 m0, s22, 0x2000
	s_add_u32 s2, s2, 0x40080
	v_lshl_add_u64 v[168:169], v[192:193], 0, s[10:11]
	s_addc_u32 s3, s3, 0
	s_add_i32 s22, s66, s37
	global_load_lds_dwordx4 v[168:169], off
	v_lshl_add_u64 v[168:169], s[2:3], 0, v[142:143]
	s_mov_b32 m0, s22
	s_nop 0
	global_load_lds_dwordx4 v[168:169], off
	v_lshl_add_u64 v[168:169], s[2:3], 0, v[146:147]
	s_add_i32 m0, s22, 0x2000
	s_nop 0
	global_load_lds_dwordx4 v[168:169], off
	v_lshl_add_u64 v[168:169], v[240:241], 0, s[10:11]
	s_mov_b32 m0, s43
	s_nop 0
	global_load_lds_dwordx4 v[168:169], off
	v_lshl_add_u64 v[168:169], v[242:243], 0, s[10:11]
	s_mov_b32 m0, s44
	s_nop 0
	global_load_lds_dwordx4 v[168:169], off
	s_waitcnt vmcnt(8)
	s_waitcnt lgkmcnt(0)
	s_barrier
	s_setprio 1
	s_waitcnt lgkmcnt(0)
	v_mfma_f32_16x16x32_bf16 v[52:55], v[136:139], v[208:211], v[52:55]
	v_mfma_f32_16x16x32_bf16 v[48:51], v[180:183], v[208:211], v[48:51]
	v_mfma_f32_16x16x32_bf16 v[44:47], v[136:139], v[216:219], v[44:47]
	v_mfma_f32_16x16x32_bf16 v[40:43], v[180:183], v[216:219], v[40:43]
	v_mfma_f32_16x16x32_bf16 v[28:31], v[136:139], v[224:227], v[28:31]
	v_mfma_f32_16x16x32_bf16 v[24:27], v[180:183], v[224:227], v[24:27]
	v_mfma_f32_16x16x32_bf16 v[12:15], v[136:139], v[232:235], v[12:15]
	v_mfma_f32_16x16x32_bf16 v[8:11], v[180:183], v[232:235], v[8:11]
	v_mfma_f32_16x16x32_bf16 v[52:55], v[164:167], v[212:215], v[52:55]
	v_mfma_f32_16x16x32_bf16 v[48:51], v[184:187], v[212:215], v[48:51]
	v_mfma_f32_16x16x32_bf16 v[44:47], v[164:167], v[220:223], v[44:47]
	v_mfma_f32_16x16x32_bf16 v[40:43], v[184:187], v[220:223], v[40:43]
	v_mfma_f32_16x16x32_bf16 v[28:31], v[164:167], v[228:231], v[28:31]
	v_mfma_f32_16x16x32_bf16 v[24:27], v[184:187], v[228:231], v[24:27]
	v_mfma_f32_16x16x32_bf16 v[12:15], v[164:167], v[236:239], v[12:15]
	v_mfma_f32_16x16x32_bf16 v[8:11], v[184:187], v[236:239], v[8:11]
	v_mfma_f32_16x16x32_bf16 v[60:63], v[188:191], v[208:211], v[60:63]
	v_mfma_f32_16x16x32_bf16 v[56:59], v[200:203], v[208:211], v[56:59]
	v_mfma_f32_16x16x32_bf16 v[36:39], v[188:191], v[216:219], v[36:39]
	v_mfma_f32_16x16x32_bf16 v[32:35], v[200:203], v[216:219], v[32:35]
	v_mfma_f32_16x16x32_bf16 v[20:23], v[188:191], v[224:227], v[20:23]
	v_mfma_f32_16x16x32_bf16 v[16:19], v[200:203], v[224:227], v[16:19]
	v_mfma_f32_16x16x32_bf16 v[4:7], v[188:191], v[232:235], v[4:7]
	v_mfma_f32_16x16x32_bf16 v[0:3], v[200:203], v[232:235], v[0:3]
	v_mfma_f32_16x16x32_bf16 v[60:63], v[196:199], v[212:215], v[60:63]
	v_mfma_f32_16x16x32_bf16 v[56:59], v[204:207], v[212:215], v[56:59]
	v_mfma_f32_16x16x32_bf16 v[36:39], v[196:199], v[220:223], v[36:39]
	v_mfma_f32_16x16x32_bf16 v[32:35], v[204:207], v[220:223], v[32:35]
	v_mfma_f32_16x16x32_bf16 v[20:23], v[196:199], v[228:231], v[20:23]
	v_mfma_f32_16x16x32_bf16 v[16:19], v[204:207], v[228:231], v[16:19]
	v_mfma_f32_16x16x32_bf16 v[4:7], v[196:199], v[236:239], v[4:7]
	v_mfma_f32_16x16x32_bf16 v[0:3], v[204:207], v[236:239], v[0:3]
	s_setprio 0
	s_barrier
	s_add_i32 s64, s64, 2
	s_add_u32 s14, s14, 0x100
	s_addc_u32 s15, s15, 0
	s_add_u32 s58, s58, 0x100
	s_addc_u32 s59, s59, 0
	s_cmp_gt_u32 s64, 13
	s_cbranch_scc0 .LBB0_271

.LBB0_367:
	s_ashr_i32 s25, s24, 31
	s_lshl_b64 s[22:23], s[24:25], 19
	s_add_u32 s26, s84, s22
	s_addc_u32 s27, s85, s23
	s_and_b64 s[22:23], s[0:1], exec
	s_cselect_b32 s25, s27, s15
	s_cselect_b32 s50, s26, s14
	s_ashr_i32 s21, s20, 31
	s_lshl_b64 s[22:23], s[20:21], 19
	s_add_u32 s28, s30, s22
	s_addc_u32 s29, s31, s23
	s_and_b64 s[22:23], s[0:1], exec
	s_cselect_b32 s21, s29, s3
	s_cselect_b32 s51, s28, s2
	s_add_u32 s14, s14, 0x40080
	s_addc_u32 s15, s15, 0
	s_add_u32 s52, s2, 0x100
	s_addc_u32 s53, s3, 0
	s_mov_b32 s54, -2
	s_waitcnt vmcnt(0)
	ds_read_b128 v[158:161], v154
	ds_read_b128 v[162:165], v154 offset:1024
	ds_read_b128 v[166:169], v154 offset:2048
	ds_read_b128 v[182:185], v154 offset:3072
	ds_read_b128 v[186:189], v155
	ds_read_b128 v[190:193], v155 offset:1024
	ds_read_b128 v[196:199], v155 offset:2048
	ds_read_b128 v[200:203], v155 offset:3072
	s_add_u32 s2, s14, 0xfffc0080
	s_addc_u32 s3, s15, -1
	s_cmp_eq_u32 s54, 12
	s_cselect_b32 s23, s25, s3
	s_cselect_b32 s22, s50, s2
	s_cselect_b32 s3, s21, s53
	s_cselect_b32 s2, s51, s52
	v_lshl_add_u64 v[136:137], s[14:15], 0, v[128:129]
	s_add_i32 m0, s37, 0xc000
	ds_read_b128 v[204:207], v156
	ds_read_b128 v[208:211], v156 offset:1024
	ds_read_b128 v[212:215], v156 offset:2048
	ds_read_b128 v[216:219], v156 offset:3072
	ds_read_b128 v[220:223], v156 offset:4096
	ds_read_b128 v[224:227], v156 offset:5120
	ds_read_b128 v[228:231], v156 offset:6144
	ds_read_b128 v[232:235], v156 offset:7168
	global_load_lds_dwordx4 v[136:137], off
	v_lshl_add_u64 v[136:137], s[14:15], 0, v[130:131]
	s_add_i32 m0, s37, 0xe000
	s_nop 0
	global_load_lds_dwordx4 v[136:137], off
	s_waitcnt vmcnt(8)
	s_waitcnt lgkmcnt(0)
	s_barrier
	s_setprio 1
	s_waitcnt lgkmcnt(0)
	v_mfma_f32_16x16x32_bf16 v[112:115], v[158:161], v[204:207], 0
	v_mfma_f32_16x16x32_bf16 v[108:111], v[166:169], v[204:207], 0
	v_mfma_f32_16x16x32_bf16 v[104:107], v[158:161], v[212:215], 0
	v_mfma_f32_16x16x32_bf16 v[100:103], v[166:169], v[212:215], 0
	v_mfma_f32_16x16x32_bf16 v[92:95], v[158:161], v[220:223], 0
	v_mfma_f32_16x16x32_bf16 v[84:87], v[166:169], v[220:223], 0
	v_mfma_f32_16x16x32_bf16 v[76:79], v[158:161], v[228:231], 0
	v_mfma_f32_16x16x32_bf16 v[68:71], v[166:169], v[228:231], 0
	v_mfma_f32_16x16x32_bf16 v[112:115], v[162:165], v[208:211], v[112:115]
	v_mfma_f32_16x16x32_bf16 v[108:111], v[182:185], v[208:211], v[108:111]
	v_mfma_f32_16x16x32_bf16 v[104:107], v[162:165], v[216:219], v[104:107]
	v_mfma_f32_16x16x32_bf16 v[100:103], v[182:185], v[216:219], v[100:103]
	v_mfma_f32_16x16x32_bf16 v[92:95], v[162:165], v[224:227], v[92:95]
	v_mfma_f32_16x16x32_bf16 v[84:87], v[182:185], v[224:227], v[84:87]
	v_mfma_f32_16x16x32_bf16 v[76:79], v[162:165], v[232:235], v[76:79]
	v_mfma_f32_16x16x32_bf16 v[68:71], v[182:185], v[232:235], v[68:71]
	v_mfma_f32_16x16x32_bf16 v[124:127], v[186:189], v[204:207], 0
	v_mfma_f32_16x16x32_bf16 v[120:123], v[196:199], v[204:207], 0
	v_mfma_f32_16x16x32_bf16 v[116:119], v[186:189], v[212:215], 0
	v_mfma_f32_16x16x32_bf16 v[96:99], v[196:199], v[212:215], 0
	v_mfma_f32_16x16x32_bf16 v[88:91], v[186:189], v[220:223], 0
	v_mfma_f32_16x16x32_bf16 v[80:83], v[196:199], v[220:223], 0
	v_mfma_f32_16x16x32_bf16 v[72:75], v[186:189], v[228:231], 0
	v_mfma_f32_16x16x32_bf16 v[64:67], v[196:199], v[228:231], 0
	v_mfma_f32_16x16x32_bf16 v[124:127], v[190:193], v[208:211], v[124:127]
	v_mfma_f32_16x16x32_bf16 v[120:123], v[200:203], v[208:211], v[120:123]
	v_mfma_f32_16x16x32_bf16 v[116:119], v[190:193], v[216:219], v[116:119]
	v_mfma_f32_16x16x32_bf16 v[96:99], v[200:203], v[216:219], v[96:99]
	v_mfma_f32_16x16x32_bf16 v[88:91], v[190:193], v[224:227], v[88:91]
	v_mfma_f32_16x16x32_bf16 v[80:83], v[200:203], v[224:227], v[80:83]
	v_mfma_f32_16x16x32_bf16 v[72:75], v[190:193], v[232:235], v[72:75]
	v_mfma_f32_16x16x32_bf16 v[64:67], v[200:203], v[232:235], v[64:67]
	s_setprio 0
	s_barrier
	s_add_i32 s55, s46, s34
	v_lshl_add_u64 v[136:137], s[2:3], 0, v[142:143]
	s_mov_b32 m0, s55
	ds_read_b128 v[204:207], v156 offset:16384
	ds_read_b128 v[208:211], v156 offset:17408
	ds_read_b128 v[212:215], v156 offset:18432
	ds_read_b128 v[216:219], v156 offset:19456
	ds_read_b128 v[220:223], v156 offset:20480
	ds_read_b128 v[224:227], v156 offset:21504
	ds_read_b128 v[228:231], v156 offset:22528
	ds_read_b128 v[232:235], v156 offset:23552
	global_load_lds_dwordx4 v[136:137], off
	s_add_i32 m0, s55, 0x2000
	s_add_u32 s56, s2, 0x40000
	v_lshl_add_u64 v[236:237], s[2:3], 0, v[146:147]
	s_addc_u32 s57, s3, 0
	s_add_i32 s55, s47, s34
	global_load_lds_dwordx4 v[236:237], off
	v_lshl_add_u64 v[238:239], s[56:57], 0, v[142:143]
	s_mov_b32 m0, s55
	v_lshl_add_u64 v[240:241], s[22:23], 0, v[144:145]
	global_load_lds_dwordx4 v[238:239], off
	v_lshl_add_u64 v[238:239], s[56:57], 0, v[146:147]
	s_add_i32 m0, s55, 0x2000
	s_nop 0
	global_load_lds_dwordx4 v[238:239], off
	v_lshl_add_u64 v[238:239], s[22:23], 0, v[140:141]
	s_mov_b32 m0, s37
	s_nop 0
	global_load_lds_dwordx4 v[238:239], off
	s_mov_b32 m0, s38
	s_nop 0
	global_load_lds_dwordx4 v[240:241], off
	s_waitcnt vmcnt(8)
	s_waitcnt lgkmcnt(0)
	s_barrier
	s_setprio 1
	s_waitcnt lgkmcnt(0)
	v_mfma_f32_16x16x32_bf16 v[60:63], v[158:161], v[204:207], 0
	v_mfma_f32_16x16x32_bf16 v[52:55], v[166:169], v[204:207], 0
	v_mfma_f32_16x16x32_bf16 v[44:47], v[158:161], v[212:215], 0
	v_mfma_f32_16x16x32_bf16 v[36:39], v[166:169], v[212:215], 0
	v_mfma_f32_16x16x32_bf16 v[28:31], v[158:161], v[220:223], 0
	v_mfma_f32_16x16x32_bf16 v[20:23], v[166:169], v[220:223], 0
	v_mfma_f32_16x16x32_bf16 v[12:15], v[158:161], v[228:231], 0
	v_mfma_f32_16x16x32_bf16 v[4:7], v[166:169], v[228:231], 0
	v_mfma_f32_16x16x32_bf16 v[60:63], v[162:165], v[208:211], v[60:63]
	v_mfma_f32_16x16x32_bf16 v[52:55], v[182:185], v[208:211], v[52:55]
	v_mfma_f32_16x16x32_bf16 v[44:47], v[162:165], v[216:219], v[44:47]
	v_mfma_f32_16x16x32_bf16 v[36:39], v[182:185], v[216:219], v[36:39]
	v_mfma_f32_16x16x32_bf16 v[28:31], v[162:165], v[224:227], v[28:31]
	v_mfma_f32_16x16x32_bf16 v[20:23], v[182:185], v[224:227], v[20:23]
	v_mfma_f32_16x16x32_bf16 v[12:15], v[162:165], v[232:235], v[12:15]
	v_mfma_f32_16x16x32_bf16 v[4:7], v[182:185], v[232:235], v[4:7]
	v_mfma_f32_16x16x32_bf16 v[56:59], v[186:189], v[204:207], 0
	v_mfma_f32_16x16x32_bf16 v[48:51], v[196:199], v[204:207], 0
	v_mfma_f32_16x16x32_bf16 v[40:43], v[186:189], v[212:215], 0
	v_mfma_f32_16x16x32_bf16 v[32:35], v[196:199], v[212:215], 0
	v_mfma_f32_16x16x32_bf16 v[24:27], v[186:189], v[220:223], 0
	v_mfma_f32_16x16x32_bf16 v[16:19], v[196:199], v[220:223], 0
	v_mfma_f32_16x16x32_bf16 v[8:11], v[186:189], v[228:231], 0
	v_mfma_f32_16x16x32_bf16 v[0:3], v[196:199], v[228:231], 0
	v_mfma_f32_16x16x32_bf16 v[56:59], v[190:193], v[208:211], v[56:59]
	v_mfma_f32_16x16x32_bf16 v[48:51], v[200:203], v[208:211], v[48:51]
	v_mfma_f32_16x16x32_bf16 v[40:43], v[190:193], v[216:219], v[40:43]
	v_mfma_f32_16x16x32_bf16 v[32:35], v[200:203], v[216:219], v[32:35]
	v_mfma_f32_16x16x32_bf16 v[24:27], v[190:193], v[224:227], v[24:27]
	v_mfma_f32_16x16x32_bf16 v[16:19], v[200:203], v[224:227], v[16:19]
	v_mfma_f32_16x16x32_bf16 v[8:11], v[190:193], v[232:235], v[8:11]
	v_mfma_f32_16x16x32_bf16 v[0:3], v[200:203], v[232:235], v[0:3]
	s_setprio 0
	s_barrier
	s_add_i32 s55, 0, 0x18000
	s_add_i32 s56, 0, 0x1c000
	v_add_u32_e32 v182, s55, v139
	v_add_u32_e32 v200, s56, v139
	ds_read_b128 v[158:161], v182
	ds_read_b128 v[162:165], v182 offset:1024
	ds_read_b128 v[166:169], v182 offset:2048
	ds_read_b128 v[182:185], v182 offset:3072
	ds_read_b128 v[186:189], v200
	ds_read_b128 v[190:193], v200 offset:1024
	ds_read_b128 v[196:199], v200 offset:2048
	ds_read_b128 v[200:203], v200 offset:3072
	s_add_u32 s22, s22, 0x40000
	s_addc_u32 s23, s23, 0
	s_mov_b32 m0, s39
	v_lshl_add_u64 v[242:243], s[22:23], 0, v[140:141]
	ds_read_b128 v[204:207], v156 offset:32768
	ds_read_b128 v[208:211], v156 offset:33792
	ds_read_b128 v[212:215], v156 offset:34816
	ds_read_b128 v[216:219], v156 offset:35840
	ds_read_b128 v[220:223], v156 offset:36864
	ds_read_b128 v[224:227], v156 offset:37888
	ds_read_b128 v[228:231], v156 offset:38912
	ds_read_b128 v[232:235], v156 offset:39936
	global_load_lds_dwordx4 v[242:243], off
	v_lshl_add_u64 v[242:243], s[22:23], 0, v[144:145]
	s_mov_b32 m0, s40
	s_nop 0
	global_load_lds_dwordx4 v[242:243], off
	s_waitcnt vmcnt(8)
	s_waitcnt lgkmcnt(0)
	s_barrier
	s_setprio 1
	s_waitcnt lgkmcnt(0)
	v_mfma_f32_16x16x32_bf16 v[112:115], v[158:161], v[204:207], v[112:115]
	v_mfma_f32_16x16x32_bf16 v[108:111], v[166:169], v[204:207], v[108:111]
	v_mfma_f32_16x16x32_bf16 v[104:107], v[158:161], v[212:215], v[104:107]
	v_mfma_f32_16x16x32_bf16 v[100:103], v[166:169], v[212:215], v[100:103]
	v_mfma_f32_16x16x32_bf16 v[92:95], v[158:161], v[220:223], v[92:95]
	v_mfma_f32_16x16x32_bf16 v[84:87], v[166:169], v[220:223], v[84:87]
	v_mfma_f32_16x16x32_bf16 v[76:79], v[158:161], v[228:231], v[76:79]
	v_mfma_f32_16x16x32_bf16 v[68:71], v[166:169], v[228:231], v[68:71]
	v_mfma_f32_16x16x32_bf16 v[112:115], v[162:165], v[208:211], v[112:115]
	v_mfma_f32_16x16x32_bf16 v[108:111], v[182:185], v[208:211], v[108:111]
	v_mfma_f32_16x16x32_bf16 v[104:107], v[162:165], v[216:219], v[104:107]
	v_mfma_f32_16x16x32_bf16 v[100:103], v[182:185], v[216:219], v[100:103]
	v_mfma_f32_16x16x32_bf16 v[92:95], v[162:165], v[224:227], v[92:95]
	v_mfma_f32_16x16x32_bf16 v[84:87], v[182:185], v[224:227], v[84:87]
	v_mfma_f32_16x16x32_bf16 v[76:79], v[162:165], v[232:235], v[76:79]
	v_mfma_f32_16x16x32_bf16 v[68:71], v[182:185], v[232:235], v[68:71]
	v_mfma_f32_16x16x32_bf16 v[124:127], v[186:189], v[204:207], v[124:127]
	v_mfma_f32_16x16x32_bf16 v[120:123], v[196:199], v[204:207], v[120:123]
	v_mfma_f32_16x16x32_bf16 v[116:119], v[186:189], v[212:215], v[116:119]
	v_mfma_f32_16x16x32_bf16 v[96:99], v[196:199], v[212:215], v[96:99]
	v_mfma_f32_16x16x32_bf16 v[88:91], v[186:189], v[220:223], v[88:91]
	v_mfma_f32_16x16x32_bf16 v[80:83], v[196:199], v[220:223], v[80:83]
	v_mfma_f32_16x16x32_bf16 v[72:75], v[186:189], v[228:231], v[72:75]
	v_mfma_f32_16x16x32_bf16 v[64:67], v[196:199], v[228:231], v[64:67]
	v_mfma_f32_16x16x32_bf16 v[124:127], v[190:193], v[208:211], v[124:127]
	v_mfma_f32_16x16x32_bf16 v[120:123], v[200:203], v[208:211], v[120:123]
	v_mfma_f32_16x16x32_bf16 v[116:119], v[190:193], v[216:219], v[116:119]
	v_mfma_f32_16x16x32_bf16 v[96:99], v[200:203], v[216:219], v[96:99]
	v_mfma_f32_16x16x32_bf16 v[88:91], v[190:193], v[224:227], v[88:91]
	v_mfma_f32_16x16x32_bf16 v[80:83], v[200:203], v[224:227], v[80:83]
	v_mfma_f32_16x16x32_bf16 v[72:75], v[190:193], v[232:235], v[72:75]
	v_mfma_f32_16x16x32_bf16 v[64:67], v[200:203], v[232:235], v[64:67]
	s_setprio 0
	s_barrier
	s_add_i32 s22, s55, s34
	v_lshl_add_u64 v[136:137], v[136:137], 0, s[8:9]
	s_mov_b32 m0, s22
	ds_read_b128 v[204:207], v156 offset:49152
	ds_read_b128 v[208:211], v156 offset:50176
	ds_read_b128 v[212:215], v156 offset:51200
	ds_read_b128 v[216:219], v156 offset:52224
	ds_read_b128 v[220:223], v156 offset:53248
	ds_read_b128 v[224:227], v156 offset:54272
	ds_read_b128 v[228:231], v156 offset:55296
	ds_read_b128 v[232:235], v156 offset:56320
	global_load_lds_dwordx4 v[136:137], off
	s_add_i32 m0, s22, 0x2000
	s_add_u32 s2, s2, 0x40080
	v_lshl_add_u64 v[136:137], v[236:237], 0, s[8:9]
	s_addc_u32 s3, s3, 0
	s_add_i32 s22, s56, s34
	global_load_lds_dwordx4 v[136:137], off
	v_lshl_add_u64 v[136:137], s[2:3], 0, v[142:143]
	s_mov_b32 m0, s22
	s_nop 0
	global_load_lds_dwordx4 v[136:137], off
	v_lshl_add_u64 v[136:137], s[2:3], 0, v[146:147]
	s_add_i32 m0, s22, 0x2000
	s_nop 0
	global_load_lds_dwordx4 v[136:137], off
	v_lshl_add_u64 v[136:137], v[238:239], 0, s[8:9]
	s_mov_b32 m0, s42
	s_nop 0
	global_load_lds_dwordx4 v[136:137], off
	v_lshl_add_u64 v[136:137], v[240:241], 0, s[8:9]
	s_mov_b32 m0, s43
	s_nop 0
	global_load_lds_dwordx4 v[136:137], off
	s_waitcnt vmcnt(8)
	s_waitcnt lgkmcnt(0)
	s_barrier
	s_setprio 1
	s_waitcnt lgkmcnt(0)
	v_mfma_f32_16x16x32_bf16 v[60:63], v[158:161], v[204:207], v[60:63]
	v_mfma_f32_16x16x32_bf16 v[52:55], v[166:169], v[204:207], v[52:55]
	v_mfma_f32_16x16x32_bf16 v[44:47], v[158:161], v[212:215], v[44:47]
	v_mfma_f32_16x16x32_bf16 v[36:39], v[166:169], v[212:215], v[36:39]
	v_mfma_f32_16x16x32_bf16 v[28:31], v[158:161], v[220:223], v[28:31]
	v_mfma_f32_16x16x32_bf16 v[20:23], v[166:169], v[220:223], v[20:23]
	v_mfma_f32_16x16x32_bf16 v[12:15], v[158:161], v[228:231], v[12:15]
	v_mfma_f32_16x16x32_bf16 v[4:7], v[166:169], v[228:231], v[4:7]
	v_mfma_f32_16x16x32_bf16 v[60:63], v[162:165], v[208:211], v[60:63]
	v_mfma_f32_16x16x32_bf16 v[52:55], v[182:185], v[208:211], v[52:55]
	v_mfma_f32_16x16x32_bf16 v[44:47], v[162:165], v[216:219], v[44:47]
	v_mfma_f32_16x16x32_bf16 v[36:39], v[182:185], v[216:219], v[36:39]
	v_mfma_f32_16x16x32_bf16 v[28:31], v[162:165], v[224:227], v[28:31]
	v_mfma_f32_16x16x32_bf16 v[20:23], v[182:185], v[224:227], v[20:23]
	v_mfma_f32_16x16x32_bf16 v[12:15], v[162:165], v[232:235], v[12:15]
	v_mfma_f32_16x16x32_bf16 v[4:7], v[182:185], v[232:235], v[4:7]
	v_mfma_f32_16x16x32_bf16 v[56:59], v[186:189], v[204:207], v[56:59]
	v_mfma_f32_16x16x32_bf16 v[48:51], v[196:199], v[204:207], v[48:51]
	v_mfma_f32_16x16x32_bf16 v[40:43], v[186:189], v[212:215], v[40:43]
	v_mfma_f32_16x16x32_bf16 v[32:35], v[196:199], v[212:215], v[32:35]
	v_mfma_f32_16x16x32_bf16 v[24:27], v[186:189], v[220:223], v[24:27]
	v_mfma_f32_16x16x32_bf16 v[16:19], v[196:199], v[220:223], v[16:19]
	v_mfma_f32_16x16x32_bf16 v[8:11], v[186:189], v[228:231], v[8:11]
	v_mfma_f32_16x16x32_bf16 v[0:3], v[196:199], v[228:231], v[0:3]
	v_mfma_f32_16x16x32_bf16 v[56:59], v[190:193], v[208:211], v[56:59]
	v_mfma_f32_16x16x32_bf16 v[48:51], v[200:203], v[208:211], v[48:51]
	v_mfma_f32_16x16x32_bf16 v[40:43], v[190:193], v[216:219], v[40:43]
	v_mfma_f32_16x16x32_bf16 v[32:35], v[200:203], v[216:219], v[32:35]
	v_mfma_f32_16x16x32_bf16 v[24:27], v[190:193], v[224:227], v[24:27]
	v_mfma_f32_16x16x32_bf16 v[16:19], v[200:203], v[224:227], v[16:19]
	v_mfma_f32_16x16x32_bf16 v[8:11], v[190:193], v[232:235], v[8:11]
	v_mfma_f32_16x16x32_bf16 v[0:3], v[200:203], v[232:235], v[0:3]
	s_setprio 0
	s_barrier
	s_add_i32 s54, s54, 2
	s_add_u32 s14, s14, 0x100
	s_addc_u32 s15, s15, 0
	s_add_u32 s52, s52, 0x100
	s_addc_u32 s53, s53, 0
	s_cmp_gt_u32 s54, 13
	s_cbranch_scc1 .Lgemm_kdone_1
.LBB0_368:
	ds_read_b128 v[158:161], v154
	ds_read_b128 v[162:165], v154 offset:1024
	ds_read_b128 v[166:169], v154 offset:2048
	ds_read_b128 v[182:185], v154 offset:3072
	ds_read_b128 v[186:189], v155
	ds_read_b128 v[190:193], v155 offset:1024
	ds_read_b128 v[196:199], v155 offset:2048
	ds_read_b128 v[200:203], v155 offset:3072
	s_add_u32 s2, s14, 0xfffc0080
	s_addc_u32 s3, s15, -1
	s_cmp_eq_u32 s54, 12
	s_cselect_b32 s23, s25, s3
	s_cselect_b32 s22, s50, s2
	s_cselect_b32 s3, s21, s53
	s_cselect_b32 s2, s51, s52
	v_lshl_add_u64 v[136:137], s[14:15], 0, v[128:129]
	s_add_i32 m0, s37, 0xc000
	ds_read_b128 v[204:207], v156
	ds_read_b128 v[208:211], v156 offset:1024
	ds_read_b128 v[212:215], v156 offset:2048
	ds_read_b128 v[216:219], v156 offset:3072
	ds_read_b128 v[220:223], v156 offset:4096
	ds_read_b128 v[224:227], v156 offset:5120
	ds_read_b128 v[228:231], v156 offset:6144
	ds_read_b128 v[232:235], v156 offset:7168
	global_load_lds_dwordx4 v[136:137], off
	v_lshl_add_u64 v[136:137], s[14:15], 0, v[130:131]
	s_add_i32 m0, s37, 0xe000
	s_nop 0
	global_load_lds_dwordx4 v[136:137], off
	s_waitcnt vmcnt(8)
	s_waitcnt lgkmcnt(0)
	s_barrier
	s_setprio 1
	s_waitcnt lgkmcnt(0)
	v_mfma_f32_16x16x32_bf16 v[112:115], v[158:161], v[204:207], v[112:115]
	v_mfma_f32_16x16x32_bf16 v[108:111], v[166:169], v[204:207], v[108:111]
	v_mfma_f32_16x16x32_bf16 v[104:107], v[158:161], v[212:215], v[104:107]
	v_mfma_f32_16x16x32_bf16 v[100:103], v[166:169], v[212:215], v[100:103]
	v_mfma_f32_16x16x32_bf16 v[92:95], v[158:161], v[220:223], v[92:95]
	v_mfma_f32_16x16x32_bf16 v[84:87], v[166:169], v[220:223], v[84:87]
	v_mfma_f32_16x16x32_bf16 v[76:79], v[158:161], v[228:231], v[76:79]
	v_mfma_f32_16x16x32_bf16 v[68:71], v[166:169], v[228:231], v[68:71]
	v_mfma_f32_16x16x32_bf16 v[112:115], v[162:165], v[208:211], v[112:115]
	v_mfma_f32_16x16x32_bf16 v[108:111], v[182:185], v[208:211], v[108:111]
	v_mfma_f32_16x16x32_bf16 v[104:107], v[162:165], v[216:219], v[104:107]
	v_mfma_f32_16x16x32_bf16 v[100:103], v[182:185], v[216:219], v[100:103]
	v_mfma_f32_16x16x32_bf16 v[92:95], v[162:165], v[224:227], v[92:95]
	v_mfma_f32_16x16x32_bf16 v[84:87], v[182:185], v[224:227], v[84:87]
	v_mfma_f32_16x16x32_bf16 v[76:79], v[162:165], v[232:235], v[76:79]
	v_mfma_f32_16x16x32_bf16 v[68:71], v[182:185], v[232:235], v[68:71]
	v_mfma_f32_16x16x32_bf16 v[124:127], v[186:189], v[204:207], v[124:127]
	v_mfma_f32_16x16x32_bf16 v[120:123], v[196:199], v[204:207], v[120:123]
	v_mfma_f32_16x16x32_bf16 v[116:119], v[186:189], v[212:215], v[116:119]
	v_mfma_f32_16x16x32_bf16 v[96:99], v[196:199], v[212:215], v[96:99]
	v_mfma_f32_16x16x32_bf16 v[88:91], v[186:189], v[220:223], v[88:91]
	v_mfma_f32_16x16x32_bf16 v[80:83], v[196:199], v[220:223], v[80:83]
	v_mfma_f32_16x16x32_bf16 v[72:75], v[186:189], v[228:231], v[72:75]
	v_mfma_f32_16x16x32_bf16 v[64:67], v[196:199], v[228:231], v[64:67]
	v_mfma_f32_16x16x32_bf16 v[124:127], v[190:193], v[208:211], v[124:127]
	v_mfma_f32_16x16x32_bf16 v[120:123], v[200:203], v[208:211], v[120:123]
	v_mfma_f32_16x16x32_bf16 v[116:119], v[190:193], v[216:219], v[116:119]
	v_mfma_f32_16x16x32_bf16 v[96:99], v[200:203], v[216:219], v[96:99]
	v_mfma_f32_16x16x32_bf16 v[88:91], v[190:193], v[224:227], v[88:91]
	v_mfma_f32_16x16x32_bf16 v[80:83], v[200:203], v[224:227], v[80:83]
	v_mfma_f32_16x16x32_bf16 v[72:75], v[190:193], v[232:235], v[72:75]
	v_mfma_f32_16x16x32_bf16 v[64:67], v[200:203], v[232:235], v[64:67]
	s_setprio 0
	s_barrier
	s_add_i32 s55, s46, s34
	v_lshl_add_u64 v[136:137], s[2:3], 0, v[142:143]
	s_mov_b32 m0, s55
	ds_read_b128 v[204:207], v156 offset:16384
	ds_read_b128 v[208:211], v156 offset:17408
	ds_read_b128 v[212:215], v156 offset:18432
	ds_read_b128 v[216:219], v156 offset:19456
	ds_read_b128 v[220:223], v156 offset:20480
	ds_read_b128 v[224:227], v156 offset:21504
	ds_read_b128 v[228:231], v156 offset:22528
	ds_read_b128 v[232:235], v156 offset:23552
	global_load_lds_dwordx4 v[136:137], off
	s_add_i32 m0, s55, 0x2000
	s_add_u32 s56, s2, 0x40000
	v_lshl_add_u64 v[236:237], s[2:3], 0, v[146:147]
	s_addc_u32 s57, s3, 0
	s_add_i32 s55, s47, s34
	global_load_lds_dwordx4 v[236:237], off
	v_lshl_add_u64 v[238:239], s[56:57], 0, v[142:143]
	s_mov_b32 m0, s55
	v_lshl_add_u64 v[240:241], s[22:23], 0, v[144:145]
	global_load_lds_dwordx4 v[238:239], off
	v_lshl_add_u64 v[238:239], s[56:57], 0, v[146:147]
	s_add_i32 m0, s55, 0x2000
	s_nop 0
	global_load_lds_dwordx4 v[238:239], off
	v_lshl_add_u64 v[238:239], s[22:23], 0, v[140:141]
	s_mov_b32 m0, s37
	s_nop 0
	global_load_lds_dwordx4 v[238:239], off
	s_mov_b32 m0, s38
	s_nop 0
	global_load_lds_dwordx4 v[240:241], off
	s_waitcnt vmcnt(8)
	s_waitcnt lgkmcnt(0)
	s_barrier
	s_setprio 1
	s_waitcnt lgkmcnt(0)
	v_mfma_f32_16x16x32_bf16 v[60:63], v[158:161], v[204:207], v[60:63]
	v_mfma_f32_16x16x32_bf16 v[52:55], v[166:169], v[204:207], v[52:55]
	v_mfma_f32_16x16x32_bf16 v[44:47], v[158:161], v[212:215], v[44:47]
	v_mfma_f32_16x16x32_bf16 v[36:39], v[166:169], v[212:215], v[36:39]
	v_mfma_f32_16x16x32_bf16 v[28:31], v[158:161], v[220:223], v[28:31]
	v_mfma_f32_16x16x32_bf16 v[20:23], v[166:169], v[220:223], v[20:23]
	v_mfma_f32_16x16x32_bf16 v[12:15], v[158:161], v[228:231], v[12:15]
	v_mfma_f32_16x16x32_bf16 v[4:7], v[166:169], v[228:231], v[4:7]
	v_mfma_f32_16x16x32_bf16 v[60:63], v[162:165], v[208:211], v[60:63]
	v_mfma_f32_16x16x32_bf16 v[52:55], v[182:185], v[208:211], v[52:55]
	v_mfma_f32_16x16x32_bf16 v[44:47], v[162:165], v[216:219], v[44:47]
	v_mfma_f32_16x16x32_bf16 v[36:39], v[182:185], v[216:219], v[36:39]
	v_mfma_f32_16x16x32_bf16 v[28:31], v[162:165], v[224:227], v[28:31]
	v_mfma_f32_16x16x32_bf16 v[20:23], v[182:185], v[224:227], v[20:23]
	v_mfma_f32_16x16x32_bf16 v[12:15], v[162:165], v[232:235], v[12:15]
	v_mfma_f32_16x16x32_bf16 v[4:7], v[182:185], v[232:235], v[4:7]
	v_mfma_f32_16x16x32_bf16 v[56:59], v[186:189], v[204:207], v[56:59]
	v_mfma_f32_16x16x32_bf16 v[48:51], v[196:199], v[204:207], v[48:51]
	v_mfma_f32_16x16x32_bf16 v[40:43], v[186:189], v[212:215], v[40:43]
	v_mfma_f32_16x16x32_bf16 v[32:35], v[196:199], v[212:215], v[32:35]
	v_mfma_f32_16x16x32_bf16 v[24:27], v[186:189], v[220:223], v[24:27]
	v_mfma_f32_16x16x32_bf16 v[16:19], v[196:199], v[220:223], v[16:19]
	v_mfma_f32_16x16x32_bf16 v[8:11], v[186:189], v[228:231], v[8:11]
	v_mfma_f32_16x16x32_bf16 v[0:3], v[196:199], v[228:231], v[0:3]
	v_mfma_f32_16x16x32_bf16 v[56:59], v[190:193], v[208:211], v[56:59]
	v_mfma_f32_16x16x32_bf16 v[48:51], v[200:203], v[208:211], v[48:51]
	v_mfma_f32_16x16x32_bf16 v[40:43], v[190:193], v[216:219], v[40:43]
	v_mfma_f32_16x16x32_bf16 v[32:35], v[200:203], v[216:219], v[32:35]
	v_mfma_f32_16x16x32_bf16 v[24:27], v[190:193], v[224:227], v[24:27]
	v_mfma_f32_16x16x32_bf16 v[16:19], v[200:203], v[224:227], v[16:19]
	v_mfma_f32_16x16x32_bf16 v[8:11], v[190:193], v[232:235], v[8:11]
	v_mfma_f32_16x16x32_bf16 v[0:3], v[200:203], v[232:235], v[0:3]
	s_setprio 0
	s_barrier
	s_add_i32 s55, 0, 0x18000
	s_add_i32 s56, 0, 0x1c000
	v_add_u32_e32 v182, s55, v139
	v_add_u32_e32 v200, s56, v139
	ds_read_b128 v[158:161], v182
	ds_read_b128 v[162:165], v182 offset:1024
	ds_read_b128 v[166:169], v182 offset:2048
	ds_read_b128 v[182:185], v182 offset:3072
	ds_read_b128 v[186:189], v200
	ds_read_b128 v[190:193], v200 offset:1024
	ds_read_b128 v[196:199], v200 offset:2048
	ds_read_b128 v[200:203], v200 offset:3072
	s_add_u32 s22, s22, 0x40000
	s_addc_u32 s23, s23, 0
	s_mov_b32 m0, s39
	v_lshl_add_u64 v[242:243], s[22:23], 0, v[140:141]
	ds_read_b128 v[204:207], v156 offset:32768
	ds_read_b128 v[208:211], v156 offset:33792
	ds_read_b128 v[212:215], v156 offset:34816
	ds_read_b128 v[216:219], v156 offset:35840
	ds_read_b128 v[220:223], v156 offset:36864
	ds_read_b128 v[224:227], v156 offset:37888
	ds_read_b128 v[228:231], v156 offset:38912
	ds_read_b128 v[232:235], v156 offset:39936
	global_load_lds_dwordx4 v[242:243], off
	v_lshl_add_u64 v[242:243], s[22:23], 0, v[144:145]
	s_mov_b32 m0, s40
	s_nop 0
	global_load_lds_dwordx4 v[242:243], off
	s_waitcnt vmcnt(8)
	s_waitcnt lgkmcnt(0)
	s_barrier
	s_setprio 1
	s_waitcnt lgkmcnt(0)
	v_mfma_f32_16x16x32_bf16 v[112:115], v[158:161], v[204:207], v[112:115]
	v_mfma_f32_16x16x32_bf16 v[108:111], v[166:169], v[204:207], v[108:111]
	v_mfma_f32_16x16x32_bf16 v[104:107], v[158:161], v[212:215], v[104:107]
	v_mfma_f32_16x16x32_bf16 v[100:103], v[166:169], v[212:215], v[100:103]
	v_mfma_f32_16x16x32_bf16 v[92:95], v[158:161], v[220:223], v[92:95]
	v_mfma_f32_16x16x32_bf16 v[84:87], v[166:169], v[220:223], v[84:87]
	v_mfma_f32_16x16x32_bf16 v[76:79], v[158:161], v[228:231], v[76:79]
	v_mfma_f32_16x16x32_bf16 v[68:71], v[166:169], v[228:231], v[68:71]
	v_mfma_f32_16x16x32_bf16 v[112:115], v[162:165], v[208:211], v[112:115]
	v_mfma_f32_16x16x32_bf16 v[108:111], v[182:185], v[208:211], v[108:111]
	v_mfma_f32_16x16x32_bf16 v[104:107], v[162:165], v[216:219], v[104:107]
	v_mfma_f32_16x16x32_bf16 v[100:103], v[182:185], v[216:219], v[100:103]
	v_mfma_f32_16x16x32_bf16 v[92:95], v[162:165], v[224:227], v[92:95]
	v_mfma_f32_16x16x32_bf16 v[84:87], v[182:185], v[224:227], v[84:87]
	v_mfma_f32_16x16x32_bf16 v[76:79], v[162:165], v[232:235], v[76:79]
	v_mfma_f32_16x16x32_bf16 v[68:71], v[182:185], v[232:235], v[68:71]
	v_mfma_f32_16x16x32_bf16 v[124:127], v[186:189], v[204:207], v[124:127]
	v_mfma_f32_16x16x32_bf16 v[120:123], v[196:199], v[204:207], v[120:123]
	v_mfma_f32_16x16x32_bf16 v[116:119], v[186:189], v[212:215], v[116:119]
	v_mfma_f32_16x16x32_bf16 v[96:99], v[196:199], v[212:215], v[96:99]
	v_mfma_f32_16x16x32_bf16 v[88:91], v[186:189], v[220:223], v[88:91]
	v_mfma_f32_16x16x32_bf16 v[80:83], v[196:199], v[220:223], v[80:83]
	v_mfma_f32_16x16x32_bf16 v[72:75], v[186:189], v[228:231], v[72:75]
	v_mfma_f32_16x16x32_bf16 v[64:67], v[196:199], v[228:231], v[64:67]
	v_mfma_f32_16x16x32_bf16 v[124:127], v[190:193], v[208:211], v[124:127]
	v_mfma_f32_16x16x32_bf16 v[120:123], v[200:203], v[208:211], v[120:123]
	v_mfma_f32_16x16x32_bf16 v[116:119], v[190:193], v[216:219], v[116:119]
	v_mfma_f32_16x16x32_bf16 v[96:99], v[200:203], v[216:219], v[96:99]
	v_mfma_f32_16x16x32_bf16 v[88:91], v[190:193], v[224:227], v[88:91]
	v_mfma_f32_16x16x32_bf16 v[80:83], v[200:203], v[224:227], v[80:83]
	v_mfma_f32_16x16x32_bf16 v[72:75], v[190:193], v[232:235], v[72:75]
	v_mfma_f32_16x16x32_bf16 v[64:67], v[200:203], v[232:235], v[64:67]
	s_setprio 0
	s_barrier
	s_add_i32 s22, s55, s34
	v_lshl_add_u64 v[136:137], v[136:137], 0, s[8:9]
	s_mov_b32 m0, s22
	ds_read_b128 v[204:207], v156 offset:49152
	ds_read_b128 v[208:211], v156 offset:50176
	ds_read_b128 v[212:215], v156 offset:51200
	ds_read_b128 v[216:219], v156 offset:52224
	ds_read_b128 v[220:223], v156 offset:53248
	ds_read_b128 v[224:227], v156 offset:54272
	ds_read_b128 v[228:231], v156 offset:55296
	ds_read_b128 v[232:235], v156 offset:56320
	global_load_lds_dwordx4 v[136:137], off
	s_add_i32 m0, s22, 0x2000
	s_add_u32 s2, s2, 0x40080
	v_lshl_add_u64 v[136:137], v[236:237], 0, s[8:9]
	s_addc_u32 s3, s3, 0
	s_add_i32 s22, s56, s34
	global_load_lds_dwordx4 v[136:137], off
	v_lshl_add_u64 v[136:137], s[2:3], 0, v[142:143]
	s_mov_b32 m0, s22
	s_nop 0
	global_load_lds_dwordx4 v[136:137], off
	v_lshl_add_u64 v[136:137], s[2:3], 0, v[146:147]
	s_add_i32 m0, s22, 0x2000
	s_nop 0
	global_load_lds_dwordx4 v[136:137], off
	v_lshl_add_u64 v[136:137], v[238:239], 0, s[8:9]
	s_mov_b32 m0, s42
	s_nop 0
	global_load_lds_dwordx4 v[136:137], off
	v_lshl_add_u64 v[136:137], v[240:241], 0, s[8:9]
	s_mov_b32 m0, s43
	s_nop 0
	global_load_lds_dwordx4 v[136:137], off
	s_waitcnt vmcnt(8)
	s_waitcnt lgkmcnt(0)
	s_barrier
	s_setprio 1
	s_waitcnt lgkmcnt(0)
	v_mfma_f32_16x16x32_bf16 v[60:63], v[158:161], v[204:207], v[60:63]
	v_mfma_f32_16x16x32_bf16 v[52:55], v[166:169], v[204:207], v[52:55]
	v_mfma_f32_16x16x32_bf16 v[44:47], v[158:161], v[212:215], v[44:47]
	v_mfma_f32_16x16x32_bf16 v[36:39], v[166:169], v[212:215], v[36:39]
	v_mfma_f32_16x16x32_bf16 v[28:31], v[158:161], v[220:223], v[28:31]
	v_mfma_f32_16x16x32_bf16 v[20:23], v[166:169], v[220:223], v[20:23]
	v_mfma_f32_16x16x32_bf16 v[12:15], v[158:161], v[228:231], v[12:15]
	v_mfma_f32_16x16x32_bf16 v[4:7], v[166:169], v[228:231], v[4:7]
	v_mfma_f32_16x16x32_bf16 v[60:63], v[162:165], v[208:211], v[60:63]
	v_mfma_f32_16x16x32_bf16 v[52:55], v[182:185], v[208:211], v[52:55]
	v_mfma_f32_16x16x32_bf16 v[44:47], v[162:165], v[216:219], v[44:47]
	v_mfma_f32_16x16x32_bf16 v[36:39], v[182:185], v[216:219], v[36:39]
	v_mfma_f32_16x16x32_bf16 v[28:31], v[162:165], v[224:227], v[28:31]
	v_mfma_f32_16x16x32_bf16 v[20:23], v[182:185], v[224:227], v[20:23]
	v_mfma_f32_16x16x32_bf16 v[12:15], v[162:165], v[232:235], v[12:15]
	v_mfma_f32_16x16x32_bf16 v[4:7], v[182:185], v[232:235], v[4:7]
	v_mfma_f32_16x16x32_bf16 v[56:59], v[186:189], v[204:207], v[56:59]
	v_mfma_f32_16x16x32_bf16 v[48:51], v[196:199], v[204:207], v[48:51]
	v_mfma_f32_16x16x32_bf16 v[40:43], v[186:189], v[212:215], v[40:43]
	v_mfma_f32_16x16x32_bf16 v[32:35], v[196:199], v[212:215], v[32:35]
	v_mfma_f32_16x16x32_bf16 v[24:27], v[186:189], v[220:223], v[24:27]
	v_mfma_f32_16x16x32_bf16 v[16:19], v[196:199], v[220:223], v[16:19]
	v_mfma_f32_16x16x32_bf16 v[8:11], v[186:189], v[228:231], v[8:11]
	v_mfma_f32_16x16x32_bf16 v[0:3], v[196:199], v[228:231], v[0:3]
	v_mfma_f32_16x16x32_bf16 v[56:59], v[190:193], v[208:211], v[56:59]
	v_mfma_f32_16x16x32_bf16 v[48:51], v[200:203], v[208:211], v[48:51]
	v_mfma_f32_16x16x32_bf16 v[40:43], v[190:193], v[216:219], v[40:43]
	v_mfma_f32_16x16x32_bf16 v[32:35], v[200:203], v[216:219], v[32:35]
	v_mfma_f32_16x16x32_bf16 v[24:27], v[190:193], v[224:227], v[24:27]
	v_mfma_f32_16x16x32_bf16 v[16:19], v[200:203], v[224:227], v[16:19]
	v_mfma_f32_16x16x32_bf16 v[8:11], v[190:193], v[232:235], v[8:11]
	v_mfma_f32_16x16x32_bf16 v[0:3], v[200:203], v[232:235], v[0:3]
	s_setprio 0
	s_barrier
	s_add_i32 s54, s54, 2
	s_add_u32 s14, s14, 0x100
	s_addc_u32 s15, s15, 0
	s_add_u32 s52, s52, 0x100
	s_addc_u32 s53, s53, 0
	s_cmp_gt_u32 s54, 13
	s_cbranch_scc0 .LBB0_368

.LBB0_454:
	s_add_u32 s14, s14, 0xb0080
	s_addc_u32 s15, s15, 0
	s_add_u32 s65, s2, 0x100
	s_addc_u32 s66, s3, 0
	s_mov_b32 s67, -2
	s_waitcnt lgkmcnt(0)
	s_waitcnt vmcnt(0)
	ds_read_b128 v[128:131], v147
	ds_read_b128 v[132:135], v147 offset:1024
	ds_read_b128 v[136:139], v147 offset:2048
	ds_read_b128 v[164:167], v147 offset:3072
	ds_read_b128 v[188:191], v184
	ds_read_b128 v[196:199], v184 offset:1024
	ds_read_b128 v[200:203], v184 offset:2048
	ds_read_b128 v[204:207], v184 offset:3072
	s_add_u32 s2, s14, 0xfff50080
	s_addc_u32 s3, s15, -1
	s_cmp_eq_u32 s67, 40
	s_cselect_b32 s23, s1, s3
	s_cselect_b32 s22, s0, s2
	s_cselect_b32 s3, s31, s66
	s_cselect_b32 s2, s30, s65
	v_lshl_add_u64 v[168:169], s[14:15], 0, v[156:157]
	s_add_i32 m0, s37, 0xc000
	ds_read_b128 v[208:211], v185
	ds_read_b128 v[212:215], v185 offset:1024
	ds_read_b128 v[216:219], v185 offset:2048
	ds_read_b128 v[220:223], v185 offset:3072
	ds_read_b128 v[224:227], v185 offset:4096
	ds_read_b128 v[228:231], v185 offset:5120
	ds_read_b128 v[232:235], v185 offset:6144
	ds_read_b128 v[236:239], v185 offset:7168
	global_load_lds_dwordx4 v[168:169], off
	v_lshl_add_u64 v[168:169], s[14:15], 0, v[158:159]
	s_add_i32 m0, s37, 0xe000
	s_nop 0
	global_load_lds_dwordx4 v[168:169], off
	s_waitcnt vmcnt(8)
	s_waitcnt lgkmcnt(0)
	s_barrier
	s_setprio 1
	s_waitcnt lgkmcnt(0)
	v_mfma_f32_16x16x32_bf16 v[124:127], v[128:131], v[208:211], 0
	v_mfma_f32_16x16x32_bf16 v[120:123], v[136:139], v[208:211], 0
	v_mfma_f32_16x16x32_bf16 v[108:111], v[128:131], v[216:219], 0
	v_mfma_f32_16x16x32_bf16 v[104:107], v[136:139], v[216:219], 0
	v_mfma_f32_16x16x32_bf16 v[92:95], v[128:131], v[224:227], 0
	v_mfma_f32_16x16x32_bf16 v[88:91], v[136:139], v[224:227], 0
	v_mfma_f32_16x16x32_bf16 v[76:79], v[128:131], v[232:235], 0
	v_mfma_f32_16x16x32_bf16 v[72:75], v[136:139], v[232:235], 0
	v_mfma_f32_16x16x32_bf16 v[124:127], v[132:135], v[212:215], v[124:127]
	v_mfma_f32_16x16x32_bf16 v[120:123], v[164:167], v[212:215], v[120:123]
	v_mfma_f32_16x16x32_bf16 v[108:111], v[132:135], v[220:223], v[108:111]
	v_mfma_f32_16x16x32_bf16 v[104:107], v[164:167], v[220:223], v[104:107]
	v_mfma_f32_16x16x32_bf16 v[92:95], v[132:135], v[228:231], v[92:95]
	v_mfma_f32_16x16x32_bf16 v[88:91], v[164:167], v[228:231], v[88:91]
	v_mfma_f32_16x16x32_bf16 v[76:79], v[132:135], v[236:239], v[76:79]
	v_mfma_f32_16x16x32_bf16 v[72:75], v[164:167], v[236:239], v[72:75]
	v_mfma_f32_16x16x32_bf16 v[116:119], v[188:191], v[208:211], 0
	v_mfma_f32_16x16x32_bf16 v[112:115], v[200:203], v[208:211], 0
	v_mfma_f32_16x16x32_bf16 v[100:103], v[188:191], v[216:219], 0
	v_mfma_f32_16x16x32_bf16 v[96:99], v[200:203], v[216:219], 0
	v_mfma_f32_16x16x32_bf16 v[84:87], v[188:191], v[224:227], 0
	v_mfma_f32_16x16x32_bf16 v[80:83], v[200:203], v[224:227], 0
	v_mfma_f32_16x16x32_bf16 v[68:71], v[188:191], v[232:235], 0
	v_mfma_f32_16x16x32_bf16 v[64:67], v[200:203], v[232:235], 0
	v_mfma_f32_16x16x32_bf16 v[116:119], v[196:199], v[212:215], v[116:119]
	v_mfma_f32_16x16x32_bf16 v[112:115], v[204:207], v[212:215], v[112:115]
	v_mfma_f32_16x16x32_bf16 v[100:103], v[196:199], v[220:223], v[100:103]
	v_mfma_f32_16x16x32_bf16 v[96:99], v[204:207], v[220:223], v[96:99]
	v_mfma_f32_16x16x32_bf16 v[84:87], v[196:199], v[228:231], v[84:87]
	v_mfma_f32_16x16x32_bf16 v[80:83], v[204:207], v[228:231], v[80:83]
	v_mfma_f32_16x16x32_bf16 v[68:71], v[196:199], v[236:239], v[68:71]
	v_mfma_f32_16x16x32_bf16 v[64:67], v[204:207], v[236:239], v[64:67]
	s_setprio 0
	s_barrier
	s_add_i32 s68, s51, s36
	v_lshl_add_u64 v[168:169], s[2:3], 0, v[150:151]
	s_mov_b32 m0, s68
	ds_read_b128 v[208:211], v185 offset:16384
	ds_read_b128 v[212:215], v185 offset:17408
	ds_read_b128 v[216:219], v185 offset:18432
	ds_read_b128 v[220:223], v185 offset:19456
	ds_read_b128 v[224:227], v185 offset:20480
	ds_read_b128 v[228:231], v185 offset:21504
	ds_read_b128 v[232:235], v185 offset:22528
	ds_read_b128 v[236:239], v185 offset:23552
	global_load_lds_dwordx4 v[168:169], off
	s_add_i32 m0, s68, 0x2000
	s_add_u32 s68, s2, 0xb0000
	v_lshl_add_u64 v[192:193], s[2:3], 0, v[154:155]
	s_addc_u32 s69, s3, 0
	s_add_i32 s70, s52, s36
	global_load_lds_dwordx4 v[192:193], off
	v_lshl_add_u64 v[240:241], s[68:69], 0, v[150:151]
	s_mov_b32 m0, s70
	v_lshl_add_u64 v[242:243], s[22:23], 0, v[152:153]
	global_load_lds_dwordx4 v[240:241], off
	v_lshl_add_u64 v[240:241], s[68:69], 0, v[154:155]
	s_add_i32 m0, s70, 0x2000
	s_nop 0
	global_load_lds_dwordx4 v[240:241], off
	v_lshl_add_u64 v[240:241], s[22:23], 0, v[148:149]
	s_mov_b32 m0, s37
	s_nop 0
	global_load_lds_dwordx4 v[240:241], off
	s_mov_b32 m0, s38
	s_nop 0
	global_load_lds_dwordx4 v[242:243], off
	s_waitcnt vmcnt(8)
	s_waitcnt lgkmcnt(0)
	s_barrier
	s_setprio 1
	s_waitcnt lgkmcnt(0)
	v_mfma_f32_16x16x32_bf16 v[60:63], v[128:131], v[208:211], 0
	v_mfma_f32_16x16x32_bf16 v[56:59], v[136:139], v[208:211], 0
	v_mfma_f32_16x16x32_bf16 v[44:47], v[128:131], v[216:219], 0
	v_mfma_f32_16x16x32_bf16 v[40:43], v[136:139], v[216:219], 0
	v_mfma_f32_16x16x32_bf16 v[28:31], v[128:131], v[224:227], 0
	v_mfma_f32_16x16x32_bf16 v[24:27], v[136:139], v[224:227], 0
	v_mfma_f32_16x16x32_bf16 v[12:15], v[128:131], v[232:235], 0
	v_mfma_f32_16x16x32_bf16 v[8:11], v[136:139], v[232:235], 0
	v_mfma_f32_16x16x32_bf16 v[60:63], v[132:135], v[212:215], v[60:63]
	v_mfma_f32_16x16x32_bf16 v[56:59], v[164:167], v[212:215], v[56:59]
	v_mfma_f32_16x16x32_bf16 v[44:47], v[132:135], v[220:223], v[44:47]
	v_mfma_f32_16x16x32_bf16 v[40:43], v[164:167], v[220:223], v[40:43]
	v_mfma_f32_16x16x32_bf16 v[28:31], v[132:135], v[228:231], v[28:31]
	v_mfma_f32_16x16x32_bf16 v[24:27], v[164:167], v[228:231], v[24:27]
	v_mfma_f32_16x16x32_bf16 v[12:15], v[132:135], v[236:239], v[12:15]
	v_mfma_f32_16x16x32_bf16 v[8:11], v[164:167], v[236:239], v[8:11]
	v_mfma_f32_16x16x32_bf16 v[52:55], v[188:191], v[208:211], 0
	v_mfma_f32_16x16x32_bf16 v[48:51], v[200:203], v[208:211], 0
	v_mfma_f32_16x16x32_bf16 v[36:39], v[188:191], v[216:219], 0
	v_mfma_f32_16x16x32_bf16 v[32:35], v[200:203], v[216:219], 0
	v_mfma_f32_16x16x32_bf16 v[20:23], v[188:191], v[224:227], 0
	v_mfma_f32_16x16x32_bf16 v[16:19], v[200:203], v[224:227], 0
	v_mfma_f32_16x16x32_bf16 v[4:7], v[188:191], v[232:235], 0
	v_mfma_f32_16x16x32_bf16 v[0:3], v[200:203], v[232:235], 0
	v_mfma_f32_16x16x32_bf16 v[52:55], v[196:199], v[212:215], v[52:55]
	v_mfma_f32_16x16x32_bf16 v[48:51], v[204:207], v[212:215], v[48:51]
	v_mfma_f32_16x16x32_bf16 v[36:39], v[196:199], v[220:223], v[36:39]
	v_mfma_f32_16x16x32_bf16 v[32:35], v[204:207], v[220:223], v[32:35]
	v_mfma_f32_16x16x32_bf16 v[20:23], v[196:199], v[228:231], v[20:23]
	v_mfma_f32_16x16x32_bf16 v[16:19], v[204:207], v[228:231], v[16:19]
	v_mfma_f32_16x16x32_bf16 v[4:7], v[196:199], v[236:239], v[4:7]
	v_mfma_f32_16x16x32_bf16 v[0:3], v[204:207], v[236:239], v[0:3]
	s_setprio 0
	s_barrier
	s_add_i32 s68, 0, 0x18000
	s_add_i32 s69, 0, 0x1c000
	v_add_u32_e32 v164, s68, v141
	v_add_u32_e32 v187, s69, v141
	ds_read_b128 v[128:131], v164
	ds_read_b128 v[132:135], v164 offset:1024
	ds_read_b128 v[136:139], v164 offset:2048
	ds_read_b128 v[164:167], v164 offset:3072
	ds_read_b128 v[188:191], v187
	ds_read_b128 v[196:199], v187 offset:1024
	ds_read_b128 v[200:203], v187 offset:2048
	ds_read_b128 v[204:207], v187 offset:3072
	s_add_u32 s22, s22, 0xb0000
	s_addc_u32 s23, s23, 0
	s_mov_b32 m0, s39
	v_lshl_add_u64 v[244:245], s[22:23], 0, v[148:149]
	ds_read_b128 v[208:211], v185 offset:32768
	ds_read_b128 v[212:215], v185 offset:33792
	ds_read_b128 v[216:219], v185 offset:34816
	ds_read_b128 v[220:223], v185 offset:35840
	ds_read_b128 v[224:227], v185 offset:36864
	ds_read_b128 v[228:231], v185 offset:37888
	ds_read_b128 v[232:235], v185 offset:38912
	ds_read_b128 v[236:239], v185 offset:39936
	global_load_lds_dwordx4 v[244:245], off
	v_lshl_add_u64 v[244:245], s[22:23], 0, v[152:153]
	s_mov_b32 m0, s40
	s_nop 0
	global_load_lds_dwordx4 v[244:245], off
	s_waitcnt vmcnt(8)
	s_waitcnt lgkmcnt(0)
	s_barrier
	s_setprio 1
	s_waitcnt lgkmcnt(0)
	v_mfma_f32_16x16x32_bf16 v[124:127], v[128:131], v[208:211], v[124:127]
	v_mfma_f32_16x16x32_bf16 v[120:123], v[136:139], v[208:211], v[120:123]
	v_mfma_f32_16x16x32_bf16 v[108:111], v[128:131], v[216:219], v[108:111]
	v_mfma_f32_16x16x32_bf16 v[104:107], v[136:139], v[216:219], v[104:107]
	v_mfma_f32_16x16x32_bf16 v[92:95], v[128:131], v[224:227], v[92:95]
	v_mfma_f32_16x16x32_bf16 v[88:91], v[136:139], v[224:227], v[88:91]
	v_mfma_f32_16x16x32_bf16 v[76:79], v[128:131], v[232:235], v[76:79]
	v_mfma_f32_16x16x32_bf16 v[72:75], v[136:139], v[232:235], v[72:75]
	v_mfma_f32_16x16x32_bf16 v[124:127], v[132:135], v[212:215], v[124:127]
	v_mfma_f32_16x16x32_bf16 v[120:123], v[164:167], v[212:215], v[120:123]
	v_mfma_f32_16x16x32_bf16 v[108:111], v[132:135], v[220:223], v[108:111]
	v_mfma_f32_16x16x32_bf16 v[104:107], v[164:167], v[220:223], v[104:107]
	v_mfma_f32_16x16x32_bf16 v[92:95], v[132:135], v[228:231], v[92:95]
	v_mfma_f32_16x16x32_bf16 v[88:91], v[164:167], v[228:231], v[88:91]
	v_mfma_f32_16x16x32_bf16 v[76:79], v[132:135], v[236:239], v[76:79]
	v_mfma_f32_16x16x32_bf16 v[72:75], v[164:167], v[236:239], v[72:75]
	v_mfma_f32_16x16x32_bf16 v[116:119], v[188:191], v[208:211], v[116:119]
	v_mfma_f32_16x16x32_bf16 v[112:115], v[200:203], v[208:211], v[112:115]
	v_mfma_f32_16x16x32_bf16 v[100:103], v[188:191], v[216:219], v[100:103]
	v_mfma_f32_16x16x32_bf16 v[96:99], v[200:203], v[216:219], v[96:99]
	v_mfma_f32_16x16x32_bf16 v[84:87], v[188:191], v[224:227], v[84:87]
	v_mfma_f32_16x16x32_bf16 v[80:83], v[200:203], v[224:227], v[80:83]
	v_mfma_f32_16x16x32_bf16 v[68:71], v[188:191], v[232:235], v[68:71]
	v_mfma_f32_16x16x32_bf16 v[64:67], v[200:203], v[232:235], v[64:67]
	v_mfma_f32_16x16x32_bf16 v[116:119], v[196:199], v[212:215], v[116:119]
	v_mfma_f32_16x16x32_bf16 v[112:115], v[204:207], v[212:215], v[112:115]
	v_mfma_f32_16x16x32_bf16 v[100:103], v[196:199], v[220:223], v[100:103]
	v_mfma_f32_16x16x32_bf16 v[96:99], v[204:207], v[220:223], v[96:99]
	v_mfma_f32_16x16x32_bf16 v[84:87], v[196:199], v[228:231], v[84:87]
	v_mfma_f32_16x16x32_bf16 v[80:83], v[204:207], v[228:231], v[80:83]
	v_mfma_f32_16x16x32_bf16 v[68:71], v[196:199], v[236:239], v[68:71]
	v_mfma_f32_16x16x32_bf16 v[64:67], v[204:207], v[236:239], v[64:67]
	s_setprio 0
	s_barrier
	s_add_i32 s22, s68, s36
	v_lshl_add_u64 v[168:169], v[168:169], 0, s[26:27]
	s_mov_b32 m0, s22
	ds_read_b128 v[208:211], v185 offset:49152
	ds_read_b128 v[212:215], v185 offset:50176
	ds_read_b128 v[216:219], v185 offset:51200
	ds_read_b128 v[220:223], v185 offset:52224
	ds_read_b128 v[224:227], v185 offset:53248
	ds_read_b128 v[228:231], v185 offset:54272
	ds_read_b128 v[232:235], v185 offset:55296
	ds_read_b128 v[236:239], v185 offset:56320
	global_load_lds_dwordx4 v[168:169], off
	s_add_i32 m0, s22, 0x2000
	s_add_u32 s2, s2, 0xb0080
	v_lshl_add_u64 v[168:169], v[192:193], 0, s[26:27]
	s_addc_u32 s3, s3, 0
	s_add_i32 s22, s69, s36
	global_load_lds_dwordx4 v[168:169], off
	v_lshl_add_u64 v[168:169], s[2:3], 0, v[150:151]
	s_mov_b32 m0, s22
	s_nop 0
	global_load_lds_dwordx4 v[168:169], off
	v_lshl_add_u64 v[168:169], s[2:3], 0, v[154:155]
	s_add_i32 m0, s22, 0x2000
	s_nop 0
	global_load_lds_dwordx4 v[168:169], off
	v_lshl_add_u64 v[168:169], v[240:241], 0, s[26:27]
	s_mov_b32 m0, s44
	s_nop 0
	global_load_lds_dwordx4 v[168:169], off
	v_lshl_add_u64 v[168:169], v[242:243], 0, s[26:27]
	s_mov_b32 m0, s45
	s_nop 0
	global_load_lds_dwordx4 v[168:169], off
	s_waitcnt vmcnt(8)
	s_waitcnt lgkmcnt(0)
	s_barrier
	s_setprio 1
	s_waitcnt lgkmcnt(0)
	v_mfma_f32_16x16x32_bf16 v[60:63], v[128:131], v[208:211], v[60:63]
	v_mfma_f32_16x16x32_bf16 v[56:59], v[136:139], v[208:211], v[56:59]
	v_mfma_f32_16x16x32_bf16 v[44:47], v[128:131], v[216:219], v[44:47]
	v_mfma_f32_16x16x32_bf16 v[40:43], v[136:139], v[216:219], v[40:43]
	v_mfma_f32_16x16x32_bf16 v[28:31], v[128:131], v[224:227], v[28:31]
	v_mfma_f32_16x16x32_bf16 v[24:27], v[136:139], v[224:227], v[24:27]
	v_mfma_f32_16x16x32_bf16 v[12:15], v[128:131], v[232:235], v[12:15]
	v_mfma_f32_16x16x32_bf16 v[8:11], v[136:139], v[232:235], v[8:11]
	v_mfma_f32_16x16x32_bf16 v[60:63], v[132:135], v[212:215], v[60:63]
	v_mfma_f32_16x16x32_bf16 v[56:59], v[164:167], v[212:215], v[56:59]
	v_mfma_f32_16x16x32_bf16 v[44:47], v[132:135], v[220:223], v[44:47]
	v_mfma_f32_16x16x32_bf16 v[40:43], v[164:167], v[220:223], v[40:43]
	v_mfma_f32_16x16x32_bf16 v[28:31], v[132:135], v[228:231], v[28:31]
	v_mfma_f32_16x16x32_bf16 v[24:27], v[164:167], v[228:231], v[24:27]
	v_mfma_f32_16x16x32_bf16 v[12:15], v[132:135], v[236:239], v[12:15]
	v_mfma_f32_16x16x32_bf16 v[8:11], v[164:167], v[236:239], v[8:11]
	v_mfma_f32_16x16x32_bf16 v[52:55], v[188:191], v[208:211], v[52:55]
	v_mfma_f32_16x16x32_bf16 v[48:51], v[200:203], v[208:211], v[48:51]
	v_mfma_f32_16x16x32_bf16 v[36:39], v[188:191], v[216:219], v[36:39]
	v_mfma_f32_16x16x32_bf16 v[32:35], v[200:203], v[216:219], v[32:35]
	v_mfma_f32_16x16x32_bf16 v[20:23], v[188:191], v[224:227], v[20:23]
	v_mfma_f32_16x16x32_bf16 v[16:19], v[200:203], v[224:227], v[16:19]
	v_mfma_f32_16x16x32_bf16 v[4:7], v[188:191], v[232:235], v[4:7]
	v_mfma_f32_16x16x32_bf16 v[0:3], v[200:203], v[232:235], v[0:3]
	v_mfma_f32_16x16x32_bf16 v[52:55], v[196:199], v[212:215], v[52:55]
	v_mfma_f32_16x16x32_bf16 v[48:51], v[204:207], v[212:215], v[48:51]
	v_mfma_f32_16x16x32_bf16 v[36:39], v[196:199], v[220:223], v[36:39]
	v_mfma_f32_16x16x32_bf16 v[32:35], v[204:207], v[220:223], v[32:35]
	v_mfma_f32_16x16x32_bf16 v[20:23], v[196:199], v[228:231], v[20:23]
	v_mfma_f32_16x16x32_bf16 v[16:19], v[204:207], v[228:231], v[16:19]
	v_mfma_f32_16x16x32_bf16 v[4:7], v[196:199], v[236:239], v[4:7]
	v_mfma_f32_16x16x32_bf16 v[0:3], v[204:207], v[236:239], v[0:3]
	s_setprio 0
	s_barrier
	s_add_i32 s67, s67, 2
	s_add_u32 s14, s14, 0x100
	s_addc_u32 s15, s15, 0
	s_add_u32 s65, s65, 0x100
	s_addc_u32 s66, s66, 0
	s_cmp_gt_u32 s67, 41
	s_cbranch_scc1 .Lgemm_kdone_2
.LBB0_455:
	ds_read_b128 v[128:131], v147
	ds_read_b128 v[132:135], v147 offset:1024
	ds_read_b128 v[136:139], v147 offset:2048
	ds_read_b128 v[164:167], v147 offset:3072
	ds_read_b128 v[188:191], v184
	ds_read_b128 v[196:199], v184 offset:1024
	ds_read_b128 v[200:203], v184 offset:2048
	ds_read_b128 v[204:207], v184 offset:3072
	s_add_u32 s2, s14, 0xfff50080
	s_addc_u32 s3, s15, -1
	s_cmp_eq_u32 s67, 40
	s_cselect_b32 s23, s1, s3
	s_cselect_b32 s22, s0, s2
	s_cselect_b32 s3, s31, s66
	s_cselect_b32 s2, s30, s65
	v_lshl_add_u64 v[168:169], s[14:15], 0, v[156:157]
	s_add_i32 m0, s37, 0xc000
	ds_read_b128 v[208:211], v185
	ds_read_b128 v[212:215], v185 offset:1024
	ds_read_b128 v[216:219], v185 offset:2048
	ds_read_b128 v[220:223], v185 offset:3072
	ds_read_b128 v[224:227], v185 offset:4096
	ds_read_b128 v[228:231], v185 offset:5120
	ds_read_b128 v[232:235], v185 offset:6144
	ds_read_b128 v[236:239], v185 offset:7168
	global_load_lds_dwordx4 v[168:169], off
	v_lshl_add_u64 v[168:169], s[14:15], 0, v[158:159]
	s_add_i32 m0, s37, 0xe000
	s_nop 0
	global_load_lds_dwordx4 v[168:169], off
	s_waitcnt vmcnt(8)
	s_waitcnt lgkmcnt(0)
	s_barrier
	s_setprio 1
	s_waitcnt lgkmcnt(0)
	v_mfma_f32_16x16x32_bf16 v[124:127], v[128:131], v[208:211], v[124:127]
	v_mfma_f32_16x16x32_bf16 v[120:123], v[136:139], v[208:211], v[120:123]
	v_mfma_f32_16x16x32_bf16 v[108:111], v[128:131], v[216:219], v[108:111]
	v_mfma_f32_16x16x32_bf16 v[104:107], v[136:139], v[216:219], v[104:107]
	v_mfma_f32_16x16x32_bf16 v[92:95], v[128:131], v[224:227], v[92:95]
	v_mfma_f32_16x16x32_bf16 v[88:91], v[136:139], v[224:227], v[88:91]
	v_mfma_f32_16x16x32_bf16 v[76:79], v[128:131], v[232:235], v[76:79]
	v_mfma_f32_16x16x32_bf16 v[72:75], v[136:139], v[232:235], v[72:75]
	v_mfma_f32_16x16x32_bf16 v[124:127], v[132:135], v[212:215], v[124:127]
	v_mfma_f32_16x16x32_bf16 v[120:123], v[164:167], v[212:215], v[120:123]
	v_mfma_f32_16x16x32_bf16 v[108:111], v[132:135], v[220:223], v[108:111]
	v_mfma_f32_16x16x32_bf16 v[104:107], v[164:167], v[220:223], v[104:107]
	v_mfma_f32_16x16x32_bf16 v[92:95], v[132:135], v[228:231], v[92:95]
	v_mfma_f32_16x16x32_bf16 v[88:91], v[164:167], v[228:231], v[88:91]
	v_mfma_f32_16x16x32_bf16 v[76:79], v[132:135], v[236:239], v[76:79]
	v_mfma_f32_16x16x32_bf16 v[72:75], v[164:167], v[236:239], v[72:75]
	v_mfma_f32_16x16x32_bf16 v[116:119], v[188:191], v[208:211], v[116:119]
	v_mfma_f32_16x16x32_bf16 v[112:115], v[200:203], v[208:211], v[112:115]
	v_mfma_f32_16x16x32_bf16 v[100:103], v[188:191], v[216:219], v[100:103]
	v_mfma_f32_16x16x32_bf16 v[96:99], v[200:203], v[216:219], v[96:99]
	v_mfma_f32_16x16x32_bf16 v[84:87], v[188:191], v[224:227], v[84:87]
	v_mfma_f32_16x16x32_bf16 v[80:83], v[200:203], v[224:227], v[80:83]
	v_mfma_f32_16x16x32_bf16 v[68:71], v[188:191], v[232:235], v[68:71]
	v_mfma_f32_16x16x32_bf16 v[64:67], v[200:203], v[232:235], v[64:67]
	v_mfma_f32_16x16x32_bf16 v[116:119], v[196:199], v[212:215], v[116:119]
	v_mfma_f32_16x16x32_bf16 v[112:115], v[204:207], v[212:215], v[112:115]
	v_mfma_f32_16x16x32_bf16 v[100:103], v[196:199], v[220:223], v[100:103]
	v_mfma_f32_16x16x32_bf16 v[96:99], v[204:207], v[220:223], v[96:99]
	v_mfma_f32_16x16x32_bf16 v[84:87], v[196:199], v[228:231], v[84:87]
	v_mfma_f32_16x16x32_bf16 v[80:83], v[204:207], v[228:231], v[80:83]
	v_mfma_f32_16x16x32_bf16 v[68:71], v[196:199], v[236:239], v[68:71]
	v_mfma_f32_16x16x32_bf16 v[64:67], v[204:207], v[236:239], v[64:67]
	s_setprio 0
	s_barrier
	s_add_i32 s68, s51, s36
	v_lshl_add_u64 v[168:169], s[2:3], 0, v[150:151]
	s_mov_b32 m0, s68
	ds_read_b128 v[208:211], v185 offset:16384
	ds_read_b128 v[212:215], v185 offset:17408
	ds_read_b128 v[216:219], v185 offset:18432
	ds_read_b128 v[220:223], v185 offset:19456
	ds_read_b128 v[224:227], v185 offset:20480
	ds_read_b128 v[228:231], v185 offset:21504
	ds_read_b128 v[232:235], v185 offset:22528
	ds_read_b128 v[236:239], v185 offset:23552
	global_load_lds_dwordx4 v[168:169], off
	s_add_i32 m0, s68, 0x2000
	s_add_u32 s68, s2, 0xb0000
	v_lshl_add_u64 v[192:193], s[2:3], 0, v[154:155]
	s_addc_u32 s69, s3, 0
	s_add_i32 s70, s52, s36
	global_load_lds_dwordx4 v[192:193], off
	v_lshl_add_u64 v[240:241], s[68:69], 0, v[150:151]
	s_mov_b32 m0, s70
	v_lshl_add_u64 v[242:243], s[22:23], 0, v[152:153]
	global_load_lds_dwordx4 v[240:241], off
	v_lshl_add_u64 v[240:241], s[68:69], 0, v[154:155]
	s_add_i32 m0, s70, 0x2000
	s_nop 0
	global_load_lds_dwordx4 v[240:241], off
	v_lshl_add_u64 v[240:241], s[22:23], 0, v[148:149]
	s_mov_b32 m0, s37
	s_nop 0
	global_load_lds_dwordx4 v[240:241], off
	s_mov_b32 m0, s38
	s_nop 0
	global_load_lds_dwordx4 v[242:243], off
	s_waitcnt vmcnt(8)
	s_waitcnt lgkmcnt(0)
	s_barrier
	s_setprio 1
	s_waitcnt lgkmcnt(0)
	v_mfma_f32_16x16x32_bf16 v[60:63], v[128:131], v[208:211], v[60:63]
	v_mfma_f32_16x16x32_bf16 v[56:59], v[136:139], v[208:211], v[56:59]
	v_mfma_f32_16x16x32_bf16 v[44:47], v[128:131], v[216:219], v[44:47]
	v_mfma_f32_16x16x32_bf16 v[40:43], v[136:139], v[216:219], v[40:43]
	v_mfma_f32_16x16x32_bf16 v[28:31], v[128:131], v[224:227], v[28:31]
	v_mfma_f32_16x16x32_bf16 v[24:27], v[136:139], v[224:227], v[24:27]
	v_mfma_f32_16x16x32_bf16 v[12:15], v[128:131], v[232:235], v[12:15]
	v_mfma_f32_16x16x32_bf16 v[8:11], v[136:139], v[232:235], v[8:11]
	v_mfma_f32_16x16x32_bf16 v[60:63], v[132:135], v[212:215], v[60:63]
	v_mfma_f32_16x16x32_bf16 v[56:59], v[164:167], v[212:215], v[56:59]
	v_mfma_f32_16x16x32_bf16 v[44:47], v[132:135], v[220:223], v[44:47]
	v_mfma_f32_16x16x32_bf16 v[40:43], v[164:167], v[220:223], v[40:43]
	v_mfma_f32_16x16x32_bf16 v[28:31], v[132:135], v[228:231], v[28:31]
	v_mfma_f32_16x16x32_bf16 v[24:27], v[164:167], v[228:231], v[24:27]
	v_mfma_f32_16x16x32_bf16 v[12:15], v[132:135], v[236:239], v[12:15]
	v_mfma_f32_16x16x32_bf16 v[8:11], v[164:167], v[236:239], v[8:11]
	v_mfma_f32_16x16x32_bf16 v[52:55], v[188:191], v[208:211], v[52:55]
	v_mfma_f32_16x16x32_bf16 v[48:51], v[200:203], v[208:211], v[48:51]
	v_mfma_f32_16x16x32_bf16 v[36:39], v[188:191], v[216:219], v[36:39]
	v_mfma_f32_16x16x32_bf16 v[32:35], v[200:203], v[216:219], v[32:35]
	v_mfma_f32_16x16x32_bf16 v[20:23], v[188:191], v[224:227], v[20:23]
	v_mfma_f32_16x16x32_bf16 v[16:19], v[200:203], v[224:227], v[16:19]
	v_mfma_f32_16x16x32_bf16 v[4:7], v[188:191], v[232:235], v[4:7]
	v_mfma_f32_16x16x32_bf16 v[0:3], v[200:203], v[232:235], v[0:3]
	v_mfma_f32_16x16x32_bf16 v[52:55], v[196:199], v[212:215], v[52:55]
	v_mfma_f32_16x16x32_bf16 v[48:51], v[204:207], v[212:215], v[48:51]
	v_mfma_f32_16x16x32_bf16 v[36:39], v[196:199], v[220:223], v[36:39]
	v_mfma_f32_16x16x32_bf16 v[32:35], v[204:207], v[220:223], v[32:35]
	v_mfma_f32_16x16x32_bf16 v[20:23], v[196:199], v[228:231], v[20:23]
	v_mfma_f32_16x16x32_bf16 v[16:19], v[204:207], v[228:231], v[16:19]
	v_mfma_f32_16x16x32_bf16 v[4:7], v[196:199], v[236:239], v[4:7]
	v_mfma_f32_16x16x32_bf16 v[0:3], v[204:207], v[236:239], v[0:3]
	s_setprio 0
	s_barrier
	s_add_i32 s68, 0, 0x18000
	s_add_i32 s69, 0, 0x1c000
	v_add_u32_e32 v164, s68, v141
	v_add_u32_e32 v187, s69, v141
	ds_read_b128 v[128:131], v164
	ds_read_b128 v[132:135], v164 offset:1024
	ds_read_b128 v[136:139], v164 offset:2048
	ds_read_b128 v[164:167], v164 offset:3072
	ds_read_b128 v[188:191], v187
	ds_read_b128 v[196:199], v187 offset:1024
	ds_read_b128 v[200:203], v187 offset:2048
	ds_read_b128 v[204:207], v187 offset:3072
	s_add_u32 s22, s22, 0xb0000
	s_addc_u32 s23, s23, 0
	s_mov_b32 m0, s39
	v_lshl_add_u64 v[244:245], s[22:23], 0, v[148:149]
	ds_read_b128 v[208:211], v185 offset:32768
	ds_read_b128 v[212:215], v185 offset:33792
	ds_read_b128 v[216:219], v185 offset:34816
	ds_read_b128 v[220:223], v185 offset:35840
	ds_read_b128 v[224:227], v185 offset:36864
	ds_read_b128 v[228:231], v185 offset:37888
	ds_read_b128 v[232:235], v185 offset:38912
	ds_read_b128 v[236:239], v185 offset:39936
	global_load_lds_dwordx4 v[244:245], off
	v_lshl_add_u64 v[244:245], s[22:23], 0, v[152:153]
	s_mov_b32 m0, s40
	s_nop 0
	global_load_lds_dwordx4 v[244:245], off
	s_waitcnt vmcnt(8)
	s_waitcnt lgkmcnt(0)
	s_barrier
	s_setprio 1
	s_waitcnt lgkmcnt(0)
	v_mfma_f32_16x16x32_bf16 v[124:127], v[128:131], v[208:211], v[124:127]
	v_mfma_f32_16x16x32_bf16 v[120:123], v[136:139], v[208:211], v[120:123]
	v_mfma_f32_16x16x32_bf16 v[108:111], v[128:131], v[216:219], v[108:111]
	v_mfma_f32_16x16x32_bf16 v[104:107], v[136:139], v[216:219], v[104:107]
	v_mfma_f32_16x16x32_bf16 v[92:95], v[128:131], v[224:227], v[92:95]
	v_mfma_f32_16x16x32_bf16 v[88:91], v[136:139], v[224:227], v[88:91]
	v_mfma_f32_16x16x32_bf16 v[76:79], v[128:131], v[232:235], v[76:79]
	v_mfma_f32_16x16x32_bf16 v[72:75], v[136:139], v[232:235], v[72:75]
	v_mfma_f32_16x16x32_bf16 v[124:127], v[132:135], v[212:215], v[124:127]
	v_mfma_f32_16x16x32_bf16 v[120:123], v[164:167], v[212:215], v[120:123]
	v_mfma_f32_16x16x32_bf16 v[108:111], v[132:135], v[220:223], v[108:111]
	v_mfma_f32_16x16x32_bf16 v[104:107], v[164:167], v[220:223], v[104:107]
	v_mfma_f32_16x16x32_bf16 v[92:95], v[132:135], v[228:231], v[92:95]
	v_mfma_f32_16x16x32_bf16 v[88:91], v[164:167], v[228:231], v[88:91]
	v_mfma_f32_16x16x32_bf16 v[76:79], v[132:135], v[236:239], v[76:79]
	v_mfma_f32_16x16x32_bf16 v[72:75], v[164:167], v[236:239], v[72:75]
	v_mfma_f32_16x16x32_bf16 v[116:119], v[188:191], v[208:211], v[116:119]
	v_mfma_f32_16x16x32_bf16 v[112:115], v[200:203], v[208:211], v[112:115]
	v_mfma_f32_16x16x32_bf16 v[100:103], v[188:191], v[216:219], v[100:103]
	v_mfma_f32_16x16x32_bf16 v[96:99], v[200:203], v[216:219], v[96:99]
	v_mfma_f32_16x16x32_bf16 v[84:87], v[188:191], v[224:227], v[84:87]
	v_mfma_f32_16x16x32_bf16 v[80:83], v[200:203], v[224:227], v[80:83]
	v_mfma_f32_16x16x32_bf16 v[68:71], v[188:191], v[232:235], v[68:71]
	v_mfma_f32_16x16x32_bf16 v[64:67], v[200:203], v[232:235], v[64:67]
	v_mfma_f32_16x16x32_bf16 v[116:119], v[196:199], v[212:215], v[116:119]
	v_mfma_f32_16x16x32_bf16 v[112:115], v[204:207], v[212:215], v[112:115]
	v_mfma_f32_16x16x32_bf16 v[100:103], v[196:199], v[220:223], v[100:103]
	v_mfma_f32_16x16x32_bf16 v[96:99], v[204:207], v[220:223], v[96:99]
	v_mfma_f32_16x16x32_bf16 v[84:87], v[196:199], v[228:231], v[84:87]
	v_mfma_f32_16x16x32_bf16 v[80:83], v[204:207], v[228:231], v[80:83]
	v_mfma_f32_16x16x32_bf16 v[68:71], v[196:199], v[236:239], v[68:71]
	v_mfma_f32_16x16x32_bf16 v[64:67], v[204:207], v[236:239], v[64:67]
	s_setprio 0
	s_barrier
	s_add_i32 s22, s68, s36
	v_lshl_add_u64 v[168:169], v[168:169], 0, s[26:27]
	s_mov_b32 m0, s22
	ds_read_b128 v[208:211], v185 offset:49152
	ds_read_b128 v[212:215], v185 offset:50176
	ds_read_b128 v[216:219], v185 offset:51200
	ds_read_b128 v[220:223], v185 offset:52224
	ds_read_b128 v[224:227], v185 offset:53248
	ds_read_b128 v[228:231], v185 offset:54272
	ds_read_b128 v[232:235], v185 offset:55296
	ds_read_b128 v[236:239], v185 offset:56320
	global_load_lds_dwordx4 v[168:169], off
	s_add_i32 m0, s22, 0x2000
	s_add_u32 s2, s2, 0xb0080
	v_lshl_add_u64 v[168:169], v[192:193], 0, s[26:27]
	s_addc_u32 s3, s3, 0
	s_add_i32 s22, s69, s36
	global_load_lds_dwordx4 v[168:169], off
	v_lshl_add_u64 v[168:169], s[2:3], 0, v[150:151]
	s_mov_b32 m0, s22
	s_nop 0
	global_load_lds_dwordx4 v[168:169], off
	v_lshl_add_u64 v[168:169], s[2:3], 0, v[154:155]
	s_add_i32 m0, s22, 0x2000
	s_nop 0
	global_load_lds_dwordx4 v[168:169], off
	v_lshl_add_u64 v[168:169], v[240:241], 0, s[26:27]
	s_mov_b32 m0, s44
	s_nop 0
	global_load_lds_dwordx4 v[168:169], off
	v_lshl_add_u64 v[168:169], v[242:243], 0, s[26:27]
	s_mov_b32 m0, s45
	s_nop 0
	global_load_lds_dwordx4 v[168:169], off
	s_waitcnt vmcnt(8)
	s_waitcnt lgkmcnt(0)
	s_barrier
	s_setprio 1
	s_waitcnt lgkmcnt(0)
	v_mfma_f32_16x16x32_bf16 v[60:63], v[128:131], v[208:211], v[60:63]
	v_mfma_f32_16x16x32_bf16 v[56:59], v[136:139], v[208:211], v[56:59]
	v_mfma_f32_16x16x32_bf16 v[44:47], v[128:131], v[216:219], v[44:47]
	v_mfma_f32_16x16x32_bf16 v[40:43], v[136:139], v[216:219], v[40:43]
	v_mfma_f32_16x16x32_bf16 v[28:31], v[128:131], v[224:227], v[28:31]
	v_mfma_f32_16x16x32_bf16 v[24:27], v[136:139], v[224:227], v[24:27]
	v_mfma_f32_16x16x32_bf16 v[12:15], v[128:131], v[232:235], v[12:15]
	v_mfma_f32_16x16x32_bf16 v[8:11], v[136:139], v[232:235], v[8:11]
	v_mfma_f32_16x16x32_bf16 v[60:63], v[132:135], v[212:215], v[60:63]
	v_mfma_f32_16x16x32_bf16 v[56:59], v[164:167], v[212:215], v[56:59]
	v_mfma_f32_16x16x32_bf16 v[44:47], v[132:135], v[220:223], v[44:47]
	v_mfma_f32_16x16x32_bf16 v[40:43], v[164:167], v[220:223], v[40:43]
	v_mfma_f32_16x16x32_bf16 v[28:31], v[132:135], v[228:231], v[28:31]
	v_mfma_f32_16x16x32_bf16 v[24:27], v[164:167], v[228:231], v[24:27]
	v_mfma_f32_16x16x32_bf16 v[12:15], v[132:135], v[236:239], v[12:15]
	v_mfma_f32_16x16x32_bf16 v[8:11], v[164:167], v[236:239], v[8:11]
	v_mfma_f32_16x16x32_bf16 v[52:55], v[188:191], v[208:211], v[52:55]
	v_mfma_f32_16x16x32_bf16 v[48:51], v[200:203], v[208:211], v[48:51]
	v_mfma_f32_16x16x32_bf16 v[36:39], v[188:191], v[216:219], v[36:39]
	v_mfma_f32_16x16x32_bf16 v[32:35], v[200:203], v[216:219], v[32:35]
	v_mfma_f32_16x16x32_bf16 v[20:23], v[188:191], v[224:227], v[20:23]
	v_mfma_f32_16x16x32_bf16 v[16:19], v[200:203], v[224:227], v[16:19]
	v_mfma_f32_16x16x32_bf16 v[4:7], v[188:191], v[232:235], v[4:7]
	v_mfma_f32_16x16x32_bf16 v[0:3], v[200:203], v[232:235], v[0:3]
	v_mfma_f32_16x16x32_bf16 v[52:55], v[196:199], v[212:215], v[52:55]
	v_mfma_f32_16x16x32_bf16 v[48:51], v[204:207], v[212:215], v[48:51]
	v_mfma_f32_16x16x32_bf16 v[36:39], v[196:199], v[220:223], v[36:39]
	v_mfma_f32_16x16x32_bf16 v[32:35], v[204:207], v[220:223], v[32:35]
	v_mfma_f32_16x16x32_bf16 v[20:23], v[196:199], v[228:231], v[20:23]
	v_mfma_f32_16x16x32_bf16 v[16:19], v[204:207], v[228:231], v[16:19]
	v_mfma_f32_16x16x32_bf16 v[4:7], v[196:199], v[236:239], v[4:7]
	v_mfma_f32_16x16x32_bf16 v[0:3], v[204:207], v[236:239], v[0:3]
	s_setprio 0
	s_barrier
	s_add_i32 s67, s67, 2
	s_add_u32 s14, s14, 0x100
	s_addc_u32 s15, s15, 0
	s_add_u32 s65, s65, 0x100
	s_addc_u32 s66, s66, 0
	s_cmp_gt_u32 s67, 41
	s_cbranch_scc0 .LBB0_455

.LBB0_551:
	s_ashr_i32 s41, s40, 31
	s_lshl_b64 s[22:23], s[40:41], 19
	s_add_u32 s42, s84, s22
	s_addc_u32 s43, s85, s23
	s_and_b64 s[22:23], s[4:5], exec
	s_cselect_b32 s41, s43, s15
	s_cselect_b32 s69, s42, s14
	s_ashr_i32 s39, s38, 31
	s_lshl_b64 s[22:23], s[38:39], 19
	s_add_u32 s44, s34, s22
	s_addc_u32 s45, s35, s23
	s_and_b64 s[22:23], s[4:5], exec
	s_cselect_b32 s39, s45, s3
	s_cselect_b32 s70, s44, s2
	s_add_u32 s14, s14, 0x40080
	s_addc_u32 s15, s15, 0
	s_add_u32 s71, s2, 0x100
	s_addc_u32 s72, s3, 0
	s_mov_b32 s73, -2
	s_waitcnt vmcnt(0)
	ds_read_b128 v[156:159], v155
	ds_read_b128 v[160:163], v155 offset:1024
	ds_read_b128 v[184:187], v155 offset:2048
	ds_read_b128 v[188:191], v155 offset:3072
	ds_read_b128 v[196:199], v166
	ds_read_b128 v[200:203], v166 offset:1024
	ds_read_b128 v[204:207], v166 offset:2048
	ds_read_b128 v[208:211], v166 offset:3072
	s_add_u32 s2, s14, 0xfffc0080
	s_addc_u32 s3, s15, -1
	s_cmp_eq_u32 s73, 12
	s_cselect_b32 s23, s41, s3
	s_cselect_b32 s22, s69, s2
	s_cselect_b32 s3, s39, s72
	s_cselect_b32 s2, s70, s71
	v_lshl_add_u64 v[138:139], s[14:15], 0, v[130:131]
	s_add_i32 m0, s49, 0xc000
	ds_read_b128 v[212:215], v167
	ds_read_b128 v[216:219], v167 offset:1024
	ds_read_b128 v[220:223], v167 offset:2048
	ds_read_b128 v[224:227], v167 offset:3072
	ds_read_b128 v[228:231], v167 offset:4096
	ds_read_b128 v[232:235], v167 offset:5120
	ds_read_b128 v[236:239], v167 offset:6144
	ds_read_b128 v[240:243], v167 offset:7168
	global_load_lds_dwordx4 v[138:139], off
	v_lshl_add_u64 v[138:139], s[14:15], 0, v[132:133]
	s_add_i32 m0, s49, 0xe000
	s_nop 0
	global_load_lds_dwordx4 v[138:139], off
	s_waitcnt vmcnt(8)
	s_waitcnt lgkmcnt(0)
	s_barrier
	s_setprio 1
	s_waitcnt lgkmcnt(0)
	v_mfma_f32_16x16x32_bf16 v[124:127], v[156:159], v[212:215], 0
	v_mfma_f32_16x16x32_bf16 v[120:123], v[184:187], v[212:215], 0
	v_mfma_f32_16x16x32_bf16 v[116:119], v[156:159], v[220:223], 0
	v_mfma_f32_16x16x32_bf16 v[112:115], v[184:187], v[220:223], 0
	v_mfma_f32_16x16x32_bf16 v[92:95], v[156:159], v[228:231], 0
	v_mfma_f32_16x16x32_bf16 v[88:91], v[184:187], v[228:231], 0
	v_mfma_f32_16x16x32_bf16 v[76:79], v[156:159], v[236:239], 0
	v_mfma_f32_16x16x32_bf16 v[72:75], v[184:187], v[236:239], 0
	v_mfma_f32_16x16x32_bf16 v[124:127], v[160:163], v[216:219], v[124:127]
	v_mfma_f32_16x16x32_bf16 v[120:123], v[188:191], v[216:219], v[120:123]
	v_mfma_f32_16x16x32_bf16 v[116:119], v[160:163], v[224:227], v[116:119]
	v_mfma_f32_16x16x32_bf16 v[112:115], v[188:191], v[224:227], v[112:115]
	v_mfma_f32_16x16x32_bf16 v[92:95], v[160:163], v[232:235], v[92:95]
	v_mfma_f32_16x16x32_bf16 v[88:91], v[188:191], v[232:235], v[88:91]
	v_mfma_f32_16x16x32_bf16 v[76:79], v[160:163], v[240:243], v[76:79]
	v_mfma_f32_16x16x32_bf16 v[72:75], v[188:191], v[240:243], v[72:75]
	v_mfma_f32_16x16x32_bf16 v[108:111], v[196:199], v[212:215], 0
	v_mfma_f32_16x16x32_bf16 v[104:107], v[204:207], v[212:215], 0
	v_mfma_f32_16x16x32_bf16 v[100:103], v[196:199], v[220:223], 0
	v_mfma_f32_16x16x32_bf16 v[96:99], v[204:207], v[220:223], 0
	v_mfma_f32_16x16x32_bf16 v[84:87], v[196:199], v[228:231], 0
	v_mfma_f32_16x16x32_bf16 v[80:83], v[204:207], v[228:231], 0
	v_mfma_f32_16x16x32_bf16 v[68:71], v[196:199], v[236:239], 0
	v_mfma_f32_16x16x32_bf16 v[64:67], v[204:207], v[236:239], 0
	v_mfma_f32_16x16x32_bf16 v[108:111], v[200:203], v[216:219], v[108:111]
	v_mfma_f32_16x16x32_bf16 v[104:107], v[208:211], v[216:219], v[104:107]
	v_mfma_f32_16x16x32_bf16 v[100:103], v[200:203], v[224:227], v[100:103]
	v_mfma_f32_16x16x32_bf16 v[96:99], v[208:211], v[224:227], v[96:99]
	v_mfma_f32_16x16x32_bf16 v[84:87], v[200:203], v[232:235], v[84:87]
	v_mfma_f32_16x16x32_bf16 v[80:83], v[208:211], v[232:235], v[80:83]
	v_mfma_f32_16x16x32_bf16 v[68:71], v[200:203], v[240:243], v[68:71]
	v_mfma_f32_16x16x32_bf16 v[64:67], v[208:211], v[240:243], v[64:67]
	s_setprio 0
	s_barrier
	s_add_i32 s74, s58, s46
	v_lshl_add_u64 v[138:139], s[2:3], 0, v[142:143]
	s_mov_b32 m0, s74
	ds_read_b128 v[212:215], v167 offset:16384
	ds_read_b128 v[216:219], v167 offset:17408
	ds_read_b128 v[220:223], v167 offset:18432
	ds_read_b128 v[224:227], v167 offset:19456
	ds_read_b128 v[228:231], v167 offset:20480
	ds_read_b128 v[232:235], v167 offset:21504
	ds_read_b128 v[236:239], v167 offset:22528
	ds_read_b128 v[240:243], v167 offset:23552
	global_load_lds_dwordx4 v[138:139], off
	s_add_i32 m0, s74, 0x2000
	s_add_u32 s74, s2, 0x40000
	v_lshl_add_u64 v[164:165], s[2:3], 0, v[146:147]
	s_addc_u32 s75, s3, 0
	s_add_i32 s76, s59, s46
	global_load_lds_dwordx4 v[164:165], off
	v_lshl_add_u64 v[192:193], s[74:75], 0, v[142:143]
	s_mov_b32 m0, s76
	v_lshl_add_u64 v[244:245], s[22:23], 0, v[144:145]
	global_load_lds_dwordx4 v[192:193], off
	v_lshl_add_u64 v[192:193], s[74:75], 0, v[146:147]
	s_add_i32 m0, s76, 0x2000
	s_nop 0
	global_load_lds_dwordx4 v[192:193], off
	v_lshl_add_u64 v[192:193], s[22:23], 0, v[140:141]
	s_mov_b32 m0, s49
	s_nop 0
	global_load_lds_dwordx4 v[192:193], off
	s_mov_b32 m0, s50
	s_nop 0
	global_load_lds_dwordx4 v[244:245], off
	s_waitcnt vmcnt(8)
	s_waitcnt lgkmcnt(0)
	s_barrier
	s_setprio 1
	s_waitcnt lgkmcnt(0)
	v_mfma_f32_16x16x32_bf16 v[60:63], v[156:159], v[212:215], 0
	v_mfma_f32_16x16x32_bf16 v[56:59], v[184:187], v[212:215], 0
	v_mfma_f32_16x16x32_bf16 v[44:47], v[156:159], v[220:223], 0
	v_mfma_f32_16x16x32_bf16 v[40:43], v[184:187], v[220:223], 0
	v_mfma_f32_16x16x32_bf16 v[28:31], v[156:159], v[228:231], 0
	v_mfma_f32_16x16x32_bf16 v[24:27], v[184:187], v[228:231], 0
	v_mfma_f32_16x16x32_bf16 v[12:15], v[156:159], v[236:239], 0
	v_mfma_f32_16x16x32_bf16 v[8:11], v[184:187], v[236:239], 0
	v_mfma_f32_16x16x32_bf16 v[60:63], v[160:163], v[216:219], v[60:63]
	v_mfma_f32_16x16x32_bf16 v[56:59], v[188:191], v[216:219], v[56:59]
	v_mfma_f32_16x16x32_bf16 v[44:47], v[160:163], v[224:227], v[44:47]
	v_mfma_f32_16x16x32_bf16 v[40:43], v[188:191], v[224:227], v[40:43]
	v_mfma_f32_16x16x32_bf16 v[28:31], v[160:163], v[232:235], v[28:31]
	v_mfma_f32_16x16x32_bf16 v[24:27], v[188:191], v[232:235], v[24:27]
	v_mfma_f32_16x16x32_bf16 v[12:15], v[160:163], v[240:243], v[12:15]
	v_mfma_f32_16x16x32_bf16 v[8:11], v[188:191], v[240:243], v[8:11]
	v_mfma_f32_16x16x32_bf16 v[52:55], v[196:199], v[212:215], 0
	v_mfma_f32_16x16x32_bf16 v[48:51], v[204:207], v[212:215], 0
	v_mfma_f32_16x16x32_bf16 v[36:39], v[196:199], v[220:223], 0
	v_mfma_f32_16x16x32_bf16 v[32:35], v[204:207], v[220:223], 0
	v_mfma_f32_16x16x32_bf16 v[20:23], v[196:199], v[228:231], 0
	v_mfma_f32_16x16x32_bf16 v[16:19], v[204:207], v[228:231], 0
	v_mfma_f32_16x16x32_bf16 v[4:7], v[196:199], v[236:239], 0
	v_mfma_f32_16x16x32_bf16 v[0:3], v[204:207], v[236:239], 0
	v_mfma_f32_16x16x32_bf16 v[52:55], v[200:203], v[216:219], v[52:55]
	v_mfma_f32_16x16x32_bf16 v[48:51], v[208:211], v[216:219], v[48:51]
	v_mfma_f32_16x16x32_bf16 v[36:39], v[200:203], v[224:227], v[36:39]
	v_mfma_f32_16x16x32_bf16 v[32:35], v[208:211], v[224:227], v[32:35]
	v_mfma_f32_16x16x32_bf16 v[20:23], v[200:203], v[232:235], v[20:23]
	v_mfma_f32_16x16x32_bf16 v[16:19], v[208:211], v[232:235], v[16:19]
	v_mfma_f32_16x16x32_bf16 v[4:7], v[200:203], v[240:243], v[4:7]
	v_mfma_f32_16x16x32_bf16 v[0:3], v[208:211], v[240:243], v[0:3]
	s_setprio 0
	s_barrier
	s_add_i32 s74, 0, 0x18000
	v_add_u32_e32 v128, s74, v151
	s_add_i32 s75, 0, 0x1c000
	ds_read_b128 v[156:159], v128
	ds_read_b128 v[160:163], v128 offset:1024
	ds_read_b128 v[184:187], v128 offset:2048
	ds_read_b128 v[188:191], v128 offset:3072
	v_add_u32_e32 v128, s75, v151
	ds_read_b128 v[196:199], v128
	ds_read_b128 v[200:203], v128 offset:1024
	ds_read_b128 v[204:207], v128 offset:2048
	ds_read_b128 v[208:211], v128 offset:3072
	s_add_u32 s22, s22, 0x40000
	s_addc_u32 s23, s23, 0
	s_mov_b32 m0, s51
	v_lshl_add_u64 v[246:247], s[22:23], 0, v[140:141]
	ds_read_b128 v[212:215], v167 offset:32768
	ds_read_b128 v[216:219], v167 offset:33792
	ds_read_b128 v[220:223], v167 offset:34816
	ds_read_b128 v[224:227], v167 offset:35840
	ds_read_b128 v[228:231], v167 offset:36864
	ds_read_b128 v[232:235], v167 offset:37888
	ds_read_b128 v[236:239], v167 offset:38912
	ds_read_b128 v[240:243], v167 offset:39936
	global_load_lds_dwordx4 v[246:247], off
	v_lshl_add_u64 v[246:247], s[22:23], 0, v[144:145]
	s_mov_b32 m0, s52
	s_nop 0
	global_load_lds_dwordx4 v[246:247], off
	s_waitcnt vmcnt(8)
	s_waitcnt lgkmcnt(0)
	s_barrier
	s_setprio 1
	s_waitcnt lgkmcnt(0)
	v_mfma_f32_16x16x32_bf16 v[124:127], v[156:159], v[212:215], v[124:127]
	v_mfma_f32_16x16x32_bf16 v[120:123], v[184:187], v[212:215], v[120:123]
	v_mfma_f32_16x16x32_bf16 v[116:119], v[156:159], v[220:223], v[116:119]
	v_mfma_f32_16x16x32_bf16 v[112:115], v[184:187], v[220:223], v[112:115]
	v_mfma_f32_16x16x32_bf16 v[92:95], v[156:159], v[228:231], v[92:95]
	v_mfma_f32_16x16x32_bf16 v[88:91], v[184:187], v[228:231], v[88:91]
	v_mfma_f32_16x16x32_bf16 v[76:79], v[156:159], v[236:239], v[76:79]
	v_mfma_f32_16x16x32_bf16 v[72:75], v[184:187], v[236:239], v[72:75]
	v_mfma_f32_16x16x32_bf16 v[124:127], v[160:163], v[216:219], v[124:127]
	v_mfma_f32_16x16x32_bf16 v[120:123], v[188:191], v[216:219], v[120:123]
	v_mfma_f32_16x16x32_bf16 v[116:119], v[160:163], v[224:227], v[116:119]
	v_mfma_f32_16x16x32_bf16 v[112:115], v[188:191], v[224:227], v[112:115]
	v_mfma_f32_16x16x32_bf16 v[92:95], v[160:163], v[232:235], v[92:95]
	v_mfma_f32_16x16x32_bf16 v[88:91], v[188:191], v[232:235], v[88:91]
	v_mfma_f32_16x16x32_bf16 v[76:79], v[160:163], v[240:243], v[76:79]
	v_mfma_f32_16x16x32_bf16 v[72:75], v[188:191], v[240:243], v[72:75]
	v_mfma_f32_16x16x32_bf16 v[108:111], v[196:199], v[212:215], v[108:111]
	v_mfma_f32_16x16x32_bf16 v[104:107], v[204:207], v[212:215], v[104:107]
	v_mfma_f32_16x16x32_bf16 v[100:103], v[196:199], v[220:223], v[100:103]
	v_mfma_f32_16x16x32_bf16 v[96:99], v[204:207], v[220:223], v[96:99]
	v_mfma_f32_16x16x32_bf16 v[84:87], v[196:199], v[228:231], v[84:87]
	v_mfma_f32_16x16x32_bf16 v[80:83], v[204:207], v[228:231], v[80:83]
	v_mfma_f32_16x16x32_bf16 v[68:71], v[196:199], v[236:239], v[68:71]
	v_mfma_f32_16x16x32_bf16 v[64:67], v[204:207], v[236:239], v[64:67]
	v_mfma_f32_16x16x32_bf16 v[108:111], v[200:203], v[216:219], v[108:111]
	v_mfma_f32_16x16x32_bf16 v[104:107], v[208:211], v[216:219], v[104:107]
	v_mfma_f32_16x16x32_bf16 v[100:103], v[200:203], v[224:227], v[100:103]
	v_mfma_f32_16x16x32_bf16 v[96:99], v[208:211], v[224:227], v[96:99]
	v_mfma_f32_16x16x32_bf16 v[84:87], v[200:203], v[232:235], v[84:87]
	v_mfma_f32_16x16x32_bf16 v[80:83], v[208:211], v[232:235], v[80:83]
	v_mfma_f32_16x16x32_bf16 v[68:71], v[200:203], v[240:243], v[68:71]
	v_mfma_f32_16x16x32_bf16 v[64:67], v[208:211], v[240:243], v[64:67]
	s_setprio 0
	s_barrier
	s_add_i32 s22, s74, s46
	v_lshl_add_u64 v[138:139], v[138:139], 0, s[24:25]
	s_mov_b32 m0, s22
	ds_read_b128 v[212:215], v167 offset:49152
	ds_read_b128 v[216:219], v167 offset:50176
	ds_read_b128 v[220:223], v167 offset:51200
	ds_read_b128 v[224:227], v167 offset:52224
	ds_read_b128 v[228:231], v167 offset:53248
	ds_read_b128 v[232:235], v167 offset:54272
	ds_read_b128 v[236:239], v167 offset:55296
	ds_read_b128 v[240:243], v167 offset:56320
	global_load_lds_dwordx4 v[138:139], off
	s_add_i32 m0, s22, 0x2000
	s_add_u32 s2, s2, 0x40080
	v_lshl_add_u64 v[138:139], v[164:165], 0, s[24:25]
	s_addc_u32 s3, s3, 0
	s_add_i32 s22, s75, s46
	global_load_lds_dwordx4 v[138:139], off
	v_lshl_add_u64 v[138:139], s[2:3], 0, v[142:143]
	s_mov_b32 m0, s22
	s_nop 0
	global_load_lds_dwordx4 v[138:139], off
	v_lshl_add_u64 v[138:139], s[2:3], 0, v[146:147]
	s_add_i32 m0, s22, 0x2000
	s_nop 0
	global_load_lds_dwordx4 v[138:139], off
	v_lshl_add_u64 v[138:139], v[192:193], 0, s[24:25]
	s_mov_b32 m0, s54
	s_nop 0
	global_load_lds_dwordx4 v[138:139], off
	v_lshl_add_u64 v[138:139], v[244:245], 0, s[24:25]
	s_mov_b32 m0, s55
	s_nop 0
	global_load_lds_dwordx4 v[138:139], off
	s_waitcnt vmcnt(8)
	s_waitcnt lgkmcnt(0)
	s_barrier
	s_setprio 1
	s_waitcnt lgkmcnt(0)
	v_mfma_f32_16x16x32_bf16 v[60:63], v[156:159], v[212:215], v[60:63]
	v_mfma_f32_16x16x32_bf16 v[56:59], v[184:187], v[212:215], v[56:59]
	v_mfma_f32_16x16x32_bf16 v[44:47], v[156:159], v[220:223], v[44:47]
	v_mfma_f32_16x16x32_bf16 v[40:43], v[184:187], v[220:223], v[40:43]
	v_mfma_f32_16x16x32_bf16 v[28:31], v[156:159], v[228:231], v[28:31]
	v_mfma_f32_16x16x32_bf16 v[24:27], v[184:187], v[228:231], v[24:27]
	v_mfma_f32_16x16x32_bf16 v[12:15], v[156:159], v[236:239], v[12:15]
	v_mfma_f32_16x16x32_bf16 v[8:11], v[184:187], v[236:239], v[8:11]
	v_mfma_f32_16x16x32_bf16 v[60:63], v[160:163], v[216:219], v[60:63]
	v_mfma_f32_16x16x32_bf16 v[56:59], v[188:191], v[216:219], v[56:59]
	v_mfma_f32_16x16x32_bf16 v[44:47], v[160:163], v[224:227], v[44:47]
	v_mfma_f32_16x16x32_bf16 v[40:43], v[188:191], v[224:227], v[40:43]
	v_mfma_f32_16x16x32_bf16 v[28:31], v[160:163], v[232:235], v[28:31]
	v_mfma_f32_16x16x32_bf16 v[24:27], v[188:191], v[232:235], v[24:27]
	v_mfma_f32_16x16x32_bf16 v[12:15], v[160:163], v[240:243], v[12:15]
	v_mfma_f32_16x16x32_bf16 v[8:11], v[188:191], v[240:243], v[8:11]
	v_mfma_f32_16x16x32_bf16 v[52:55], v[196:199], v[212:215], v[52:55]
	v_mfma_f32_16x16x32_bf16 v[48:51], v[204:207], v[212:215], v[48:51]
	v_mfma_f32_16x16x32_bf16 v[36:39], v[196:199], v[220:223], v[36:39]
	v_mfma_f32_16x16x32_bf16 v[32:35], v[204:207], v[220:223], v[32:35]
	v_mfma_f32_16x16x32_bf16 v[20:23], v[196:199], v[228:231], v[20:23]
	v_mfma_f32_16x16x32_bf16 v[16:19], v[204:207], v[228:231], v[16:19]
	v_mfma_f32_16x16x32_bf16 v[4:7], v[196:199], v[236:239], v[4:7]
	v_mfma_f32_16x16x32_bf16 v[0:3], v[204:207], v[236:239], v[0:3]
	v_mfma_f32_16x16x32_bf16 v[52:55], v[200:203], v[216:219], v[52:55]
	v_mfma_f32_16x16x32_bf16 v[48:51], v[208:211], v[216:219], v[48:51]
	v_mfma_f32_16x16x32_bf16 v[36:39], v[200:203], v[224:227], v[36:39]
	v_mfma_f32_16x16x32_bf16 v[32:35], v[208:211], v[224:227], v[32:35]
	v_mfma_f32_16x16x32_bf16 v[20:23], v[200:203], v[232:235], v[20:23]
	v_mfma_f32_16x16x32_bf16 v[16:19], v[208:211], v[232:235], v[16:19]
	v_mfma_f32_16x16x32_bf16 v[4:7], v[200:203], v[240:243], v[4:7]
	v_mfma_f32_16x16x32_bf16 v[0:3], v[208:211], v[240:243], v[0:3]
	s_setprio 0
	s_barrier
	s_add_i32 s73, s73, 2
	s_add_u32 s14, s14, 0x100
	s_addc_u32 s15, s15, 0
	s_add_u32 s71, s71, 0x100
	s_addc_u32 s72, s72, 0
	s_cmp_gt_u32 s73, 13
	s_cbranch_scc1 .Lgemm_kdone_3
.LBB0_552:
	ds_read_b128 v[156:159], v155
	ds_read_b128 v[160:163], v155 offset:1024
	ds_read_b128 v[184:187], v155 offset:2048
	ds_read_b128 v[188:191], v155 offset:3072
	ds_read_b128 v[196:199], v166
	ds_read_b128 v[200:203], v166 offset:1024
	ds_read_b128 v[204:207], v166 offset:2048
	ds_read_b128 v[208:211], v166 offset:3072
	s_add_u32 s2, s14, 0xfffc0080
	s_addc_u32 s3, s15, -1
	s_cmp_eq_u32 s73, 12
	s_cselect_b32 s23, s41, s3
	s_cselect_b32 s22, s69, s2
	s_cselect_b32 s3, s39, s72
	s_cselect_b32 s2, s70, s71
	v_lshl_add_u64 v[138:139], s[14:15], 0, v[130:131]
	s_add_i32 m0, s49, 0xc000
	ds_read_b128 v[212:215], v167
	ds_read_b128 v[216:219], v167 offset:1024
	ds_read_b128 v[220:223], v167 offset:2048
	ds_read_b128 v[224:227], v167 offset:3072
	ds_read_b128 v[228:231], v167 offset:4096
	ds_read_b128 v[232:235], v167 offset:5120
	ds_read_b128 v[236:239], v167 offset:6144
	ds_read_b128 v[240:243], v167 offset:7168
	global_load_lds_dwordx4 v[138:139], off
	v_lshl_add_u64 v[138:139], s[14:15], 0, v[132:133]
	s_add_i32 m0, s49, 0xe000
	s_nop 0
	global_load_lds_dwordx4 v[138:139], off
	s_waitcnt vmcnt(8)
	s_waitcnt lgkmcnt(0)
	s_barrier
	s_setprio 1
	s_waitcnt lgkmcnt(0)
	v_mfma_f32_16x16x32_bf16 v[124:127], v[156:159], v[212:215], v[124:127]
	v_mfma_f32_16x16x32_bf16 v[120:123], v[184:187], v[212:215], v[120:123]
	v_mfma_f32_16x16x32_bf16 v[116:119], v[156:159], v[220:223], v[116:119]
	v_mfma_f32_16x16x32_bf16 v[112:115], v[184:187], v[220:223], v[112:115]
	v_mfma_f32_16x16x32_bf16 v[92:95], v[156:159], v[228:231], v[92:95]
	v_mfma_f32_16x16x32_bf16 v[88:91], v[184:187], v[228:231], v[88:91]
	v_mfma_f32_16x16x32_bf16 v[76:79], v[156:159], v[236:239], v[76:79]
	v_mfma_f32_16x16x32_bf16 v[72:75], v[184:187], v[236:239], v[72:75]
	v_mfma_f32_16x16x32_bf16 v[124:127], v[160:163], v[216:219], v[124:127]
	v_mfma_f32_16x16x32_bf16 v[120:123], v[188:191], v[216:219], v[120:123]
	v_mfma_f32_16x16x32_bf16 v[116:119], v[160:163], v[224:227], v[116:119]
	v_mfma_f32_16x16x32_bf16 v[112:115], v[188:191], v[224:227], v[112:115]
	v_mfma_f32_16x16x32_bf16 v[92:95], v[160:163], v[232:235], v[92:95]
	v_mfma_f32_16x16x32_bf16 v[88:91], v[188:191], v[232:235], v[88:91]
	v_mfma_f32_16x16x32_bf16 v[76:79], v[160:163], v[240:243], v[76:79]
	v_mfma_f32_16x16x32_bf16 v[72:75], v[188:191], v[240:243], v[72:75]
	v_mfma_f32_16x16x32_bf16 v[108:111], v[196:199], v[212:215], v[108:111]
	v_mfma_f32_16x16x32_bf16 v[104:107], v[204:207], v[212:215], v[104:107]
	v_mfma_f32_16x16x32_bf16 v[100:103], v[196:199], v[220:223], v[100:103]
	v_mfma_f32_16x16x32_bf16 v[96:99], v[204:207], v[220:223], v[96:99]
	v_mfma_f32_16x16x32_bf16 v[84:87], v[196:199], v[228:231], v[84:87]
	v_mfma_f32_16x16x32_bf16 v[80:83], v[204:207], v[228:231], v[80:83]
	v_mfma_f32_16x16x32_bf16 v[68:71], v[196:199], v[236:239], v[68:71]
	v_mfma_f32_16x16x32_bf16 v[64:67], v[204:207], v[236:239], v[64:67]
	v_mfma_f32_16x16x32_bf16 v[108:111], v[200:203], v[216:219], v[108:111]
	v_mfma_f32_16x16x32_bf16 v[104:107], v[208:211], v[216:219], v[104:107]
	v_mfma_f32_16x16x32_bf16 v[100:103], v[200:203], v[224:227], v[100:103]
	v_mfma_f32_16x16x32_bf16 v[96:99], v[208:211], v[224:227], v[96:99]
	v_mfma_f32_16x16x32_bf16 v[84:87], v[200:203], v[232:235], v[84:87]
	v_mfma_f32_16x16x32_bf16 v[80:83], v[208:211], v[232:235], v[80:83]
	v_mfma_f32_16x16x32_bf16 v[68:71], v[200:203], v[240:243], v[68:71]
	v_mfma_f32_16x16x32_bf16 v[64:67], v[208:211], v[240:243], v[64:67]
	s_setprio 0
	s_barrier
	s_add_i32 s74, s58, s46
	v_lshl_add_u64 v[138:139], s[2:3], 0, v[142:143]
	s_mov_b32 m0, s74
	ds_read_b128 v[212:215], v167 offset:16384
	ds_read_b128 v[216:219], v167 offset:17408
	ds_read_b128 v[220:223], v167 offset:18432
	ds_read_b128 v[224:227], v167 offset:19456
	ds_read_b128 v[228:231], v167 offset:20480
	ds_read_b128 v[232:235], v167 offset:21504
	ds_read_b128 v[236:239], v167 offset:22528
	ds_read_b128 v[240:243], v167 offset:23552
	global_load_lds_dwordx4 v[138:139], off
	s_add_i32 m0, s74, 0x2000
	s_add_u32 s74, s2, 0x40000
	v_lshl_add_u64 v[164:165], s[2:3], 0, v[146:147]
	s_addc_u32 s75, s3, 0
	s_add_i32 s76, s59, s46
	global_load_lds_dwordx4 v[164:165], off
	v_lshl_add_u64 v[192:193], s[74:75], 0, v[142:143]
	s_mov_b32 m0, s76
	v_lshl_add_u64 v[244:245], s[22:23], 0, v[144:145]
	global_load_lds_dwordx4 v[192:193], off
	v_lshl_add_u64 v[192:193], s[74:75], 0, v[146:147]
	s_add_i32 m0, s76, 0x2000
	s_nop 0
	global_load_lds_dwordx4 v[192:193], off
	v_lshl_add_u64 v[192:193], s[22:23], 0, v[140:141]
	s_mov_b32 m0, s49
	s_nop 0
	global_load_lds_dwordx4 v[192:193], off
	s_mov_b32 m0, s50
	s_nop 0
	global_load_lds_dwordx4 v[244:245], off
	s_waitcnt vmcnt(8)
	s_waitcnt lgkmcnt(0)
	s_barrier
	s_setprio 1
	s_waitcnt lgkmcnt(0)
	v_mfma_f32_16x16x32_bf16 v[60:63], v[156:159], v[212:215], v[60:63]
	v_mfma_f32_16x16x32_bf16 v[56:59], v[184:187], v[212:215], v[56:59]
	v_mfma_f32_16x16x32_bf16 v[44:47], v[156:159], v[220:223], v[44:47]
	v_mfma_f32_16x16x32_bf16 v[40:43], v[184:187], v[220:223], v[40:43]
	v_mfma_f32_16x16x32_bf16 v[28:31], v[156:159], v[228:231], v[28:31]
	v_mfma_f32_16x16x32_bf16 v[24:27], v[184:187], v[228:231], v[24:27]
	v_mfma_f32_16x16x32_bf16 v[12:15], v[156:159], v[236:239], v[12:15]
	v_mfma_f32_16x16x32_bf16 v[8:11], v[184:187], v[236:239], v[8:11]
	v_mfma_f32_16x16x32_bf16 v[60:63], v[160:163], v[216:219], v[60:63]
	v_mfma_f32_16x16x32_bf16 v[56:59], v[188:191], v[216:219], v[56:59]
	v_mfma_f32_16x16x32_bf16 v[44:47], v[160:163], v[224:227], v[44:47]
	v_mfma_f32_16x16x32_bf16 v[40:43], v[188:191], v[224:227], v[40:43]
	v_mfma_f32_16x16x32_bf16 v[28:31], v[160:163], v[232:235], v[28:31]
	v_mfma_f32_16x16x32_bf16 v[24:27], v[188:191], v[232:235], v[24:27]
	v_mfma_f32_16x16x32_bf16 v[12:15], v[160:163], v[240:243], v[12:15]
	v_mfma_f32_16x16x32_bf16 v[8:11], v[188:191], v[240:243], v[8:11]
	v_mfma_f32_16x16x32_bf16 v[52:55], v[196:199], v[212:215], v[52:55]
	v_mfma_f32_16x16x32_bf16 v[48:51], v[204:207], v[212:215], v[48:51]
	v_mfma_f32_16x16x32_bf16 v[36:39], v[196:199], v[220:223], v[36:39]
	v_mfma_f32_16x16x32_bf16 v[32:35], v[204:207], v[220:223], v[32:35]
	v_mfma_f32_16x16x32_bf16 v[20:23], v[196:199], v[228:231], v[20:23]
	v_mfma_f32_16x16x32_bf16 v[16:19], v[204:207], v[228:231], v[16:19]
	v_mfma_f32_16x16x32_bf16 v[4:7], v[196:199], v[236:239], v[4:7]
	v_mfma_f32_16x16x32_bf16 v[0:3], v[204:207], v[236:239], v[0:3]
	v_mfma_f32_16x16x32_bf16 v[52:55], v[200:203], v[216:219], v[52:55]
	v_mfma_f32_16x16x32_bf16 v[48:51], v[208:211], v[216:219], v[48:51]
	v_mfma_f32_16x16x32_bf16 v[36:39], v[200:203], v[224:227], v[36:39]
	v_mfma_f32_16x16x32_bf16 v[32:35], v[208:211], v[224:227], v[32:35]
	v_mfma_f32_16x16x32_bf16 v[20:23], v[200:203], v[232:235], v[20:23]
	v_mfma_f32_16x16x32_bf16 v[16:19], v[208:211], v[232:235], v[16:19]
	v_mfma_f32_16x16x32_bf16 v[4:7], v[200:203], v[240:243], v[4:7]
	v_mfma_f32_16x16x32_bf16 v[0:3], v[208:211], v[240:243], v[0:3]
	s_setprio 0
	s_barrier
	s_add_i32 s74, 0, 0x18000
	v_add_u32_e32 v128, s74, v151
	s_add_i32 s75, 0, 0x1c000
	ds_read_b128 v[156:159], v128
	ds_read_b128 v[160:163], v128 offset:1024
	ds_read_b128 v[184:187], v128 offset:2048
	ds_read_b128 v[188:191], v128 offset:3072
	v_add_u32_e32 v128, s75, v151
	ds_read_b128 v[196:199], v128
	ds_read_b128 v[200:203], v128 offset:1024
	ds_read_b128 v[204:207], v128 offset:2048
	ds_read_b128 v[208:211], v128 offset:3072
	s_add_u32 s22, s22, 0x40000
	s_addc_u32 s23, s23, 0
	s_mov_b32 m0, s51
	v_lshl_add_u64 v[246:247], s[22:23], 0, v[140:141]
	ds_read_b128 v[212:215], v167 offset:32768
	ds_read_b128 v[216:219], v167 offset:33792
	ds_read_b128 v[220:223], v167 offset:34816
	ds_read_b128 v[224:227], v167 offset:35840
	ds_read_b128 v[228:231], v167 offset:36864
	ds_read_b128 v[232:235], v167 offset:37888
	ds_read_b128 v[236:239], v167 offset:38912
	ds_read_b128 v[240:243], v167 offset:39936
	global_load_lds_dwordx4 v[246:247], off
	v_lshl_add_u64 v[246:247], s[22:23], 0, v[144:145]
	s_mov_b32 m0, s52
	s_nop 0
	global_load_lds_dwordx4 v[246:247], off
	s_waitcnt vmcnt(8)
	s_waitcnt lgkmcnt(0)
	s_barrier
	s_setprio 1
	s_waitcnt lgkmcnt(0)
	v_mfma_f32_16x16x32_bf16 v[124:127], v[156:159], v[212:215], v[124:127]
	v_mfma_f32_16x16x32_bf16 v[120:123], v[184:187], v[212:215], v[120:123]
	v_mfma_f32_16x16x32_bf16 v[116:119], v[156:159], v[220:223], v[116:119]
	v_mfma_f32_16x16x32_bf16 v[112:115], v[184:187], v[220:223], v[112:115]
	v_mfma_f32_16x16x32_bf16 v[92:95], v[156:159], v[228:231], v[92:95]
	v_mfma_f32_16x16x32_bf16 v[88:91], v[184:187], v[228:231], v[88:91]
	v_mfma_f32_16x16x32_bf16 v[76:79], v[156:159], v[236:239], v[76:79]
	v_mfma_f32_16x16x32_bf16 v[72:75], v[184:187], v[236:239], v[72:75]
	v_mfma_f32_16x16x32_bf16 v[124:127], v[160:163], v[216:219], v[124:127]
	v_mfma_f32_16x16x32_bf16 v[120:123], v[188:191], v[216:219], v[120:123]
	v_mfma_f32_16x16x32_bf16 v[116:119], v[160:163], v[224:227], v[116:119]
	v_mfma_f32_16x16x32_bf16 v[112:115], v[188:191], v[224:227], v[112:115]
	v_mfma_f32_16x16x32_bf16 v[92:95], v[160:163], v[232:235], v[92:95]
	v_mfma_f32_16x16x32_bf16 v[88:91], v[188:191], v[232:235], v[88:91]
	v_mfma_f32_16x16x32_bf16 v[76:79], v[160:163], v[240:243], v[76:79]
	v_mfma_f32_16x16x32_bf16 v[72:75], v[188:191], v[240:243], v[72:75]
	v_mfma_f32_16x16x32_bf16 v[108:111], v[196:199], v[212:215], v[108:111]
	v_mfma_f32_16x16x32_bf16 v[104:107], v[204:207], v[212:215], v[104:107]
	v_mfma_f32_16x16x32_bf16 v[100:103], v[196:199], v[220:223], v[100:103]
	v_mfma_f32_16x16x32_bf16 v[96:99], v[204:207], v[220:223], v[96:99]
	v_mfma_f32_16x16x32_bf16 v[84:87], v[196:199], v[228:231], v[84:87]
	v_mfma_f32_16x16x32_bf16 v[80:83], v[204:207], v[228:231], v[80:83]
	v_mfma_f32_16x16x32_bf16 v[68:71], v[196:199], v[236:239], v[68:71]
	v_mfma_f32_16x16x32_bf16 v[64:67], v[204:207], v[236:239], v[64:67]
	v_mfma_f32_16x16x32_bf16 v[108:111], v[200:203], v[216:219], v[108:111]
	v_mfma_f32_16x16x32_bf16 v[104:107], v[208:211], v[216:219], v[104:107]
	v_mfma_f32_16x16x32_bf16 v[100:103], v[200:203], v[224:227], v[100:103]
	v_mfma_f32_16x16x32_bf16 v[96:99], v[208:211], v[224:227], v[96:99]
	v_mfma_f32_16x16x32_bf16 v[84:87], v[200:203], v[232:235], v[84:87]
	v_mfma_f32_16x16x32_bf16 v[80:83], v[208:211], v[232:235], v[80:83]
	v_mfma_f32_16x16x32_bf16 v[68:71], v[200:203], v[240:243], v[68:71]
	v_mfma_f32_16x16x32_bf16 v[64:67], v[208:211], v[240:243], v[64:67]
	s_setprio 0
	s_barrier
	s_add_i32 s22, s74, s46
	v_lshl_add_u64 v[138:139], v[138:139], 0, s[24:25]
	s_mov_b32 m0, s22
	ds_read_b128 v[212:215], v167 offset:49152
	ds_read_b128 v[216:219], v167 offset:50176
	ds_read_b128 v[220:223], v167 offset:51200
	ds_read_b128 v[224:227], v167 offset:52224
	ds_read_b128 v[228:231], v167 offset:53248
	ds_read_b128 v[232:235], v167 offset:54272
	ds_read_b128 v[236:239], v167 offset:55296
	ds_read_b128 v[240:243], v167 offset:56320
	global_load_lds_dwordx4 v[138:139], off
	s_add_i32 m0, s22, 0x2000
	s_add_u32 s2, s2, 0x40080
	v_lshl_add_u64 v[138:139], v[164:165], 0, s[24:25]
	s_addc_u32 s3, s3, 0
	s_add_i32 s22, s75, s46
	global_load_lds_dwordx4 v[138:139], off
	v_lshl_add_u64 v[138:139], s[2:3], 0, v[142:143]
	s_mov_b32 m0, s22
	s_nop 0
	global_load_lds_dwordx4 v[138:139], off
	v_lshl_add_u64 v[138:139], s[2:3], 0, v[146:147]
	s_add_i32 m0, s22, 0x2000
	s_nop 0
	global_load_lds_dwordx4 v[138:139], off
	v_lshl_add_u64 v[138:139], v[192:193], 0, s[24:25]
	s_mov_b32 m0, s54
	s_nop 0
	global_load_lds_dwordx4 v[138:139], off
	v_lshl_add_u64 v[138:139], v[244:245], 0, s[24:25]
	s_mov_b32 m0, s55
	s_nop 0
	global_load_lds_dwordx4 v[138:139], off
	s_waitcnt vmcnt(8)
	s_waitcnt lgkmcnt(0)
	s_barrier
	s_setprio 1
	s_waitcnt lgkmcnt(0)
	v_mfma_f32_16x16x32_bf16 v[60:63], v[156:159], v[212:215], v[60:63]
	v_mfma_f32_16x16x32_bf16 v[56:59], v[184:187], v[212:215], v[56:59]
	v_mfma_f32_16x16x32_bf16 v[44:47], v[156:159], v[220:223], v[44:47]
	v_mfma_f32_16x16x32_bf16 v[40:43], v[184:187], v[220:223], v[40:43]
	v_mfma_f32_16x16x32_bf16 v[28:31], v[156:159], v[228:231], v[28:31]
	v_mfma_f32_16x16x32_bf16 v[24:27], v[184:187], v[228:231], v[24:27]
	v_mfma_f32_16x16x32_bf16 v[12:15], v[156:159], v[236:239], v[12:15]
	v_mfma_f32_16x16x32_bf16 v[8:11], v[184:187], v[236:239], v[8:11]
	v_mfma_f32_16x16x32_bf16 v[60:63], v[160:163], v[216:219], v[60:63]
	v_mfma_f32_16x16x32_bf16 v[56:59], v[188:191], v[216:219], v[56:59]
	v_mfma_f32_16x16x32_bf16 v[44:47], v[160:163], v[224:227], v[44:47]
	v_mfma_f32_16x16x32_bf16 v[40:43], v[188:191], v[224:227], v[40:43]
	v_mfma_f32_16x16x32_bf16 v[28:31], v[160:163], v[232:235], v[28:31]
	v_mfma_f32_16x16x32_bf16 v[24:27], v[188:191], v[232:235], v[24:27]
	v_mfma_f32_16x16x32_bf16 v[12:15], v[160:163], v[240:243], v[12:15]
	v_mfma_f32_16x16x32_bf16 v[8:11], v[188:191], v[240:243], v[8:11]
	v_mfma_f32_16x16x32_bf16 v[52:55], v[196:199], v[212:215], v[52:55]
	v_mfma_f32_16x16x32_bf16 v[48:51], v[204:207], v[212:215], v[48:51]
	v_mfma_f32_16x16x32_bf16 v[36:39], v[196:199], v[220:223], v[36:39]
	v_mfma_f32_16x16x32_bf16 v[32:35], v[204:207], v[220:223], v[32:35]
	v_mfma_f32_16x16x32_bf16 v[20:23], v[196:199], v[228:231], v[20:23]
	v_mfma_f32_16x16x32_bf16 v[16:19], v[204:207], v[228:231], v[16:19]
	v_mfma_f32_16x16x32_bf16 v[4:7], v[196:199], v[236:239], v[4:7]
	v_mfma_f32_16x16x32_bf16 v[0:3], v[204:207], v[236:239], v[0:3]
	v_mfma_f32_16x16x32_bf16 v[52:55], v[200:203], v[216:219], v[52:55]
	v_mfma_f32_16x16x32_bf16 v[48:51], v[208:211], v[216:219], v[48:51]
	v_mfma_f32_16x16x32_bf16 v[36:39], v[200:203], v[224:227], v[36:39]
	v_mfma_f32_16x16x32_bf16 v[32:35], v[208:211], v[224:227], v[32:35]
	v_mfma_f32_16x16x32_bf16 v[20:23], v[200:203], v[232:235], v[20:23]
	v_mfma_f32_16x16x32_bf16 v[16:19], v[208:211], v[232:235], v[16:19]
	v_mfma_f32_16x16x32_bf16 v[4:7], v[200:203], v[240:243], v[4:7]
	v_mfma_f32_16x16x32_bf16 v[0:3], v[208:211], v[240:243], v[0:3]
	s_setprio 0
	s_barrier
	s_add_i32 s73, s73, 2
	s_add_u32 s14, s14, 0x100
	s_addc_u32 s15, s15, 0
	s_add_u32 s71, s71, 0x100
	s_addc_u32 s72, s72, 0
	s_cmp_gt_u32 s73, 13
	s_cbranch_scc0 .LBB0_552

.LBB0_724:
	s_ashr_i32 s27, s26, 31
	s_lshl_b64 s[22:23], s[26:27], 19
	s_add_u32 s28, s16, s22
	s_addc_u32 s29, s17, s23
	s_and_b64 s[22:23], s[6:7], exec
	s_cselect_b32 s27, s29, s15
	s_cselect_b32 s59, s28, s14
	s_ashr_i32 s25, s24, 31
	s_lshl_b64 s[22:23], s[24:25], 19
	s_add_u32 s30, s35, s22
	s_addc_u32 s31, s38, s23
	s_and_b64 s[22:23], s[6:7], exec
	s_cselect_b32 s25, s31, s3
	s_cselect_b32 s64, s30, s2
	s_add_u32 s14, s14, 0x40080
	s_addc_u32 s15, s15, 0
	s_add_u32 s65, s2, 0x100
	s_addc_u32 s66, s3, 0
	s_mov_b32 s67, -2
	s_waitcnt lgkmcnt(0)
	s_waitcnt vmcnt(0)
	ds_read_b128 v[128:131], v155
	ds_read_b128 v[132:135], v155 offset:1024
	ds_read_b128 v[136:139], v155 offset:2048
	ds_read_b128 v[164:167], v155 offset:3072
	ds_read_b128 v[188:191], v184
	ds_read_b128 v[196:199], v184 offset:1024
	ds_read_b128 v[200:203], v184 offset:2048
	ds_read_b128 v[204:207], v184 offset:3072
	s_add_u32 s2, s14, 0xfffc0080
	s_addc_u32 s3, s15, -1
	s_cmp_eq_u32 s67, 12
	s_cselect_b32 s23, s27, s3
	s_cselect_b32 s22, s59, s2
	s_cselect_b32 s3, s25, s66
	s_cselect_b32 s2, s64, s65
	v_lshl_add_u64 v[168:169], s[14:15], 0, v[156:157]
	s_add_i32 m0, s37, 0xc000
	ds_read_b128 v[208:211], v185
	ds_read_b128 v[212:215], v185 offset:1024
	ds_read_b128 v[216:219], v185 offset:2048
	ds_read_b128 v[220:223], v185 offset:3072
	ds_read_b128 v[224:227], v185 offset:4096
	ds_read_b128 v[228:231], v185 offset:5120
	ds_read_b128 v[232:235], v185 offset:6144
	ds_read_b128 v[236:239], v185 offset:7168
	global_load_lds_dwordx4 v[168:169], off
	v_lshl_add_u64 v[168:169], s[14:15], 0, v[158:159]
	s_add_i32 m0, s37, 0xe000
	s_nop 0
	global_load_lds_dwordx4 v[168:169], off
	s_waitcnt vmcnt(8)
	s_waitcnt lgkmcnt(0)
	s_barrier
	s_setprio 1
	s_waitcnt lgkmcnt(0)
	v_mfma_f32_16x16x32_bf16 v[124:127], v[128:131], v[208:211], 0
	v_mfma_f32_16x16x32_bf16 v[120:123], v[136:139], v[208:211], 0
	v_mfma_f32_16x16x32_bf16 v[108:111], v[128:131], v[216:219], 0
	v_mfma_f32_16x16x32_bf16 v[104:107], v[136:139], v[216:219], 0
	v_mfma_f32_16x16x32_bf16 v[92:95], v[128:131], v[224:227], 0
	v_mfma_f32_16x16x32_bf16 v[88:91], v[136:139], v[224:227], 0
	v_mfma_f32_16x16x32_bf16 v[76:79], v[128:131], v[232:235], 0
	v_mfma_f32_16x16x32_bf16 v[72:75], v[136:139], v[232:235], 0
	v_mfma_f32_16x16x32_bf16 v[124:127], v[132:135], v[212:215], v[124:127]
	v_mfma_f32_16x16x32_bf16 v[120:123], v[164:167], v[212:215], v[120:123]
	v_mfma_f32_16x16x32_bf16 v[108:111], v[132:135], v[220:223], v[108:111]
	v_mfma_f32_16x16x32_bf16 v[104:107], v[164:167], v[220:223], v[104:107]
	v_mfma_f32_16x16x32_bf16 v[92:95], v[132:135], v[228:231], v[92:95]
	v_mfma_f32_16x16x32_bf16 v[88:91], v[164:167], v[228:231], v[88:91]
	v_mfma_f32_16x16x32_bf16 v[76:79], v[132:135], v[236:239], v[76:79]
	v_mfma_f32_16x16x32_bf16 v[72:75], v[164:167], v[236:239], v[72:75]
	v_mfma_f32_16x16x32_bf16 v[116:119], v[188:191], v[208:211], 0
	v_mfma_f32_16x16x32_bf16 v[112:115], v[200:203], v[208:211], 0
	v_mfma_f32_16x16x32_bf16 v[100:103], v[188:191], v[216:219], 0
	v_mfma_f32_16x16x32_bf16 v[96:99], v[200:203], v[216:219], 0
	v_mfma_f32_16x16x32_bf16 v[84:87], v[188:191], v[224:227], 0
	v_mfma_f32_16x16x32_bf16 v[80:83], v[200:203], v[224:227], 0
	v_mfma_f32_16x16x32_bf16 v[68:71], v[188:191], v[232:235], 0
	v_mfma_f32_16x16x32_bf16 v[64:67], v[200:203], v[232:235], 0
	v_mfma_f32_16x16x32_bf16 v[116:119], v[196:199], v[212:215], v[116:119]
	v_mfma_f32_16x16x32_bf16 v[112:115], v[204:207], v[212:215], v[112:115]
	v_mfma_f32_16x16x32_bf16 v[100:103], v[196:199], v[220:223], v[100:103]
	v_mfma_f32_16x16x32_bf16 v[96:99], v[204:207], v[220:223], v[96:99]
	v_mfma_f32_16x16x32_bf16 v[84:87], v[196:199], v[228:231], v[84:87]
	v_mfma_f32_16x16x32_bf16 v[80:83], v[204:207], v[228:231], v[80:83]
	v_mfma_f32_16x16x32_bf16 v[68:71], v[196:199], v[236:239], v[68:71]
	v_mfma_f32_16x16x32_bf16 v[64:67], v[204:207], v[236:239], v[64:67]
	s_setprio 0
	s_barrier
	s_add_i32 s68, s52, s39
	v_lshl_add_u64 v[168:169], s[2:3], 0, v[142:143]
	s_mov_b32 m0, s68
	ds_read_b128 v[208:211], v185 offset:16384
	ds_read_b128 v[212:215], v185 offset:17408
	ds_read_b128 v[216:219], v185 offset:18432
	ds_read_b128 v[220:223], v185 offset:19456
	ds_read_b128 v[224:227], v185 offset:20480
	ds_read_b128 v[228:231], v185 offset:21504
	ds_read_b128 v[232:235], v185 offset:22528
	ds_read_b128 v[236:239], v185 offset:23552
	global_load_lds_dwordx4 v[168:169], off
	s_add_i32 m0, s68, 0x2000
	s_add_u32 s68, s2, 0x40000
	v_lshl_add_u64 v[192:193], s[2:3], 0, v[146:147]
	s_addc_u32 s69, s3, 0
	s_add_i32 s70, s53, s39
	global_load_lds_dwordx4 v[192:193], off
	v_lshl_add_u64 v[240:241], s[68:69], 0, v[142:143]
	s_mov_b32 m0, s70
	v_lshl_add_u64 v[242:243], s[22:23], 0, v[144:145]
	global_load_lds_dwordx4 v[240:241], off
	v_lshl_add_u64 v[240:241], s[68:69], 0, v[146:147]
	s_add_i32 m0, s70, 0x2000
	s_nop 0
	global_load_lds_dwordx4 v[240:241], off
	v_lshl_add_u64 v[240:241], s[22:23], 0, v[140:141]
	s_mov_b32 m0, s37
	s_nop 0
	global_load_lds_dwordx4 v[240:241], off
	s_mov_b32 m0, s40
	s_nop 0
	global_load_lds_dwordx4 v[242:243], off
	s_waitcnt vmcnt(8)
	s_waitcnt lgkmcnt(0)
	s_barrier
	s_setprio 1
	s_waitcnt lgkmcnt(0)
	v_mfma_f32_16x16x32_bf16 v[60:63], v[128:131], v[208:211], 0
	v_mfma_f32_16x16x32_bf16 v[56:59], v[136:139], v[208:211], 0
	v_mfma_f32_16x16x32_bf16 v[44:47], v[128:131], v[216:219], 0
	v_mfma_f32_16x16x32_bf16 v[40:43], v[136:139], v[216:219], 0
	v_mfma_f32_16x16x32_bf16 v[28:31], v[128:131], v[224:227], 0
	v_mfma_f32_16x16x32_bf16 v[24:27], v[136:139], v[224:227], 0
	v_mfma_f32_16x16x32_bf16 v[12:15], v[128:131], v[232:235], 0
	v_mfma_f32_16x16x32_bf16 v[8:11], v[136:139], v[232:235], 0
	v_mfma_f32_16x16x32_bf16 v[60:63], v[132:135], v[212:215], v[60:63]
	v_mfma_f32_16x16x32_bf16 v[56:59], v[164:167], v[212:215], v[56:59]
	v_mfma_f32_16x16x32_bf16 v[44:47], v[132:135], v[220:223], v[44:47]
	v_mfma_f32_16x16x32_bf16 v[40:43], v[164:167], v[220:223], v[40:43]
	v_mfma_f32_16x16x32_bf16 v[28:31], v[132:135], v[228:231], v[28:31]
	v_mfma_f32_16x16x32_bf16 v[24:27], v[164:167], v[228:231], v[24:27]
	v_mfma_f32_16x16x32_bf16 v[12:15], v[132:135], v[236:239], v[12:15]
	v_mfma_f32_16x16x32_bf16 v[8:11], v[164:167], v[236:239], v[8:11]
	v_mfma_f32_16x16x32_bf16 v[52:55], v[188:191], v[208:211], 0
	v_mfma_f32_16x16x32_bf16 v[48:51], v[200:203], v[208:211], 0
	v_mfma_f32_16x16x32_bf16 v[36:39], v[188:191], v[216:219], 0
	v_mfma_f32_16x16x32_bf16 v[32:35], v[200:203], v[216:219], 0
	v_mfma_f32_16x16x32_bf16 v[20:23], v[188:191], v[224:227], 0
	v_mfma_f32_16x16x32_bf16 v[16:19], v[200:203], v[224:227], 0
	v_mfma_f32_16x16x32_bf16 v[4:7], v[188:191], v[232:235], 0
	v_mfma_f32_16x16x32_bf16 v[0:3], v[200:203], v[232:235], 0
	v_mfma_f32_16x16x32_bf16 v[52:55], v[196:199], v[212:215], v[52:55]
	v_mfma_f32_16x16x32_bf16 v[48:51], v[204:207], v[212:215], v[48:51]
	v_mfma_f32_16x16x32_bf16 v[36:39], v[196:199], v[220:223], v[36:39]
	v_mfma_f32_16x16x32_bf16 v[32:35], v[204:207], v[220:223], v[32:35]
	v_mfma_f32_16x16x32_bf16 v[20:23], v[196:199], v[228:231], v[20:23]
	v_mfma_f32_16x16x32_bf16 v[16:19], v[204:207], v[228:231], v[16:19]
	v_mfma_f32_16x16x32_bf16 v[4:7], v[196:199], v[236:239], v[4:7]
	v_mfma_f32_16x16x32_bf16 v[0:3], v[204:207], v[236:239], v[0:3]
	s_setprio 0
	s_barrier
	s_add_i32 s68, 0, 0x18000
	s_add_i32 s69, 0, 0x1c000
	v_add_u32_e32 v164, s68, v149
	v_add_u32_e32 v187, s69, v149
	ds_read_b128 v[128:131], v164
	ds_read_b128 v[132:135], v164 offset:1024
	ds_read_b128 v[136:139], v164 offset:2048
	ds_read_b128 v[164:167], v164 offset:3072
	ds_read_b128 v[188:191], v187
	ds_read_b128 v[196:199], v187 offset:1024
	ds_read_b128 v[200:203], v187 offset:2048
	ds_read_b128 v[204:207], v187 offset:3072
	s_add_u32 s22, s22, 0x40000
	s_addc_u32 s23, s23, 0
	s_mov_b32 m0, s41
	v_lshl_add_u64 v[244:245], s[22:23], 0, v[140:141]
	ds_read_b128 v[208:211], v185 offset:32768
	ds_read_b128 v[212:215], v185 offset:33792
	ds_read_b128 v[216:219], v185 offset:34816
	ds_read_b128 v[220:223], v185 offset:35840
	ds_read_b128 v[224:227], v185 offset:36864
	ds_read_b128 v[228:231], v185 offset:37888
	ds_read_b128 v[232:235], v185 offset:38912
	ds_read_b128 v[236:239], v185 offset:39936
	global_load_lds_dwordx4 v[244:245], off
	v_lshl_add_u64 v[244:245], s[22:23], 0, v[144:145]
	s_mov_b32 m0, s42
	s_nop 0
	global_load_lds_dwordx4 v[244:245], off
	s_waitcnt vmcnt(8)
	s_waitcnt lgkmcnt(0)
	s_barrier
	s_setprio 1
	s_waitcnt lgkmcnt(0)
	v_mfma_f32_16x16x32_bf16 v[124:127], v[128:131], v[208:211], v[124:127]
	v_mfma_f32_16x16x32_bf16 v[120:123], v[136:139], v[208:211], v[120:123]
	v_mfma_f32_16x16x32_bf16 v[108:111], v[128:131], v[216:219], v[108:111]
	v_mfma_f32_16x16x32_bf16 v[104:107], v[136:139], v[216:219], v[104:107]
	v_mfma_f32_16x16x32_bf16 v[92:95], v[128:131], v[224:227], v[92:95]
	v_mfma_f32_16x16x32_bf16 v[88:91], v[136:139], v[224:227], v[88:91]
	v_mfma_f32_16x16x32_bf16 v[76:79], v[128:131], v[232:235], v[76:79]
	v_mfma_f32_16x16x32_bf16 v[72:75], v[136:139], v[232:235], v[72:75]
	v_mfma_f32_16x16x32_bf16 v[124:127], v[132:135], v[212:215], v[124:127]
	v_mfma_f32_16x16x32_bf16 v[120:123], v[164:167], v[212:215], v[120:123]
	v_mfma_f32_16x16x32_bf16 v[108:111], v[132:135], v[220:223], v[108:111]
	v_mfma_f32_16x16x32_bf16 v[104:107], v[164:167], v[220:223], v[104:107]
	v_mfma_f32_16x16x32_bf16 v[92:95], v[132:135], v[228:231], v[92:95]
	v_mfma_f32_16x16x32_bf16 v[88:91], v[164:167], v[228:231], v[88:91]
	v_mfma_f32_16x16x32_bf16 v[76:79], v[132:135], v[236:239], v[76:79]
	v_mfma_f32_16x16x32_bf16 v[72:75], v[164:167], v[236:239], v[72:75]
	v_mfma_f32_16x16x32_bf16 v[116:119], v[188:191], v[208:211], v[116:119]
	v_mfma_f32_16x16x32_bf16 v[112:115], v[200:203], v[208:211], v[112:115]
	v_mfma_f32_16x16x32_bf16 v[100:103], v[188:191], v[216:219], v[100:103]
	v_mfma_f32_16x16x32_bf16 v[96:99], v[200:203], v[216:219], v[96:99]
	v_mfma_f32_16x16x32_bf16 v[84:87], v[188:191], v[224:227], v[84:87]
	v_mfma_f32_16x16x32_bf16 v[80:83], v[200:203], v[224:227], v[80:83]
	v_mfma_f32_16x16x32_bf16 v[68:71], v[188:191], v[232:235], v[68:71]
	v_mfma_f32_16x16x32_bf16 v[64:67], v[200:203], v[232:235], v[64:67]
	v_mfma_f32_16x16x32_bf16 v[116:119], v[196:199], v[212:215], v[116:119]
	v_mfma_f32_16x16x32_bf16 v[112:115], v[204:207], v[212:215], v[112:115]
	v_mfma_f32_16x16x32_bf16 v[100:103], v[196:199], v[220:223], v[100:103]
	v_mfma_f32_16x16x32_bf16 v[96:99], v[204:207], v[220:223], v[96:99]
	v_mfma_f32_16x16x32_bf16 v[84:87], v[196:199], v[228:231], v[84:87]
	v_mfma_f32_16x16x32_bf16 v[80:83], v[204:207], v[228:231], v[80:83]
	v_mfma_f32_16x16x32_bf16 v[68:71], v[196:199], v[236:239], v[68:71]
	v_mfma_f32_16x16x32_bf16 v[64:67], v[204:207], v[236:239], v[64:67]
	s_setprio 0
	s_barrier
	s_add_i32 s22, s68, s39
	v_lshl_add_u64 v[168:169], v[168:169], 0, s[18:19]
	s_mov_b32 m0, s22
	ds_read_b128 v[208:211], v185 offset:49152
	ds_read_b128 v[212:215], v185 offset:50176
	ds_read_b128 v[216:219], v185 offset:51200
	ds_read_b128 v[220:223], v185 offset:52224
	ds_read_b128 v[224:227], v185 offset:53248
	ds_read_b128 v[228:231], v185 offset:54272
	ds_read_b128 v[232:235], v185 offset:55296
	ds_read_b128 v[236:239], v185 offset:56320
	global_load_lds_dwordx4 v[168:169], off
	s_add_i32 m0, s22, 0x2000
	s_add_u32 s2, s2, 0x40080
	v_lshl_add_u64 v[168:169], v[192:193], 0, s[18:19]
	s_addc_u32 s3, s3, 0
	s_add_i32 s22, s69, s39
	global_load_lds_dwordx4 v[168:169], off
	v_lshl_add_u64 v[168:169], s[2:3], 0, v[142:143]
	s_mov_b32 m0, s22
	s_nop 0
	global_load_lds_dwordx4 v[168:169], off
	v_lshl_add_u64 v[168:169], s[2:3], 0, v[146:147]
	s_add_i32 m0, s22, 0x2000
	s_nop 0
	global_load_lds_dwordx4 v[168:169], off
	v_lshl_add_u64 v[168:169], v[240:241], 0, s[18:19]
	s_mov_b32 m0, s46
	s_nop 0
	global_load_lds_dwordx4 v[168:169], off
	v_lshl_add_u64 v[168:169], v[242:243], 0, s[18:19]
	s_mov_b32 m0, s47
	s_nop 0
	global_load_lds_dwordx4 v[168:169], off
	s_waitcnt vmcnt(8)
	s_waitcnt lgkmcnt(0)
	s_barrier
	s_setprio 1
	s_waitcnt lgkmcnt(0)
	v_mfma_f32_16x16x32_bf16 v[60:63], v[128:131], v[208:211], v[60:63]
	v_mfma_f32_16x16x32_bf16 v[56:59], v[136:139], v[208:211], v[56:59]
	v_mfma_f32_16x16x32_bf16 v[44:47], v[128:131], v[216:219], v[44:47]
	v_mfma_f32_16x16x32_bf16 v[40:43], v[136:139], v[216:219], v[40:43]
	v_mfma_f32_16x16x32_bf16 v[28:31], v[128:131], v[224:227], v[28:31]
	v_mfma_f32_16x16x32_bf16 v[24:27], v[136:139], v[224:227], v[24:27]
	v_mfma_f32_16x16x32_bf16 v[12:15], v[128:131], v[232:235], v[12:15]
	v_mfma_f32_16x16x32_bf16 v[8:11], v[136:139], v[232:235], v[8:11]
	v_mfma_f32_16x16x32_bf16 v[60:63], v[132:135], v[212:215], v[60:63]
	v_mfma_f32_16x16x32_bf16 v[56:59], v[164:167], v[212:215], v[56:59]
	v_mfma_f32_16x16x32_bf16 v[44:47], v[132:135], v[220:223], v[44:47]
	v_mfma_f32_16x16x32_bf16 v[40:43], v[164:167], v[220:223], v[40:43]
	v_mfma_f32_16x16x32_bf16 v[28:31], v[132:135], v[228:231], v[28:31]
	v_mfma_f32_16x16x32_bf16 v[24:27], v[164:167], v[228:231], v[24:27]
	v_mfma_f32_16x16x32_bf16 v[12:15], v[132:135], v[236:239], v[12:15]
	v_mfma_f32_16x16x32_bf16 v[8:11], v[164:167], v[236:239], v[8:11]
	v_mfma_f32_16x16x32_bf16 v[52:55], v[188:191], v[208:211], v[52:55]
	v_mfma_f32_16x16x32_bf16 v[48:51], v[200:203], v[208:211], v[48:51]
	v_mfma_f32_16x16x32_bf16 v[36:39], v[188:191], v[216:219], v[36:39]
	v_mfma_f32_16x16x32_bf16 v[32:35], v[200:203], v[216:219], v[32:35]
	v_mfma_f32_16x16x32_bf16 v[20:23], v[188:191], v[224:227], v[20:23]
	v_mfma_f32_16x16x32_bf16 v[16:19], v[200:203], v[224:227], v[16:19]
	v_mfma_f32_16x16x32_bf16 v[4:7], v[188:191], v[232:235], v[4:7]
	v_mfma_f32_16x16x32_bf16 v[0:3], v[200:203], v[232:235], v[0:3]
	v_mfma_f32_16x16x32_bf16 v[52:55], v[196:199], v[212:215], v[52:55]
	v_mfma_f32_16x16x32_bf16 v[48:51], v[204:207], v[212:215], v[48:51]
	v_mfma_f32_16x16x32_bf16 v[36:39], v[196:199], v[220:223], v[36:39]
	v_mfma_f32_16x16x32_bf16 v[32:35], v[204:207], v[220:223], v[32:35]
	v_mfma_f32_16x16x32_bf16 v[20:23], v[196:199], v[228:231], v[20:23]
	v_mfma_f32_16x16x32_bf16 v[16:19], v[204:207], v[228:231], v[16:19]
	v_mfma_f32_16x16x32_bf16 v[4:7], v[196:199], v[236:239], v[4:7]
	v_mfma_f32_16x16x32_bf16 v[0:3], v[204:207], v[236:239], v[0:3]
	s_setprio 0
	s_barrier
	s_add_i32 s67, s67, 2
	s_add_u32 s14, s14, 0x100
	s_addc_u32 s15, s15, 0
	s_add_u32 s65, s65, 0x100
	s_addc_u32 s66, s66, 0
	s_cmp_gt_u32 s67, 13
	s_cbranch_scc1 .Lgemm_kdone_4
.LBB0_725:
	ds_read_b128 v[128:131], v155
	ds_read_b128 v[132:135], v155 offset:1024
	ds_read_b128 v[136:139], v155 offset:2048
	ds_read_b128 v[164:167], v155 offset:3072
	ds_read_b128 v[188:191], v184
	ds_read_b128 v[196:199], v184 offset:1024
	ds_read_b128 v[200:203], v184 offset:2048
	ds_read_b128 v[204:207], v184 offset:3072
	s_add_u32 s2, s14, 0xfffc0080
	s_addc_u32 s3, s15, -1
	s_cmp_eq_u32 s67, 12
	s_cselect_b32 s23, s27, s3
	s_cselect_b32 s22, s59, s2
	s_cselect_b32 s3, s25, s66
	s_cselect_b32 s2, s64, s65
	v_lshl_add_u64 v[168:169], s[14:15], 0, v[156:157]
	s_add_i32 m0, s37, 0xc000
	ds_read_b128 v[208:211], v185
	ds_read_b128 v[212:215], v185 offset:1024
	ds_read_b128 v[216:219], v185 offset:2048
	ds_read_b128 v[220:223], v185 offset:3072
	ds_read_b128 v[224:227], v185 offset:4096
	ds_read_b128 v[228:231], v185 offset:5120
	ds_read_b128 v[232:235], v185 offset:6144
	ds_read_b128 v[236:239], v185 offset:7168
	global_load_lds_dwordx4 v[168:169], off
	v_lshl_add_u64 v[168:169], s[14:15], 0, v[158:159]
	s_add_i32 m0, s37, 0xe000
	s_nop 0
	global_load_lds_dwordx4 v[168:169], off
	s_waitcnt vmcnt(8)
	s_waitcnt lgkmcnt(0)
	s_barrier
	s_setprio 1
	s_waitcnt lgkmcnt(0)
	v_mfma_f32_16x16x32_bf16 v[124:127], v[128:131], v[208:211], v[124:127]
	v_mfma_f32_16x16x32_bf16 v[120:123], v[136:139], v[208:211], v[120:123]
	v_mfma_f32_16x16x32_bf16 v[108:111], v[128:131], v[216:219], v[108:111]
	v_mfma_f32_16x16x32_bf16 v[104:107], v[136:139], v[216:219], v[104:107]
	v_mfma_f32_16x16x32_bf16 v[92:95], v[128:131], v[224:227], v[92:95]
	v_mfma_f32_16x16x32_bf16 v[88:91], v[136:139], v[224:227], v[88:91]
	v_mfma_f32_16x16x32_bf16 v[76:79], v[128:131], v[232:235], v[76:79]
	v_mfma_f32_16x16x32_bf16 v[72:75], v[136:139], v[232:235], v[72:75]
	v_mfma_f32_16x16x32_bf16 v[124:127], v[132:135], v[212:215], v[124:127]
	v_mfma_f32_16x16x32_bf16 v[120:123], v[164:167], v[212:215], v[120:123]
	v_mfma_f32_16x16x32_bf16 v[108:111], v[132:135], v[220:223], v[108:111]
	v_mfma_f32_16x16x32_bf16 v[104:107], v[164:167], v[220:223], v[104:107]
	v_mfma_f32_16x16x32_bf16 v[92:95], v[132:135], v[228:231], v[92:95]
	v_mfma_f32_16x16x32_bf16 v[88:91], v[164:167], v[228:231], v[88:91]
	v_mfma_f32_16x16x32_bf16 v[76:79], v[132:135], v[236:239], v[76:79]
	v_mfma_f32_16x16x32_bf16 v[72:75], v[164:167], v[236:239], v[72:75]
	v_mfma_f32_16x16x32_bf16 v[116:119], v[188:191], v[208:211], v[116:119]
	v_mfma_f32_16x16x32_bf16 v[112:115], v[200:203], v[208:211], v[112:115]
	v_mfma_f32_16x16x32_bf16 v[100:103], v[188:191], v[216:219], v[100:103]
	v_mfma_f32_16x16x32_bf16 v[96:99], v[200:203], v[216:219], v[96:99]
	v_mfma_f32_16x16x32_bf16 v[84:87], v[188:191], v[224:227], v[84:87]
	v_mfma_f32_16x16x32_bf16 v[80:83], v[200:203], v[224:227], v[80:83]
	v_mfma_f32_16x16x32_bf16 v[68:71], v[188:191], v[232:235], v[68:71]
	v_mfma_f32_16x16x32_bf16 v[64:67], v[200:203], v[232:235], v[64:67]
	v_mfma_f32_16x16x32_bf16 v[116:119], v[196:199], v[212:215], v[116:119]
	v_mfma_f32_16x16x32_bf16 v[112:115], v[204:207], v[212:215], v[112:115]
	v_mfma_f32_16x16x32_bf16 v[100:103], v[196:199], v[220:223], v[100:103]
	v_mfma_f32_16x16x32_bf16 v[96:99], v[204:207], v[220:223], v[96:99]
	v_mfma_f32_16x16x32_bf16 v[84:87], v[196:199], v[228:231], v[84:87]
	v_mfma_f32_16x16x32_bf16 v[80:83], v[204:207], v[228:231], v[80:83]
	v_mfma_f32_16x16x32_bf16 v[68:71], v[196:199], v[236:239], v[68:71]
	v_mfma_f32_16x16x32_bf16 v[64:67], v[204:207], v[236:239], v[64:67]
	s_setprio 0
	s_barrier
	s_add_i32 s68, s52, s39
	v_lshl_add_u64 v[168:169], s[2:3], 0, v[142:143]
	s_mov_b32 m0, s68
	ds_read_b128 v[208:211], v185 offset:16384
	ds_read_b128 v[212:215], v185 offset:17408
	ds_read_b128 v[216:219], v185 offset:18432
	ds_read_b128 v[220:223], v185 offset:19456
	ds_read_b128 v[224:227], v185 offset:20480
	ds_read_b128 v[228:231], v185 offset:21504
	ds_read_b128 v[232:235], v185 offset:22528
	ds_read_b128 v[236:239], v185 offset:23552
	global_load_lds_dwordx4 v[168:169], off
	s_add_i32 m0, s68, 0x2000
	s_add_u32 s68, s2, 0x40000
	v_lshl_add_u64 v[192:193], s[2:3], 0, v[146:147]
	s_addc_u32 s69, s3, 0
	s_add_i32 s70, s53, s39
	global_load_lds_dwordx4 v[192:193], off
	v_lshl_add_u64 v[240:241], s[68:69], 0, v[142:143]
	s_mov_b32 m0, s70
	v_lshl_add_u64 v[242:243], s[22:23], 0, v[144:145]
	global_load_lds_dwordx4 v[240:241], off
	v_lshl_add_u64 v[240:241], s[68:69], 0, v[146:147]
	s_add_i32 m0, s70, 0x2000
	s_nop 0
	global_load_lds_dwordx4 v[240:241], off
	v_lshl_add_u64 v[240:241], s[22:23], 0, v[140:141]
	s_mov_b32 m0, s37
	s_nop 0
	global_load_lds_dwordx4 v[240:241], off
	s_mov_b32 m0, s40
	s_nop 0
	global_load_lds_dwordx4 v[242:243], off
	s_waitcnt vmcnt(8)
	s_waitcnt lgkmcnt(0)
	s_barrier
	s_setprio 1
	s_waitcnt lgkmcnt(0)
	v_mfma_f32_16x16x32_bf16 v[60:63], v[128:131], v[208:211], v[60:63]
	v_mfma_f32_16x16x32_bf16 v[56:59], v[136:139], v[208:211], v[56:59]
	v_mfma_f32_16x16x32_bf16 v[44:47], v[128:131], v[216:219], v[44:47]
	v_mfma_f32_16x16x32_bf16 v[40:43], v[136:139], v[216:219], v[40:43]
	v_mfma_f32_16x16x32_bf16 v[28:31], v[128:131], v[224:227], v[28:31]
	v_mfma_f32_16x16x32_bf16 v[24:27], v[136:139], v[224:227], v[24:27]
	v_mfma_f32_16x16x32_bf16 v[12:15], v[128:131], v[232:235], v[12:15]
	v_mfma_f32_16x16x32_bf16 v[8:11], v[136:139], v[232:235], v[8:11]
	v_mfma_f32_16x16x32_bf16 v[60:63], v[132:135], v[212:215], v[60:63]
	v_mfma_f32_16x16x32_bf16 v[56:59], v[164:167], v[212:215], v[56:59]
	v_mfma_f32_16x16x32_bf16 v[44:47], v[132:135], v[220:223], v[44:47]
	v_mfma_f32_16x16x32_bf16 v[40:43], v[164:167], v[220:223], v[40:43]
	v_mfma_f32_16x16x32_bf16 v[28:31], v[132:135], v[228:231], v[28:31]
	v_mfma_f32_16x16x32_bf16 v[24:27], v[164:167], v[228:231], v[24:27]
	v_mfma_f32_16x16x32_bf16 v[12:15], v[132:135], v[236:239], v[12:15]
	v_mfma_f32_16x16x32_bf16 v[8:11], v[164:167], v[236:239], v[8:11]
	v_mfma_f32_16x16x32_bf16 v[52:55], v[188:191], v[208:211], v[52:55]
	v_mfma_f32_16x16x32_bf16 v[48:51], v[200:203], v[208:211], v[48:51]
	v_mfma_f32_16x16x32_bf16 v[36:39], v[188:191], v[216:219], v[36:39]
	v_mfma_f32_16x16x32_bf16 v[32:35], v[200:203], v[216:219], v[32:35]
	v_mfma_f32_16x16x32_bf16 v[20:23], v[188:191], v[224:227], v[20:23]
	v_mfma_f32_16x16x32_bf16 v[16:19], v[200:203], v[224:227], v[16:19]
	v_mfma_f32_16x16x32_bf16 v[4:7], v[188:191], v[232:235], v[4:7]
	v_mfma_f32_16x16x32_bf16 v[0:3], v[200:203], v[232:235], v[0:3]
	v_mfma_f32_16x16x32_bf16 v[52:55], v[196:199], v[212:215], v[52:55]
	v_mfma_f32_16x16x32_bf16 v[48:51], v[204:207], v[212:215], v[48:51]
	v_mfma_f32_16x16x32_bf16 v[36:39], v[196:199], v[220:223], v[36:39]
	v_mfma_f32_16x16x32_bf16 v[32:35], v[204:207], v[220:223], v[32:35]
	v_mfma_f32_16x16x32_bf16 v[20:23], v[196:199], v[228:231], v[20:23]
	v_mfma_f32_16x16x32_bf16 v[16:19], v[204:207], v[228:231], v[16:19]
	v_mfma_f32_16x16x32_bf16 v[4:7], v[196:199], v[236:239], v[4:7]
	v_mfma_f32_16x16x32_bf16 v[0:3], v[204:207], v[236:239], v[0:3]
	s_setprio 0
	s_barrier
	s_add_i32 s68, 0, 0x18000
	s_add_i32 s69, 0, 0x1c000
	v_add_u32_e32 v164, s68, v149
	v_add_u32_e32 v187, s69, v149
	ds_read_b128 v[128:131], v164
	ds_read_b128 v[132:135], v164 offset:1024
	ds_read_b128 v[136:139], v164 offset:2048
	ds_read_b128 v[164:167], v164 offset:3072
	ds_read_b128 v[188:191], v187
	ds_read_b128 v[196:199], v187 offset:1024
	ds_read_b128 v[200:203], v187 offset:2048
	ds_read_b128 v[204:207], v187 offset:3072
	s_add_u32 s22, s22, 0x40000
	s_addc_u32 s23, s23, 0
	s_mov_b32 m0, s41
	v_lshl_add_u64 v[244:245], s[22:23], 0, v[140:141]
	ds_read_b128 v[208:211], v185 offset:32768
	ds_read_b128 v[212:215], v185 offset:33792
	ds_read_b128 v[216:219], v185 offset:34816
	ds_read_b128 v[220:223], v185 offset:35840
	ds_read_b128 v[224:227], v185 offset:36864
	ds_read_b128 v[228:231], v185 offset:37888
	ds_read_b128 v[232:235], v185 offset:38912
	ds_read_b128 v[236:239], v185 offset:39936
	global_load_lds_dwordx4 v[244:245], off
	v_lshl_add_u64 v[244:245], s[22:23], 0, v[144:145]
	s_mov_b32 m0, s42
	s_nop 0
	global_load_lds_dwordx4 v[244:245], off
	s_waitcnt vmcnt(8)
	s_waitcnt lgkmcnt(0)
	s_barrier
	s_setprio 1
	s_waitcnt lgkmcnt(0)
	v_mfma_f32_16x16x32_bf16 v[124:127], v[128:131], v[208:211], v[124:127]
	v_mfma_f32_16x16x32_bf16 v[120:123], v[136:139], v[208:211], v[120:123]
	v_mfma_f32_16x16x32_bf16 v[108:111], v[128:131], v[216:219], v[108:111]
	v_mfma_f32_16x16x32_bf16 v[104:107], v[136:139], v[216:219], v[104:107]
	v_mfma_f32_16x16x32_bf16 v[92:95], v[128:131], v[224:227], v[92:95]
	v_mfma_f32_16x16x32_bf16 v[88:91], v[136:139], v[224:227], v[88:91]
	v_mfma_f32_16x16x32_bf16 v[76:79], v[128:131], v[232:235], v[76:79]
	v_mfma_f32_16x16x32_bf16 v[72:75], v[136:139], v[232:235], v[72:75]
	v_mfma_f32_16x16x32_bf16 v[124:127], v[132:135], v[212:215], v[124:127]
	v_mfma_f32_16x16x32_bf16 v[120:123], v[164:167], v[212:215], v[120:123]
	v_mfma_f32_16x16x32_bf16 v[108:111], v[132:135], v[220:223], v[108:111]
	v_mfma_f32_16x16x32_bf16 v[104:107], v[164:167], v[220:223], v[104:107]
	v_mfma_f32_16x16x32_bf16 v[92:95], v[132:135], v[228:231], v[92:95]
	v_mfma_f32_16x16x32_bf16 v[88:91], v[164:167], v[228:231], v[88:91]
	v_mfma_f32_16x16x32_bf16 v[76:79], v[132:135], v[236:239], v[76:79]
	v_mfma_f32_16x16x32_bf16 v[72:75], v[164:167], v[236:239], v[72:75]
	v_mfma_f32_16x16x32_bf16 v[116:119], v[188:191], v[208:211], v[116:119]
	v_mfma_f32_16x16x32_bf16 v[112:115], v[200:203], v[208:211], v[112:115]
	v_mfma_f32_16x16x32_bf16 v[100:103], v[188:191], v[216:219], v[100:103]
	v_mfma_f32_16x16x32_bf16 v[96:99], v[200:203], v[216:219], v[96:99]
	v_mfma_f32_16x16x32_bf16 v[84:87], v[188:191], v[224:227], v[84:87]
	v_mfma_f32_16x16x32_bf16 v[80:83], v[200:203], v[224:227], v[80:83]
	v_mfma_f32_16x16x32_bf16 v[68:71], v[188:191], v[232:235], v[68:71]
	v_mfma_f32_16x16x32_bf16 v[64:67], v[200:203], v[232:235], v[64:67]
	v_mfma_f32_16x16x32_bf16 v[116:119], v[196:199], v[212:215], v[116:119]
	v_mfma_f32_16x16x32_bf16 v[112:115], v[204:207], v[212:215], v[112:115]
	v_mfma_f32_16x16x32_bf16 v[100:103], v[196:199], v[220:223], v[100:103]
	v_mfma_f32_16x16x32_bf16 v[96:99], v[204:207], v[220:223], v[96:99]
	v_mfma_f32_16x16x32_bf16 v[84:87], v[196:199], v[228:231], v[84:87]
	v_mfma_f32_16x16x32_bf16 v[80:83], v[204:207], v[228:231], v[80:83]
	v_mfma_f32_16x16x32_bf16 v[68:71], v[196:199], v[236:239], v[68:71]
	v_mfma_f32_16x16x32_bf16 v[64:67], v[204:207], v[236:239], v[64:67]
	s_setprio 0
	s_barrier
	s_add_i32 s22, s68, s39
	v_lshl_add_u64 v[168:169], v[168:169], 0, s[18:19]
	s_mov_b32 m0, s22
	ds_read_b128 v[208:211], v185 offset:49152
	ds_read_b128 v[212:215], v185 offset:50176
	ds_read_b128 v[216:219], v185 offset:51200
	ds_read_b128 v[220:223], v185 offset:52224
	ds_read_b128 v[224:227], v185 offset:53248
	ds_read_b128 v[228:231], v185 offset:54272
	ds_read_b128 v[232:235], v185 offset:55296
	ds_read_b128 v[236:239], v185 offset:56320
	global_load_lds_dwordx4 v[168:169], off
	s_add_i32 m0, s22, 0x2000
	s_add_u32 s2, s2, 0x40080
	v_lshl_add_u64 v[168:169], v[192:193], 0, s[18:19]
	s_addc_u32 s3, s3, 0
	s_add_i32 s22, s69, s39
	global_load_lds_dwordx4 v[168:169], off
	v_lshl_add_u64 v[168:169], s[2:3], 0, v[142:143]
	s_mov_b32 m0, s22
	s_nop 0
	global_load_lds_dwordx4 v[168:169], off
	v_lshl_add_u64 v[168:169], s[2:3], 0, v[146:147]
	s_add_i32 m0, s22, 0x2000
	s_nop 0
	global_load_lds_dwordx4 v[168:169], off
	v_lshl_add_u64 v[168:169], v[240:241], 0, s[18:19]
	s_mov_b32 m0, s46
	s_nop 0
	global_load_lds_dwordx4 v[168:169], off
	v_lshl_add_u64 v[168:169], v[242:243], 0, s[18:19]
	s_mov_b32 m0, s47
	s_nop 0
	global_load_lds_dwordx4 v[168:169], off
	s_waitcnt vmcnt(8)
	s_waitcnt lgkmcnt(0)
	s_barrier
	s_setprio 1
	s_waitcnt lgkmcnt(0)
	v_mfma_f32_16x16x32_bf16 v[60:63], v[128:131], v[208:211], v[60:63]
	v_mfma_f32_16x16x32_bf16 v[56:59], v[136:139], v[208:211], v[56:59]
	v_mfma_f32_16x16x32_bf16 v[44:47], v[128:131], v[216:219], v[44:47]
	v_mfma_f32_16x16x32_bf16 v[40:43], v[136:139], v[216:219], v[40:43]
	v_mfma_f32_16x16x32_bf16 v[28:31], v[128:131], v[224:227], v[28:31]
	v_mfma_f32_16x16x32_bf16 v[24:27], v[136:139], v[224:227], v[24:27]
	v_mfma_f32_16x16x32_bf16 v[12:15], v[128:131], v[232:235], v[12:15]
	v_mfma_f32_16x16x32_bf16 v[8:11], v[136:139], v[232:235], v[8:11]
	v_mfma_f32_16x16x32_bf16 v[60:63], v[132:135], v[212:215], v[60:63]
	v_mfma_f32_16x16x32_bf16 v[56:59], v[164:167], v[212:215], v[56:59]
	v_mfma_f32_16x16x32_bf16 v[44:47], v[132:135], v[220:223], v[44:47]
	v_mfma_f32_16x16x32_bf16 v[40:43], v[164:167], v[220:223], v[40:43]
	v_mfma_f32_16x16x32_bf16 v[28:31], v[132:135], v[228:231], v[28:31]
	v_mfma_f32_16x16x32_bf16 v[24:27], v[164:167], v[228:231], v[24:27]
	v_mfma_f32_16x16x32_bf16 v[12:15], v[132:135], v[236:239], v[12:15]
	v_mfma_f32_16x16x32_bf16 v[8:11], v[164:167], v[236:239], v[8:11]
	v_mfma_f32_16x16x32_bf16 v[52:55], v[188:191], v[208:211], v[52:55]
	v_mfma_f32_16x16x32_bf16 v[48:51], v[200:203], v[208:211], v[48:51]
	v_mfma_f32_16x16x32_bf16 v[36:39], v[188:191], v[216:219], v[36:39]
	v_mfma_f32_16x16x32_bf16 v[32:35], v[200:203], v[216:219], v[32:35]
	v_mfma_f32_16x16x32_bf16 v[20:23], v[188:191], v[224:227], v[20:23]
	v_mfma_f32_16x16x32_bf16 v[16:19], v[200:203], v[224:227], v[16:19]
	v_mfma_f32_16x16x32_bf16 v[4:7], v[188:191], v[232:235], v[4:7]
	v_mfma_f32_16x16x32_bf16 v[0:3], v[200:203], v[232:235], v[0:3]
	v_mfma_f32_16x16x32_bf16 v[52:55], v[196:199], v[212:215], v[52:55]
	v_mfma_f32_16x16x32_bf16 v[48:51], v[204:207], v[212:215], v[48:51]
	v_mfma_f32_16x16x32_bf16 v[36:39], v[196:199], v[220:223], v[36:39]
	v_mfma_f32_16x16x32_bf16 v[32:35], v[204:207], v[220:223], v[32:35]
	v_mfma_f32_16x16x32_bf16 v[20:23], v[196:199], v[228:231], v[20:23]
	v_mfma_f32_16x16x32_bf16 v[16:19], v[204:207], v[228:231], v[16:19]
	v_mfma_f32_16x16x32_bf16 v[4:7], v[196:199], v[236:239], v[4:7]
	v_mfma_f32_16x16x32_bf16 v[0:3], v[204:207], v[236:239], v[0:3]
	s_setprio 0
	s_barrier
	s_add_i32 s67, s67, 2
	s_add_u32 s14, s14, 0x100
	s_addc_u32 s15, s15, 0
	s_add_u32 s65, s65, 0x100
	s_addc_u32 s66, s66, 0
	s_cmp_gt_u32 s67, 13
	s_cbranch_scc0 .LBB0_725

.LBB0_808:
	s_ashr_i32 s25, s24, 31
	s_lshl_b64 s[22:23], s[24:25], 19
	s_add_u32 s26, s84, s22
	s_addc_u32 s27, s85, s23
	s_and_b64 s[22:23], s[4:5], exec
	s_cselect_b32 s25, s27, s15
	s_cselect_b32 s50, s26, s14
	s_ashr_i32 s21, s20, 31
	s_lshl_b64 s[22:23], s[20:21], 19
	s_add_u32 s28, s30, s22
	s_addc_u32 s29, s31, s23
	s_and_b64 s[22:23], s[4:5], exec
	s_cselect_b32 s21, s29, s3
	s_cselect_b32 s51, s28, s2
	s_add_u32 s14, s14, 0x40080
	s_addc_u32 s15, s15, 0
	s_add_u32 s52, s2, 0x100
	s_addc_u32 s53, s3, 0
	s_mov_b32 s54, -2
	s_waitcnt vmcnt(0)
	ds_read_b128 v[136:139], v155
	ds_read_b128 v[162:165], v155 offset:1024
	ds_read_b128 v[166:169], v155 offset:2048
	ds_read_b128 v[178:181], v155 offset:3072
	ds_read_b128 v[184:187], v158
	ds_read_b128 v[188:191], v158 offset:1024
	ds_read_b128 v[196:199], v158 offset:2048
	ds_read_b128 v[200:203], v158 offset:3072
	s_add_u32 s2, s14, 0xfffc0080
	s_addc_u32 s3, s15, -1
	s_cmp_eq_u32 s54, 12
	s_cselect_b32 s23, s25, s3
	s_cselect_b32 s22, s50, s2
	s_cselect_b32 s3, s21, s53
	s_cselect_b32 s2, s51, s52
	v_lshl_add_u64 v[156:157], s[14:15], 0, v[128:129]
	s_add_i32 m0, s37, 0xc000
	ds_read_b128 v[204:207], v159
	ds_read_b128 v[208:211], v159 offset:1024
	ds_read_b128 v[212:215], v159 offset:2048
	ds_read_b128 v[216:219], v159 offset:3072
	ds_read_b128 v[220:223], v159 offset:4096
	ds_read_b128 v[224:227], v159 offset:5120
	ds_read_b128 v[228:231], v159 offset:6144
	ds_read_b128 v[232:235], v159 offset:7168
	global_load_lds_dwordx4 v[156:157], off
	v_lshl_add_u64 v[156:157], s[14:15], 0, v[130:131]
	s_add_i32 m0, s37, 0xe000
	s_nop 0
	global_load_lds_dwordx4 v[156:157], off
	s_waitcnt vmcnt(8)
	s_waitcnt lgkmcnt(0)
	s_barrier
	s_setprio 1
	s_waitcnt lgkmcnt(0)
	v_mfma_f32_16x16x32_bf16 v[112:115], v[136:139], v[204:207], 0
	v_mfma_f32_16x16x32_bf16 v[108:111], v[166:169], v[204:207], 0
	v_mfma_f32_16x16x32_bf16 v[104:107], v[136:139], v[212:215], 0
	v_mfma_f32_16x16x32_bf16 v[100:103], v[166:169], v[212:215], 0
	v_mfma_f32_16x16x32_bf16 v[92:95], v[136:139], v[220:223], 0
	v_mfma_f32_16x16x32_bf16 v[84:87], v[166:169], v[220:223], 0
	v_mfma_f32_16x16x32_bf16 v[76:79], v[136:139], v[228:231], 0
	v_mfma_f32_16x16x32_bf16 v[68:71], v[166:169], v[228:231], 0
	v_mfma_f32_16x16x32_bf16 v[112:115], v[162:165], v[208:211], v[112:115]
	v_mfma_f32_16x16x32_bf16 v[108:111], v[178:181], v[208:211], v[108:111]
	v_mfma_f32_16x16x32_bf16 v[104:107], v[162:165], v[216:219], v[104:107]
	v_mfma_f32_16x16x32_bf16 v[100:103], v[178:181], v[216:219], v[100:103]
	v_mfma_f32_16x16x32_bf16 v[92:95], v[162:165], v[224:227], v[92:95]
	v_mfma_f32_16x16x32_bf16 v[84:87], v[178:181], v[224:227], v[84:87]
	v_mfma_f32_16x16x32_bf16 v[76:79], v[162:165], v[232:235], v[76:79]
	v_mfma_f32_16x16x32_bf16 v[68:71], v[178:181], v[232:235], v[68:71]
	v_mfma_f32_16x16x32_bf16 v[124:127], v[184:187], v[204:207], 0
	v_mfma_f32_16x16x32_bf16 v[120:123], v[196:199], v[204:207], 0
	v_mfma_f32_16x16x32_bf16 v[116:119], v[184:187], v[212:215], 0
	v_mfma_f32_16x16x32_bf16 v[96:99], v[196:199], v[212:215], 0
	v_mfma_f32_16x16x32_bf16 v[88:91], v[184:187], v[220:223], 0
	v_mfma_f32_16x16x32_bf16 v[80:83], v[196:199], v[220:223], 0
	v_mfma_f32_16x16x32_bf16 v[72:75], v[184:187], v[228:231], 0
	v_mfma_f32_16x16x32_bf16 v[64:67], v[196:199], v[228:231], 0
	v_mfma_f32_16x16x32_bf16 v[124:127], v[188:191], v[208:211], v[124:127]
	v_mfma_f32_16x16x32_bf16 v[120:123], v[200:203], v[208:211], v[120:123]
	v_mfma_f32_16x16x32_bf16 v[116:119], v[188:191], v[216:219], v[116:119]
	v_mfma_f32_16x16x32_bf16 v[96:99], v[200:203], v[216:219], v[96:99]
	v_mfma_f32_16x16x32_bf16 v[88:91], v[188:191], v[224:227], v[88:91]
	v_mfma_f32_16x16x32_bf16 v[80:83], v[200:203], v[224:227], v[80:83]
	v_mfma_f32_16x16x32_bf16 v[72:75], v[188:191], v[232:235], v[72:75]
	v_mfma_f32_16x16x32_bf16 v[64:67], v[200:203], v[232:235], v[64:67]
	s_setprio 0
	s_barrier
	s_add_i32 s55, s46, s34
	v_lshl_add_u64 v[156:157], s[2:3], 0, v[142:143]
	s_mov_b32 m0, s55
	ds_read_b128 v[204:207], v159 offset:16384
	ds_read_b128 v[208:211], v159 offset:17408
	ds_read_b128 v[212:215], v159 offset:18432
	ds_read_b128 v[216:219], v159 offset:19456
	ds_read_b128 v[220:223], v159 offset:20480
	ds_read_b128 v[224:227], v159 offset:21504
	ds_read_b128 v[228:231], v159 offset:22528
	ds_read_b128 v[232:235], v159 offset:23552
	global_load_lds_dwordx4 v[156:157], off
	s_add_i32 m0, s55, 0x2000
	s_add_u32 s56, s2, 0x40000
	v_lshl_add_u64 v[192:193], s[2:3], 0, v[146:147]
	s_addc_u32 s57, s3, 0
	s_add_i32 s55, s47, s34
	global_load_lds_dwordx4 v[192:193], off
	v_lshl_add_u64 v[236:237], s[56:57], 0, v[142:143]
	s_mov_b32 m0, s55
	v_lshl_add_u64 v[238:239], s[22:23], 0, v[144:145]
	global_load_lds_dwordx4 v[236:237], off
	v_lshl_add_u64 v[236:237], s[56:57], 0, v[146:147]
	s_add_i32 m0, s55, 0x2000
	s_nop 0
	global_load_lds_dwordx4 v[236:237], off
	v_lshl_add_u64 v[236:237], s[22:23], 0, v[140:141]
	s_mov_b32 m0, s37
	s_nop 0
	global_load_lds_dwordx4 v[236:237], off
	s_mov_b32 m0, s38
	s_nop 0
	global_load_lds_dwordx4 v[238:239], off
	s_waitcnt vmcnt(8)
	s_waitcnt lgkmcnt(0)
	s_barrier
	s_setprio 1
	s_waitcnt lgkmcnt(0)
	v_mfma_f32_16x16x32_bf16 v[60:63], v[136:139], v[204:207], 0
	v_mfma_f32_16x16x32_bf16 v[52:55], v[166:169], v[204:207], 0
	v_mfma_f32_16x16x32_bf16 v[44:47], v[136:139], v[212:215], 0
	v_mfma_f32_16x16x32_bf16 v[36:39], v[166:169], v[212:215], 0
	v_mfma_f32_16x16x32_bf16 v[28:31], v[136:139], v[220:223], 0
	v_mfma_f32_16x16x32_bf16 v[20:23], v[166:169], v[220:223], 0
	v_mfma_f32_16x16x32_bf16 v[12:15], v[136:139], v[228:231], 0
	v_mfma_f32_16x16x32_bf16 v[4:7], v[166:169], v[228:231], 0
	v_mfma_f32_16x16x32_bf16 v[60:63], v[162:165], v[208:211], v[60:63]
	v_mfma_f32_16x16x32_bf16 v[52:55], v[178:181], v[208:211], v[52:55]
	v_mfma_f32_16x16x32_bf16 v[44:47], v[162:165], v[216:219], v[44:47]
	v_mfma_f32_16x16x32_bf16 v[36:39], v[178:181], v[216:219], v[36:39]
	v_mfma_f32_16x16x32_bf16 v[28:31], v[162:165], v[224:227], v[28:31]
	v_mfma_f32_16x16x32_bf16 v[20:23], v[178:181], v[224:227], v[20:23]
	v_mfma_f32_16x16x32_bf16 v[12:15], v[162:165], v[232:235], v[12:15]
	v_mfma_f32_16x16x32_bf16 v[4:7], v[178:181], v[232:235], v[4:7]
	v_mfma_f32_16x16x32_bf16 v[56:59], v[184:187], v[204:207], 0
	v_mfma_f32_16x16x32_bf16 v[48:51], v[196:199], v[204:207], 0
	v_mfma_f32_16x16x32_bf16 v[40:43], v[184:187], v[212:215], 0
	v_mfma_f32_16x16x32_bf16 v[32:35], v[196:199], v[212:215], 0
	v_mfma_f32_16x16x32_bf16 v[24:27], v[184:187], v[220:223], 0
	v_mfma_f32_16x16x32_bf16 v[16:19], v[196:199], v[220:223], 0
	v_mfma_f32_16x16x32_bf16 v[8:11], v[184:187], v[228:231], 0
	v_mfma_f32_16x16x32_bf16 v[0:3], v[196:199], v[228:231], 0
	v_mfma_f32_16x16x32_bf16 v[56:59], v[188:191], v[208:211], v[56:59]
	v_mfma_f32_16x16x32_bf16 v[48:51], v[200:203], v[208:211], v[48:51]
	v_mfma_f32_16x16x32_bf16 v[40:43], v[188:191], v[216:219], v[40:43]
	v_mfma_f32_16x16x32_bf16 v[32:35], v[200:203], v[216:219], v[32:35]
	v_mfma_f32_16x16x32_bf16 v[24:27], v[188:191], v[224:227], v[24:27]
	v_mfma_f32_16x16x32_bf16 v[16:19], v[200:203], v[224:227], v[16:19]
	v_mfma_f32_16x16x32_bf16 v[8:11], v[188:191], v[232:235], v[8:11]
	v_mfma_f32_16x16x32_bf16 v[0:3], v[200:203], v[232:235], v[0:3]
	s_setprio 0
	s_barrier
	s_add_i32 s55, 0, 0x18000
	v_add_u32_e32 v161, s55, v151
	s_add_i32 s56, 0, 0x1c000
	ds_read_b128 v[136:139], v161
	ds_read_b128 v[162:165], v161 offset:1024
	ds_read_b128 v[166:169], v161 offset:2048
	ds_read_b128 v[178:181], v161 offset:3072
	v_add_u32_e32 v161, s56, v151
	ds_read_b128 v[184:187], v161
	ds_read_b128 v[188:191], v161 offset:1024
	ds_read_b128 v[196:199], v161 offset:2048
	ds_read_b128 v[200:203], v161 offset:3072
	s_add_u32 s22, s22, 0x40000
	s_addc_u32 s23, s23, 0
	s_mov_b32 m0, s39
	v_lshl_add_u64 v[240:241], s[22:23], 0, v[140:141]
	ds_read_b128 v[204:207], v159 offset:32768
	ds_read_b128 v[208:211], v159 offset:33792
	ds_read_b128 v[212:215], v159 offset:34816
	ds_read_b128 v[216:219], v159 offset:35840
	ds_read_b128 v[220:223], v159 offset:36864
	ds_read_b128 v[224:227], v159 offset:37888
	ds_read_b128 v[228:231], v159 offset:38912
	ds_read_b128 v[232:235], v159 offset:39936
	global_load_lds_dwordx4 v[240:241], off
	v_lshl_add_u64 v[240:241], s[22:23], 0, v[144:145]
	s_mov_b32 m0, s40
	s_nop 0
	global_load_lds_dwordx4 v[240:241], off
	s_waitcnt vmcnt(8)
	s_waitcnt lgkmcnt(0)
	s_barrier
	s_setprio 1
	s_waitcnt lgkmcnt(0)
	v_mfma_f32_16x16x32_bf16 v[112:115], v[136:139], v[204:207], v[112:115]
	v_mfma_f32_16x16x32_bf16 v[108:111], v[166:169], v[204:207], v[108:111]
	v_mfma_f32_16x16x32_bf16 v[104:107], v[136:139], v[212:215], v[104:107]
	v_mfma_f32_16x16x32_bf16 v[100:103], v[166:169], v[212:215], v[100:103]
	v_mfma_f32_16x16x32_bf16 v[92:95], v[136:139], v[220:223], v[92:95]
	v_mfma_f32_16x16x32_bf16 v[84:87], v[166:169], v[220:223], v[84:87]
	v_mfma_f32_16x16x32_bf16 v[76:79], v[136:139], v[228:231], v[76:79]
	v_mfma_f32_16x16x32_bf16 v[68:71], v[166:169], v[228:231], v[68:71]
	v_mfma_f32_16x16x32_bf16 v[112:115], v[162:165], v[208:211], v[112:115]
	v_mfma_f32_16x16x32_bf16 v[108:111], v[178:181], v[208:211], v[108:111]
	v_mfma_f32_16x16x32_bf16 v[104:107], v[162:165], v[216:219], v[104:107]
	v_mfma_f32_16x16x32_bf16 v[100:103], v[178:181], v[216:219], v[100:103]
	v_mfma_f32_16x16x32_bf16 v[92:95], v[162:165], v[224:227], v[92:95]
	v_mfma_f32_16x16x32_bf16 v[84:87], v[178:181], v[224:227], v[84:87]
	v_mfma_f32_16x16x32_bf16 v[76:79], v[162:165], v[232:235], v[76:79]
	v_mfma_f32_16x16x32_bf16 v[68:71], v[178:181], v[232:235], v[68:71]
	v_mfma_f32_16x16x32_bf16 v[124:127], v[184:187], v[204:207], v[124:127]
	v_mfma_f32_16x16x32_bf16 v[120:123], v[196:199], v[204:207], v[120:123]
	v_mfma_f32_16x16x32_bf16 v[116:119], v[184:187], v[212:215], v[116:119]
	v_mfma_f32_16x16x32_bf16 v[96:99], v[196:199], v[212:215], v[96:99]
	v_mfma_f32_16x16x32_bf16 v[88:91], v[184:187], v[220:223], v[88:91]
	v_mfma_f32_16x16x32_bf16 v[80:83], v[196:199], v[220:223], v[80:83]
	v_mfma_f32_16x16x32_bf16 v[72:75], v[184:187], v[228:231], v[72:75]
	v_mfma_f32_16x16x32_bf16 v[64:67], v[196:199], v[228:231], v[64:67]
	v_mfma_f32_16x16x32_bf16 v[124:127], v[188:191], v[208:211], v[124:127]
	v_mfma_f32_16x16x32_bf16 v[120:123], v[200:203], v[208:211], v[120:123]
	v_mfma_f32_16x16x32_bf16 v[116:119], v[188:191], v[216:219], v[116:119]
	v_mfma_f32_16x16x32_bf16 v[96:99], v[200:203], v[216:219], v[96:99]
	v_mfma_f32_16x16x32_bf16 v[88:91], v[188:191], v[224:227], v[88:91]
	v_mfma_f32_16x16x32_bf16 v[80:83], v[200:203], v[224:227], v[80:83]
	v_mfma_f32_16x16x32_bf16 v[72:75], v[188:191], v[232:235], v[72:75]
	v_mfma_f32_16x16x32_bf16 v[64:67], v[200:203], v[232:235], v[64:67]
	s_setprio 0
	s_barrier
	s_add_i32 s22, s55, s34
	v_lshl_add_u64 v[156:157], v[156:157], 0, s[12:13]
	s_mov_b32 m0, s22
	ds_read_b128 v[204:207], v159 offset:49152
	ds_read_b128 v[208:211], v159 offset:50176
	ds_read_b128 v[212:215], v159 offset:51200
	ds_read_b128 v[216:219], v159 offset:52224
	ds_read_b128 v[220:223], v159 offset:53248
	ds_read_b128 v[224:227], v159 offset:54272
	ds_read_b128 v[228:231], v159 offset:55296
	ds_read_b128 v[232:235], v159 offset:56320
	global_load_lds_dwordx4 v[156:157], off
	s_add_i32 m0, s22, 0x2000
	s_add_u32 s2, s2, 0x40080
	v_lshl_add_u64 v[156:157], v[192:193], 0, s[12:13]
	s_addc_u32 s3, s3, 0
	s_add_i32 s22, s56, s34
	global_load_lds_dwordx4 v[156:157], off
	v_lshl_add_u64 v[156:157], s[2:3], 0, v[142:143]
	s_mov_b32 m0, s22
	s_nop 0
	global_load_lds_dwordx4 v[156:157], off
	v_lshl_add_u64 v[156:157], s[2:3], 0, v[146:147]
	s_add_i32 m0, s22, 0x2000
	s_nop 0
	global_load_lds_dwordx4 v[156:157], off
	v_lshl_add_u64 v[156:157], v[236:237], 0, s[12:13]
	s_mov_b32 m0, s42
	s_nop 0
	global_load_lds_dwordx4 v[156:157], off
	v_lshl_add_u64 v[156:157], v[238:239], 0, s[12:13]
	s_mov_b32 m0, s43
	s_nop 0
	global_load_lds_dwordx4 v[156:157], off
	s_waitcnt vmcnt(8)
	s_waitcnt lgkmcnt(0)
	s_barrier
	s_setprio 1
	s_waitcnt lgkmcnt(0)
	v_mfma_f32_16x16x32_bf16 v[60:63], v[136:139], v[204:207], v[60:63]
	v_mfma_f32_16x16x32_bf16 v[52:55], v[166:169], v[204:207], v[52:55]
	v_mfma_f32_16x16x32_bf16 v[44:47], v[136:139], v[212:215], v[44:47]
	v_mfma_f32_16x16x32_bf16 v[36:39], v[166:169], v[212:215], v[36:39]
	v_mfma_f32_16x16x32_bf16 v[28:31], v[136:139], v[220:223], v[28:31]
	v_mfma_f32_16x16x32_bf16 v[20:23], v[166:169], v[220:223], v[20:23]
	v_mfma_f32_16x16x32_bf16 v[12:15], v[136:139], v[228:231], v[12:15]
	v_mfma_f32_16x16x32_bf16 v[4:7], v[166:169], v[228:231], v[4:7]
	v_mfma_f32_16x16x32_bf16 v[60:63], v[162:165], v[208:211], v[60:63]
	v_mfma_f32_16x16x32_bf16 v[52:55], v[178:181], v[208:211], v[52:55]
	v_mfma_f32_16x16x32_bf16 v[44:47], v[162:165], v[216:219], v[44:47]
	v_mfma_f32_16x16x32_bf16 v[36:39], v[178:181], v[216:219], v[36:39]
	v_mfma_f32_16x16x32_bf16 v[28:31], v[162:165], v[224:227], v[28:31]
	v_mfma_f32_16x16x32_bf16 v[20:23], v[178:181], v[224:227], v[20:23]
	v_mfma_f32_16x16x32_bf16 v[12:15], v[162:165], v[232:235], v[12:15]
	v_mfma_f32_16x16x32_bf16 v[4:7], v[178:181], v[232:235], v[4:7]
	v_mfma_f32_16x16x32_bf16 v[56:59], v[184:187], v[204:207], v[56:59]
	v_mfma_f32_16x16x32_bf16 v[48:51], v[196:199], v[204:207], v[48:51]
	v_mfma_f32_16x16x32_bf16 v[40:43], v[184:187], v[212:215], v[40:43]
	v_mfma_f32_16x16x32_bf16 v[32:35], v[196:199], v[212:215], v[32:35]
	v_mfma_f32_16x16x32_bf16 v[24:27], v[184:187], v[220:223], v[24:27]
	v_mfma_f32_16x16x32_bf16 v[16:19], v[196:199], v[220:223], v[16:19]
	v_mfma_f32_16x16x32_bf16 v[8:11], v[184:187], v[228:231], v[8:11]
	v_mfma_f32_16x16x32_bf16 v[0:3], v[196:199], v[228:231], v[0:3]
	v_mfma_f32_16x16x32_bf16 v[56:59], v[188:191], v[208:211], v[56:59]
	v_mfma_f32_16x16x32_bf16 v[48:51], v[200:203], v[208:211], v[48:51]
	v_mfma_f32_16x16x32_bf16 v[40:43], v[188:191], v[216:219], v[40:43]
	v_mfma_f32_16x16x32_bf16 v[32:35], v[200:203], v[216:219], v[32:35]
	v_mfma_f32_16x16x32_bf16 v[24:27], v[188:191], v[224:227], v[24:27]
	v_mfma_f32_16x16x32_bf16 v[16:19], v[200:203], v[224:227], v[16:19]
	v_mfma_f32_16x16x32_bf16 v[8:11], v[188:191], v[232:235], v[8:11]
	v_mfma_f32_16x16x32_bf16 v[0:3], v[200:203], v[232:235], v[0:3]
	s_setprio 0
	s_barrier
	s_add_i32 s54, s54, 2
	s_add_u32 s14, s14, 0x100
	s_addc_u32 s15, s15, 0
	s_add_u32 s52, s52, 0x100
	s_addc_u32 s53, s53, 0
	s_cmp_gt_u32 s54, 13
	s_cbranch_scc1 .Lgemm_kdone_5
.LBB0_809:
	ds_read_b128 v[136:139], v155
	ds_read_b128 v[162:165], v155 offset:1024
	ds_read_b128 v[166:169], v155 offset:2048
	ds_read_b128 v[178:181], v155 offset:3072
	ds_read_b128 v[184:187], v158
	ds_read_b128 v[188:191], v158 offset:1024
	ds_read_b128 v[196:199], v158 offset:2048
	ds_read_b128 v[200:203], v158 offset:3072
	s_add_u32 s2, s14, 0xfffc0080
	s_addc_u32 s3, s15, -1
	s_cmp_eq_u32 s54, 12
	s_cselect_b32 s23, s25, s3
	s_cselect_b32 s22, s50, s2
	s_cselect_b32 s3, s21, s53
	s_cselect_b32 s2, s51, s52
	v_lshl_add_u64 v[156:157], s[14:15], 0, v[128:129]
	s_add_i32 m0, s37, 0xc000
	ds_read_b128 v[204:207], v159
	ds_read_b128 v[208:211], v159 offset:1024
	ds_read_b128 v[212:215], v159 offset:2048
	ds_read_b128 v[216:219], v159 offset:3072
	ds_read_b128 v[220:223], v159 offset:4096
	ds_read_b128 v[224:227], v159 offset:5120
	ds_read_b128 v[228:231], v159 offset:6144
	ds_read_b128 v[232:235], v159 offset:7168
	global_load_lds_dwordx4 v[156:157], off
	v_lshl_add_u64 v[156:157], s[14:15], 0, v[130:131]
	s_add_i32 m0, s37, 0xe000
	s_nop 0
	global_load_lds_dwordx4 v[156:157], off
	s_waitcnt vmcnt(8)
	s_waitcnt lgkmcnt(0)
	s_barrier
	s_setprio 1
	s_waitcnt lgkmcnt(0)
	v_mfma_f32_16x16x32_bf16 v[112:115], v[136:139], v[204:207], v[112:115]
	v_mfma_f32_16x16x32_bf16 v[108:111], v[166:169], v[204:207], v[108:111]
	v_mfma_f32_16x16x32_bf16 v[104:107], v[136:139], v[212:215], v[104:107]
	v_mfma_f32_16x16x32_bf16 v[100:103], v[166:169], v[212:215], v[100:103]
	v_mfma_f32_16x16x32_bf16 v[92:95], v[136:139], v[220:223], v[92:95]
	v_mfma_f32_16x16x32_bf16 v[84:87], v[166:169], v[220:223], v[84:87]
	v_mfma_f32_16x16x32_bf16 v[76:79], v[136:139], v[228:231], v[76:79]
	v_mfma_f32_16x16x32_bf16 v[68:71], v[166:169], v[228:231], v[68:71]
	v_mfma_f32_16x16x32_bf16 v[112:115], v[162:165], v[208:211], v[112:115]
	v_mfma_f32_16x16x32_bf16 v[108:111], v[178:181], v[208:211], v[108:111]
	v_mfma_f32_16x16x32_bf16 v[104:107], v[162:165], v[216:219], v[104:107]
	v_mfma_f32_16x16x32_bf16 v[100:103], v[178:181], v[216:219], v[100:103]
	v_mfma_f32_16x16x32_bf16 v[92:95], v[162:165], v[224:227], v[92:95]
	v_mfma_f32_16x16x32_bf16 v[84:87], v[178:181], v[224:227], v[84:87]
	v_mfma_f32_16x16x32_bf16 v[76:79], v[162:165], v[232:235], v[76:79]
	v_mfma_f32_16x16x32_bf16 v[68:71], v[178:181], v[232:235], v[68:71]
	v_mfma_f32_16x16x32_bf16 v[124:127], v[184:187], v[204:207], v[124:127]
	v_mfma_f32_16x16x32_bf16 v[120:123], v[196:199], v[204:207], v[120:123]
	v_mfma_f32_16x16x32_bf16 v[116:119], v[184:187], v[212:215], v[116:119]
	v_mfma_f32_16x16x32_bf16 v[96:99], v[196:199], v[212:215], v[96:99]
	v_mfma_f32_16x16x32_bf16 v[88:91], v[184:187], v[220:223], v[88:91]
	v_mfma_f32_16x16x32_bf16 v[80:83], v[196:199], v[220:223], v[80:83]
	v_mfma_f32_16x16x32_bf16 v[72:75], v[184:187], v[228:231], v[72:75]
	v_mfma_f32_16x16x32_bf16 v[64:67], v[196:199], v[228:231], v[64:67]
	v_mfma_f32_16x16x32_bf16 v[124:127], v[188:191], v[208:211], v[124:127]
	v_mfma_f32_16x16x32_bf16 v[120:123], v[200:203], v[208:211], v[120:123]
	v_mfma_f32_16x16x32_bf16 v[116:119], v[188:191], v[216:219], v[116:119]
	v_mfma_f32_16x16x32_bf16 v[96:99], v[200:203], v[216:219], v[96:99]
	v_mfma_f32_16x16x32_bf16 v[88:91], v[188:191], v[224:227], v[88:91]
	v_mfma_f32_16x16x32_bf16 v[80:83], v[200:203], v[224:227], v[80:83]
	v_mfma_f32_16x16x32_bf16 v[72:75], v[188:191], v[232:235], v[72:75]
	v_mfma_f32_16x16x32_bf16 v[64:67], v[200:203], v[232:235], v[64:67]
	s_setprio 0
	s_barrier
	s_add_i32 s55, s46, s34
	v_lshl_add_u64 v[156:157], s[2:3], 0, v[142:143]
	s_mov_b32 m0, s55
	ds_read_b128 v[204:207], v159 offset:16384
	ds_read_b128 v[208:211], v159 offset:17408
	ds_read_b128 v[212:215], v159 offset:18432
	ds_read_b128 v[216:219], v159 offset:19456
	ds_read_b128 v[220:223], v159 offset:20480
	ds_read_b128 v[224:227], v159 offset:21504
	ds_read_b128 v[228:231], v159 offset:22528
	ds_read_b128 v[232:235], v159 offset:23552
	global_load_lds_dwordx4 v[156:157], off
	s_add_i32 m0, s55, 0x2000
	s_add_u32 s56, s2, 0x40000
	v_lshl_add_u64 v[192:193], s[2:3], 0, v[146:147]
	s_addc_u32 s57, s3, 0
	s_add_i32 s55, s47, s34
	global_load_lds_dwordx4 v[192:193], off
	v_lshl_add_u64 v[236:237], s[56:57], 0, v[142:143]
	s_mov_b32 m0, s55
	v_lshl_add_u64 v[238:239], s[22:23], 0, v[144:145]
	global_load_lds_dwordx4 v[236:237], off
	v_lshl_add_u64 v[236:237], s[56:57], 0, v[146:147]
	s_add_i32 m0, s55, 0x2000
	s_nop 0
	global_load_lds_dwordx4 v[236:237], off
	v_lshl_add_u64 v[236:237], s[22:23], 0, v[140:141]
	s_mov_b32 m0, s37
	s_nop 0
	global_load_lds_dwordx4 v[236:237], off
	s_mov_b32 m0, s38
	s_nop 0
	global_load_lds_dwordx4 v[238:239], off
	s_waitcnt vmcnt(8)
	s_waitcnt lgkmcnt(0)
	s_barrier
	s_setprio 1
	s_waitcnt lgkmcnt(0)
	v_mfma_f32_16x16x32_bf16 v[60:63], v[136:139], v[204:207], v[60:63]
	v_mfma_f32_16x16x32_bf16 v[52:55], v[166:169], v[204:207], v[52:55]
	v_mfma_f32_16x16x32_bf16 v[44:47], v[136:139], v[212:215], v[44:47]
	v_mfma_f32_16x16x32_bf16 v[36:39], v[166:169], v[212:215], v[36:39]
	v_mfma_f32_16x16x32_bf16 v[28:31], v[136:139], v[220:223], v[28:31]
	v_mfma_f32_16x16x32_bf16 v[20:23], v[166:169], v[220:223], v[20:23]
	v_mfma_f32_16x16x32_bf16 v[12:15], v[136:139], v[228:231], v[12:15]
	v_mfma_f32_16x16x32_bf16 v[4:7], v[166:169], v[228:231], v[4:7]
	v_mfma_f32_16x16x32_bf16 v[60:63], v[162:165], v[208:211], v[60:63]
	v_mfma_f32_16x16x32_bf16 v[52:55], v[178:181], v[208:211], v[52:55]
	v_mfma_f32_16x16x32_bf16 v[44:47], v[162:165], v[216:219], v[44:47]
	v_mfma_f32_16x16x32_bf16 v[36:39], v[178:181], v[216:219], v[36:39]
	v_mfma_f32_16x16x32_bf16 v[28:31], v[162:165], v[224:227], v[28:31]
	v_mfma_f32_16x16x32_bf16 v[20:23], v[178:181], v[224:227], v[20:23]
	v_mfma_f32_16x16x32_bf16 v[12:15], v[162:165], v[232:235], v[12:15]
	v_mfma_f32_16x16x32_bf16 v[4:7], v[178:181], v[232:235], v[4:7]
	v_mfma_f32_16x16x32_bf16 v[56:59], v[184:187], v[204:207], v[56:59]
	v_mfma_f32_16x16x32_bf16 v[48:51], v[196:199], v[204:207], v[48:51]
	v_mfma_f32_16x16x32_bf16 v[40:43], v[184:187], v[212:215], v[40:43]
	v_mfma_f32_16x16x32_bf16 v[32:35], v[196:199], v[212:215], v[32:35]
	v_mfma_f32_16x16x32_bf16 v[24:27], v[184:187], v[220:223], v[24:27]
	v_mfma_f32_16x16x32_bf16 v[16:19], v[196:199], v[220:223], v[16:19]
	v_mfma_f32_16x16x32_bf16 v[8:11], v[184:187], v[228:231], v[8:11]
	v_mfma_f32_16x16x32_bf16 v[0:3], v[196:199], v[228:231], v[0:3]
	v_mfma_f32_16x16x32_bf16 v[56:59], v[188:191], v[208:211], v[56:59]
	v_mfma_f32_16x16x32_bf16 v[48:51], v[200:203], v[208:211], v[48:51]
	v_mfma_f32_16x16x32_bf16 v[40:43], v[188:191], v[216:219], v[40:43]
	v_mfma_f32_16x16x32_bf16 v[32:35], v[200:203], v[216:219], v[32:35]
	v_mfma_f32_16x16x32_bf16 v[24:27], v[188:191], v[224:227], v[24:27]
	v_mfma_f32_16x16x32_bf16 v[16:19], v[200:203], v[224:227], v[16:19]
	v_mfma_f32_16x16x32_bf16 v[8:11], v[188:191], v[232:235], v[8:11]
	v_mfma_f32_16x16x32_bf16 v[0:3], v[200:203], v[232:235], v[0:3]
	s_setprio 0
	s_barrier
	s_add_i32 s55, 0, 0x18000
	v_add_u32_e32 v161, s55, v151
	s_add_i32 s56, 0, 0x1c000
	ds_read_b128 v[136:139], v161
	ds_read_b128 v[162:165], v161 offset:1024
	ds_read_b128 v[166:169], v161 offset:2048
	ds_read_b128 v[178:181], v161 offset:3072
	v_add_u32_e32 v161, s56, v151
	ds_read_b128 v[184:187], v161
	ds_read_b128 v[188:191], v161 offset:1024
	ds_read_b128 v[196:199], v161 offset:2048
	ds_read_b128 v[200:203], v161 offset:3072
	s_add_u32 s22, s22, 0x40000
	s_addc_u32 s23, s23, 0
	s_mov_b32 m0, s39
	v_lshl_add_u64 v[240:241], s[22:23], 0, v[140:141]
	ds_read_b128 v[204:207], v159 offset:32768
	ds_read_b128 v[208:211], v159 offset:33792
	ds_read_b128 v[212:215], v159 offset:34816
	ds_read_b128 v[216:219], v159 offset:35840
	ds_read_b128 v[220:223], v159 offset:36864
	ds_read_b128 v[224:227], v159 offset:37888
	ds_read_b128 v[228:231], v159 offset:38912
	ds_read_b128 v[232:235], v159 offset:39936
	global_load_lds_dwordx4 v[240:241], off
	v_lshl_add_u64 v[240:241], s[22:23], 0, v[144:145]
	s_mov_b32 m0, s40
	s_nop 0
	global_load_lds_dwordx4 v[240:241], off
	s_waitcnt vmcnt(8)
	s_waitcnt lgkmcnt(0)
	s_barrier
	s_setprio 1
	s_waitcnt lgkmcnt(0)
	v_mfma_f32_16x16x32_bf16 v[112:115], v[136:139], v[204:207], v[112:115]
	v_mfma_f32_16x16x32_bf16 v[108:111], v[166:169], v[204:207], v[108:111]
	v_mfma_f32_16x16x32_bf16 v[104:107], v[136:139], v[212:215], v[104:107]
	v_mfma_f32_16x16x32_bf16 v[100:103], v[166:169], v[212:215], v[100:103]
	v_mfma_f32_16x16x32_bf16 v[92:95], v[136:139], v[220:223], v[92:95]
	v_mfma_f32_16x16x32_bf16 v[84:87], v[166:169], v[220:223], v[84:87]
	v_mfma_f32_16x16x32_bf16 v[76:79], v[136:139], v[228:231], v[76:79]
	v_mfma_f32_16x16x32_bf16 v[68:71], v[166:169], v[228:231], v[68:71]
	v_mfma_f32_16x16x32_bf16 v[112:115], v[162:165], v[208:211], v[112:115]
	v_mfma_f32_16x16x32_bf16 v[108:111], v[178:181], v[208:211], v[108:111]
	v_mfma_f32_16x16x32_bf16 v[104:107], v[162:165], v[216:219], v[104:107]
	v_mfma_f32_16x16x32_bf16 v[100:103], v[178:181], v[216:219], v[100:103]
	v_mfma_f32_16x16x32_bf16 v[92:95], v[162:165], v[224:227], v[92:95]
	v_mfma_f32_16x16x32_bf16 v[84:87], v[178:181], v[224:227], v[84:87]
	v_mfma_f32_16x16x32_bf16 v[76:79], v[162:165], v[232:235], v[76:79]
	v_mfma_f32_16x16x32_bf16 v[68:71], v[178:181], v[232:235], v[68:71]
	v_mfma_f32_16x16x32_bf16 v[124:127], v[184:187], v[204:207], v[124:127]
	v_mfma_f32_16x16x32_bf16 v[120:123], v[196:199], v[204:207], v[120:123]
	v_mfma_f32_16x16x32_bf16 v[116:119], v[184:187], v[212:215], v[116:119]
	v_mfma_f32_16x16x32_bf16 v[96:99], v[196:199], v[212:215], v[96:99]
	v_mfma_f32_16x16x32_bf16 v[88:91], v[184:187], v[220:223], v[88:91]
	v_mfma_f32_16x16x32_bf16 v[80:83], v[196:199], v[220:223], v[80:83]
	v_mfma_f32_16x16x32_bf16 v[72:75], v[184:187], v[228:231], v[72:75]
	v_mfma_f32_16x16x32_bf16 v[64:67], v[196:199], v[228:231], v[64:67]
	v_mfma_f32_16x16x32_bf16 v[124:127], v[188:191], v[208:211], v[124:127]
	v_mfma_f32_16x16x32_bf16 v[120:123], v[200:203], v[208:211], v[120:123]
	v_mfma_f32_16x16x32_bf16 v[116:119], v[188:191], v[216:219], v[116:119]
	v_mfma_f32_16x16x32_bf16 v[96:99], v[200:203], v[216:219], v[96:99]
	v_mfma_f32_16x16x32_bf16 v[88:91], v[188:191], v[224:227], v[88:91]
	v_mfma_f32_16x16x32_bf16 v[80:83], v[200:203], v[224:227], v[80:83]
	v_mfma_f32_16x16x32_bf16 v[72:75], v[188:191], v[232:235], v[72:75]
	v_mfma_f32_16x16x32_bf16 v[64:67], v[200:203], v[232:235], v[64:67]
	s_setprio 0
	s_barrier
	s_add_i32 s22, s55, s34
	v_lshl_add_u64 v[156:157], v[156:157], 0, s[12:13]
	s_mov_b32 m0, s22
	ds_read_b128 v[204:207], v159 offset:49152
	ds_read_b128 v[208:211], v159 offset:50176
	ds_read_b128 v[212:215], v159 offset:51200
	ds_read_b128 v[216:219], v159 offset:52224
	ds_read_b128 v[220:223], v159 offset:53248
	ds_read_b128 v[224:227], v159 offset:54272
	ds_read_b128 v[228:231], v159 offset:55296
	ds_read_b128 v[232:235], v159 offset:56320
	global_load_lds_dwordx4 v[156:157], off
	s_add_i32 m0, s22, 0x2000
	s_add_u32 s2, s2, 0x40080
	v_lshl_add_u64 v[156:157], v[192:193], 0, s[12:13]
	s_addc_u32 s3, s3, 0
	s_add_i32 s22, s56, s34
	global_load_lds_dwordx4 v[156:157], off
	v_lshl_add_u64 v[156:157], s[2:3], 0, v[142:143]
	s_mov_b32 m0, s22
	s_nop 0
	global_load_lds_dwordx4 v[156:157], off
	v_lshl_add_u64 v[156:157], s[2:3], 0, v[146:147]
	s_add_i32 m0, s22, 0x2000
	s_nop 0
	global_load_lds_dwordx4 v[156:157], off
	v_lshl_add_u64 v[156:157], v[236:237], 0, s[12:13]
	s_mov_b32 m0, s42
	s_nop 0
	global_load_lds_dwordx4 v[156:157], off
	v_lshl_add_u64 v[156:157], v[238:239], 0, s[12:13]
	s_mov_b32 m0, s43
	s_nop 0
	global_load_lds_dwordx4 v[156:157], off
	s_waitcnt vmcnt(8)
	s_waitcnt lgkmcnt(0)
	s_barrier
	s_setprio 1
	s_waitcnt lgkmcnt(0)
	v_mfma_f32_16x16x32_bf16 v[60:63], v[136:139], v[204:207], v[60:63]
	v_mfma_f32_16x16x32_bf16 v[52:55], v[166:169], v[204:207], v[52:55]
	v_mfma_f32_16x16x32_bf16 v[44:47], v[136:139], v[212:215], v[44:47]
	v_mfma_f32_16x16x32_bf16 v[36:39], v[166:169], v[212:215], v[36:39]
	v_mfma_f32_16x16x32_bf16 v[28:31], v[136:139], v[220:223], v[28:31]
	v_mfma_f32_16x16x32_bf16 v[20:23], v[166:169], v[220:223], v[20:23]
	v_mfma_f32_16x16x32_bf16 v[12:15], v[136:139], v[228:231], v[12:15]
	v_mfma_f32_16x16x32_bf16 v[4:7], v[166:169], v[228:231], v[4:7]
	v_mfma_f32_16x16x32_bf16 v[60:63], v[162:165], v[208:211], v[60:63]
	v_mfma_f32_16x16x32_bf16 v[52:55], v[178:181], v[208:211], v[52:55]
	v_mfma_f32_16x16x32_bf16 v[44:47], v[162:165], v[216:219], v[44:47]
	v_mfma_f32_16x16x32_bf16 v[36:39], v[178:181], v[216:219], v[36:39]
	v_mfma_f32_16x16x32_bf16 v[28:31], v[162:165], v[224:227], v[28:31]
	v_mfma_f32_16x16x32_bf16 v[20:23], v[178:181], v[224:227], v[20:23]
	v_mfma_f32_16x16x32_bf16 v[12:15], v[162:165], v[232:235], v[12:15]
	v_mfma_f32_16x16x32_bf16 v[4:7], v[178:181], v[232:235], v[4:7]
	v_mfma_f32_16x16x32_bf16 v[56:59], v[184:187], v[204:207], v[56:59]
	v_mfma_f32_16x16x32_bf16 v[48:51], v[196:199], v[204:207], v[48:51]
	v_mfma_f32_16x16x32_bf16 v[40:43], v[184:187], v[212:215], v[40:43]
	v_mfma_f32_16x16x32_bf16 v[32:35], v[196:199], v[212:215], v[32:35]
	v_mfma_f32_16x16x32_bf16 v[24:27], v[184:187], v[220:223], v[24:27]
	v_mfma_f32_16x16x32_bf16 v[16:19], v[196:199], v[220:223], v[16:19]
	v_mfma_f32_16x16x32_bf16 v[8:11], v[184:187], v[228:231], v[8:11]
	v_mfma_f32_16x16x32_bf16 v[0:3], v[196:199], v[228:231], v[0:3]
	v_mfma_f32_16x16x32_bf16 v[56:59], v[188:191], v[208:211], v[56:59]
	v_mfma_f32_16x16x32_bf16 v[48:51], v[200:203], v[208:211], v[48:51]
	v_mfma_f32_16x16x32_bf16 v[40:43], v[188:191], v[216:219], v[40:43]
	v_mfma_f32_16x16x32_bf16 v[32:35], v[200:203], v[216:219], v[32:35]
	v_mfma_f32_16x16x32_bf16 v[24:27], v[188:191], v[224:227], v[24:27]
	v_mfma_f32_16x16x32_bf16 v[16:19], v[200:203], v[224:227], v[16:19]
	v_mfma_f32_16x16x32_bf16 v[8:11], v[188:191], v[232:235], v[8:11]
	v_mfma_f32_16x16x32_bf16 v[0:3], v[200:203], v[232:235], v[0:3]
	s_setprio 0
	s_barrier
	s_add_i32 s54, s54, 2
	s_add_u32 s14, s14, 0x100
	s_addc_u32 s15, s15, 0
	s_add_u32 s52, s52, 0x100
	s_addc_u32 s53, s53, 0
	s_cmp_gt_u32 s54, 13
	s_cbranch_scc0 .LBB0_809

.LBB0_890:
	s_add_u32 s14, s14, 0xb0080
	s_addc_u32 s15, s15, 0
	s_add_u32 s53, s2, 0x100
	s_addc_u32 s54, s3, 0
	s_mov_b32 s55, -2
	s_waitcnt lgkmcnt(0)
	s_waitcnt vmcnt(0)
	ds_read_b128 v[128:131], v165
	ds_read_b128 v[132:135], v165 offset:1024
	ds_read_b128 v[136:139], v165 offset:2048
	ds_read_b128 v[156:159], v165 offset:3072
	ds_read_b128 v[172:175], v166
	ds_read_b128 v[176:179], v166 offset:1024
	ds_read_b128 v[180:183], v166 offset:2048
	ds_read_b128 v[184:187], v166 offset:3072
	s_add_u32 s2, s14, 0xfff50080
	s_addc_u32 s3, s15, -1
	s_cmp_eq_u32 s55, 40
	s_cselect_b32 s23, s1, s3
	s_cselect_b32 s22, s0, s2
	s_cselect_b32 s3, s21, s54
	s_cselect_b32 s2, s20, s53
	v_lshl_add_u64 v[160:161], s[14:15], 0, v[140:141]
	s_add_i32 m0, s27, 0xc000
	ds_read_b128 v[188:191], v167
	ds_read_b128 v[196:199], v167 offset:1024
	ds_read_b128 v[200:203], v167 offset:2048
	ds_read_b128 v[204:207], v167 offset:3072
	ds_read_b128 v[208:211], v167 offset:4096
	ds_read_b128 v[212:215], v167 offset:5120
	ds_read_b128 v[216:219], v167 offset:6144
	ds_read_b128 v[220:223], v167 offset:7168
	global_load_lds_dwordx4 v[160:161], off
	v_lshl_add_u64 v[160:161], s[14:15], 0, v[142:143]
	s_add_i32 m0, s27, 0xe000
	s_nop 0
	global_load_lds_dwordx4 v[160:161], off
	s_waitcnt vmcnt(8)
	s_waitcnt lgkmcnt(0)
	s_barrier
	s_setprio 1
	s_waitcnt lgkmcnt(0)
	v_mfma_f32_16x16x32_bf16 v[124:127], v[128:131], v[188:191], 0
	v_mfma_f32_16x16x32_bf16 v[120:123], v[136:139], v[188:191], 0
	v_mfma_f32_16x16x32_bf16 v[108:111], v[128:131], v[200:203], 0
	v_mfma_f32_16x16x32_bf16 v[104:107], v[136:139], v[200:203], 0
	v_mfma_f32_16x16x32_bf16 v[92:95], v[128:131], v[208:211], 0
	v_mfma_f32_16x16x32_bf16 v[88:91], v[136:139], v[208:211], 0
	v_mfma_f32_16x16x32_bf16 v[76:79], v[128:131], v[216:219], 0
	v_mfma_f32_16x16x32_bf16 v[72:75], v[136:139], v[216:219], 0
	v_mfma_f32_16x16x32_bf16 v[124:127], v[132:135], v[196:199], v[124:127]
	v_mfma_f32_16x16x32_bf16 v[120:123], v[156:159], v[196:199], v[120:123]
	v_mfma_f32_16x16x32_bf16 v[108:111], v[132:135], v[204:207], v[108:111]
	v_mfma_f32_16x16x32_bf16 v[104:107], v[156:159], v[204:207], v[104:107]
	v_mfma_f32_16x16x32_bf16 v[92:95], v[132:135], v[212:215], v[92:95]
	v_mfma_f32_16x16x32_bf16 v[88:91], v[156:159], v[212:215], v[88:91]
	v_mfma_f32_16x16x32_bf16 v[76:79], v[132:135], v[220:223], v[76:79]
	v_mfma_f32_16x16x32_bf16 v[72:75], v[156:159], v[220:223], v[72:75]
	v_mfma_f32_16x16x32_bf16 v[116:119], v[172:175], v[188:191], 0
	v_mfma_f32_16x16x32_bf16 v[112:115], v[180:183], v[188:191], 0
	v_mfma_f32_16x16x32_bf16 v[100:103], v[172:175], v[200:203], 0
	v_mfma_f32_16x16x32_bf16 v[96:99], v[180:183], v[200:203], 0
	v_mfma_f32_16x16x32_bf16 v[84:87], v[172:175], v[208:211], 0
	v_mfma_f32_16x16x32_bf16 v[80:83], v[180:183], v[208:211], 0
	v_mfma_f32_16x16x32_bf16 v[68:71], v[172:175], v[216:219], 0
	v_mfma_f32_16x16x32_bf16 v[64:67], v[180:183], v[216:219], 0
	v_mfma_f32_16x16x32_bf16 v[116:119], v[176:179], v[196:199], v[116:119]
	v_mfma_f32_16x16x32_bf16 v[112:115], v[184:187], v[196:199], v[112:115]
	v_mfma_f32_16x16x32_bf16 v[100:103], v[176:179], v[204:207], v[100:103]
	v_mfma_f32_16x16x32_bf16 v[96:99], v[184:187], v[204:207], v[96:99]
	v_mfma_f32_16x16x32_bf16 v[84:87], v[176:179], v[212:215], v[84:87]
	v_mfma_f32_16x16x32_bf16 v[80:83], v[184:187], v[212:215], v[80:83]
	v_mfma_f32_16x16x32_bf16 v[68:71], v[176:179], v[220:223], v[68:71]
	v_mfma_f32_16x16x32_bf16 v[64:67], v[184:187], v[220:223], v[64:67]
	s_setprio 0
	s_barrier
	s_add_i32 s56, s43, s26
	v_lshl_add_u64 v[160:161], s[2:3], 0, v[150:151]
	s_mov_b32 m0, s56
	ds_read_b128 v[188:191], v167 offset:16384
	ds_read_b128 v[196:199], v167 offset:17408
	ds_read_b128 v[200:203], v167 offset:18432
	ds_read_b128 v[204:207], v167 offset:19456
	ds_read_b128 v[208:211], v167 offset:20480
	ds_read_b128 v[212:215], v167 offset:21504
	ds_read_b128 v[216:219], v167 offset:22528
	ds_read_b128 v[220:223], v167 offset:23552
	global_load_lds_dwordx4 v[160:161], off
	s_add_i32 m0, s56, 0x2000
	s_add_u32 s56, s2, 0xb0000
	v_lshl_add_u64 v[192:193], s[2:3], 0, v[154:155]
	s_addc_u32 s57, s3, 0
	s_add_i32 s58, s44, s26
	global_load_lds_dwordx4 v[192:193], off
	v_lshl_add_u64 v[224:225], s[56:57], 0, v[150:151]
	s_mov_b32 m0, s58
	v_lshl_add_u64 v[226:227], s[22:23], 0, v[152:153]
	global_load_lds_dwordx4 v[224:225], off
	v_lshl_add_u64 v[224:225], s[56:57], 0, v[154:155]
	s_add_i32 m0, s58, 0x2000
	s_nop 0
	global_load_lds_dwordx4 v[224:225], off
	v_lshl_add_u64 v[224:225], s[22:23], 0, v[148:149]
	s_mov_b32 m0, s27
	s_nop 0
	global_load_lds_dwordx4 v[224:225], off
	s_mov_b32 m0, s28
	s_nop 0
	global_load_lds_dwordx4 v[226:227], off
	s_waitcnt vmcnt(8)
	s_waitcnt lgkmcnt(0)
	s_barrier
	s_setprio 1
	s_waitcnt lgkmcnt(0)
	v_mfma_f32_16x16x32_bf16 v[60:63], v[128:131], v[188:191], 0
	v_mfma_f32_16x16x32_bf16 v[56:59], v[136:139], v[188:191], 0
	v_mfma_f32_16x16x32_bf16 v[44:47], v[128:131], v[200:203], 0
	v_mfma_f32_16x16x32_bf16 v[40:43], v[136:139], v[200:203], 0
	v_mfma_f32_16x16x32_bf16 v[28:31], v[128:131], v[208:211], 0
	v_mfma_f32_16x16x32_bf16 v[24:27], v[136:139], v[208:211], 0
	v_mfma_f32_16x16x32_bf16 v[12:15], v[128:131], v[216:219], 0
	v_mfma_f32_16x16x32_bf16 v[8:11], v[136:139], v[216:219], 0
	v_mfma_f32_16x16x32_bf16 v[60:63], v[132:135], v[196:199], v[60:63]
	v_mfma_f32_16x16x32_bf16 v[56:59], v[156:159], v[196:199], v[56:59]
	v_mfma_f32_16x16x32_bf16 v[44:47], v[132:135], v[204:207], v[44:47]
	v_mfma_f32_16x16x32_bf16 v[40:43], v[156:159], v[204:207], v[40:43]
	v_mfma_f32_16x16x32_bf16 v[28:31], v[132:135], v[212:215], v[28:31]
	v_mfma_f32_16x16x32_bf16 v[24:27], v[156:159], v[212:215], v[24:27]
	v_mfma_f32_16x16x32_bf16 v[12:15], v[132:135], v[220:223], v[12:15]
	v_mfma_f32_16x16x32_bf16 v[8:11], v[156:159], v[220:223], v[8:11]
	v_mfma_f32_16x16x32_bf16 v[52:55], v[172:175], v[188:191], 0
	v_mfma_f32_16x16x32_bf16 v[48:51], v[180:183], v[188:191], 0
	v_mfma_f32_16x16x32_bf16 v[36:39], v[172:175], v[200:203], 0
	v_mfma_f32_16x16x32_bf16 v[32:35], v[180:183], v[200:203], 0
	v_mfma_f32_16x16x32_bf16 v[20:23], v[172:175], v[208:211], 0
	v_mfma_f32_16x16x32_bf16 v[16:19], v[180:183], v[208:211], 0
	v_mfma_f32_16x16x32_bf16 v[4:7], v[172:175], v[216:219], 0
	v_mfma_f32_16x16x32_bf16 v[0:3], v[180:183], v[216:219], 0
	v_mfma_f32_16x16x32_bf16 v[52:55], v[176:179], v[196:199], v[52:55]
	v_mfma_f32_16x16x32_bf16 v[48:51], v[184:187], v[196:199], v[48:51]
	v_mfma_f32_16x16x32_bf16 v[36:39], v[176:179], v[204:207], v[36:39]
	v_mfma_f32_16x16x32_bf16 v[32:35], v[184:187], v[204:207], v[32:35]
	v_mfma_f32_16x16x32_bf16 v[20:23], v[176:179], v[212:215], v[20:23]
	v_mfma_f32_16x16x32_bf16 v[16:19], v[184:187], v[212:215], v[16:19]
	v_mfma_f32_16x16x32_bf16 v[4:7], v[176:179], v[220:223], v[4:7]
	v_mfma_f32_16x16x32_bf16 v[0:3], v[184:187], v[220:223], v[0:3]
	s_setprio 0
	s_barrier
	s_add_i32 s56, 0, 0x18000
	s_add_i32 s57, 0, 0x1c000
	v_add_u32_e32 v156, s56, v162
	v_add_u32_e32 v169, s57, v162
	ds_read_b128 v[128:131], v156
	ds_read_b128 v[132:135], v156 offset:1024
	ds_read_b128 v[136:139], v156 offset:2048
	ds_read_b128 v[156:159], v156 offset:3072
	ds_read_b128 v[172:175], v169
	ds_read_b128 v[176:179], v169 offset:1024
	ds_read_b128 v[180:183], v169 offset:2048
	ds_read_b128 v[184:187], v169 offset:3072
	s_add_u32 s22, s22, 0xb0000
	s_addc_u32 s23, s23, 0
	s_mov_b32 m0, s29
	v_lshl_add_u64 v[228:229], s[22:23], 0, v[148:149]
	ds_read_b128 v[188:191], v167 offset:32768
	ds_read_b128 v[196:199], v167 offset:33792
	ds_read_b128 v[200:203], v167 offset:34816
	ds_read_b128 v[204:207], v167 offset:35840
	ds_read_b128 v[208:211], v167 offset:36864
	ds_read_b128 v[212:215], v167 offset:37888
	ds_read_b128 v[216:219], v167 offset:38912
	ds_read_b128 v[220:223], v167 offset:39936
	global_load_lds_dwordx4 v[228:229], off
	v_lshl_add_u64 v[228:229], s[22:23], 0, v[152:153]
	s_mov_b32 m0, s30
	s_nop 0
	global_load_lds_dwordx4 v[228:229], off
	s_waitcnt vmcnt(8)
	s_waitcnt lgkmcnt(0)
	s_barrier
	s_setprio 1
	s_waitcnt lgkmcnt(0)
	v_mfma_f32_16x16x32_bf16 v[124:127], v[128:131], v[188:191], v[124:127]
	v_mfma_f32_16x16x32_bf16 v[120:123], v[136:139], v[188:191], v[120:123]
	v_mfma_f32_16x16x32_bf16 v[108:111], v[128:131], v[200:203], v[108:111]
	v_mfma_f32_16x16x32_bf16 v[104:107], v[136:139], v[200:203], v[104:107]
	v_mfma_f32_16x16x32_bf16 v[92:95], v[128:131], v[208:211], v[92:95]
	v_mfma_f32_16x16x32_bf16 v[88:91], v[136:139], v[208:211], v[88:91]
	v_mfma_f32_16x16x32_bf16 v[76:79], v[128:131], v[216:219], v[76:79]
	v_mfma_f32_16x16x32_bf16 v[72:75], v[136:139], v[216:219], v[72:75]
	v_mfma_f32_16x16x32_bf16 v[124:127], v[132:135], v[196:199], v[124:127]
	v_mfma_f32_16x16x32_bf16 v[120:123], v[156:159], v[196:199], v[120:123]
	v_mfma_f32_16x16x32_bf16 v[108:111], v[132:135], v[204:207], v[108:111]
	v_mfma_f32_16x16x32_bf16 v[104:107], v[156:159], v[204:207], v[104:107]
	v_mfma_f32_16x16x32_bf16 v[92:95], v[132:135], v[212:215], v[92:95]
	v_mfma_f32_16x16x32_bf16 v[88:91], v[156:159], v[212:215], v[88:91]
	v_mfma_f32_16x16x32_bf16 v[76:79], v[132:135], v[220:223], v[76:79]
	v_mfma_f32_16x16x32_bf16 v[72:75], v[156:159], v[220:223], v[72:75]
	v_mfma_f32_16x16x32_bf16 v[116:119], v[172:175], v[188:191], v[116:119]
	v_mfma_f32_16x16x32_bf16 v[112:115], v[180:183], v[188:191], v[112:115]
	v_mfma_f32_16x16x32_bf16 v[100:103], v[172:175], v[200:203], v[100:103]
	v_mfma_f32_16x16x32_bf16 v[96:99], v[180:183], v[200:203], v[96:99]
	v_mfma_f32_16x16x32_bf16 v[84:87], v[172:175], v[208:211], v[84:87]
	v_mfma_f32_16x16x32_bf16 v[80:83], v[180:183], v[208:211], v[80:83]
	v_mfma_f32_16x16x32_bf16 v[68:71], v[172:175], v[216:219], v[68:71]
	v_mfma_f32_16x16x32_bf16 v[64:67], v[180:183], v[216:219], v[64:67]
	v_mfma_f32_16x16x32_bf16 v[116:119], v[176:179], v[196:199], v[116:119]
	v_mfma_f32_16x16x32_bf16 v[112:115], v[184:187], v[196:199], v[112:115]
	v_mfma_f32_16x16x32_bf16 v[100:103], v[176:179], v[204:207], v[100:103]
	v_mfma_f32_16x16x32_bf16 v[96:99], v[184:187], v[204:207], v[96:99]
	v_mfma_f32_16x16x32_bf16 v[84:87], v[176:179], v[212:215], v[84:87]
	v_mfma_f32_16x16x32_bf16 v[80:83], v[184:187], v[212:215], v[80:83]
	v_mfma_f32_16x16x32_bf16 v[68:71], v[176:179], v[220:223], v[68:71]
	v_mfma_f32_16x16x32_bf16 v[64:67], v[184:187], v[220:223], v[64:67]
	s_setprio 0
	s_barrier
	s_add_i32 s22, s56, s26
	v_lshl_add_u64 v[160:161], v[160:161], 0, s[12:13]
	s_mov_b32 m0, s22
	ds_read_b128 v[188:191], v167 offset:49152
	ds_read_b128 v[196:199], v167 offset:50176
	ds_read_b128 v[200:203], v167 offset:51200
	ds_read_b128 v[204:207], v167 offset:52224
	ds_read_b128 v[208:211], v167 offset:53248
	ds_read_b128 v[212:215], v167 offset:54272
	ds_read_b128 v[216:219], v167 offset:55296
	ds_read_b128 v[220:223], v167 offset:56320
	global_load_lds_dwordx4 v[160:161], off
	s_add_i32 m0, s22, 0x2000
	s_add_u32 s2, s2, 0xb0080
	v_lshl_add_u64 v[160:161], v[192:193], 0, s[12:13]
	s_addc_u32 s3, s3, 0
	s_add_i32 s22, s57, s26
	global_load_lds_dwordx4 v[160:161], off
	v_lshl_add_u64 v[160:161], s[2:3], 0, v[150:151]
	s_mov_b32 m0, s22
	s_nop 0
	global_load_lds_dwordx4 v[160:161], off
	v_lshl_add_u64 v[160:161], s[2:3], 0, v[154:155]
	s_add_i32 m0, s22, 0x2000
	s_nop 0
	global_load_lds_dwordx4 v[160:161], off
	v_lshl_add_u64 v[160:161], v[224:225], 0, s[12:13]
	s_mov_b32 m0, s36
	s_nop 0
	global_load_lds_dwordx4 v[160:161], off
	v_lshl_add_u64 v[160:161], v[226:227], 0, s[12:13]
	s_mov_b32 m0, s37
	s_nop 0
	global_load_lds_dwordx4 v[160:161], off
	s_waitcnt vmcnt(8)
	s_waitcnt lgkmcnt(0)
	s_barrier
	s_setprio 1
	s_waitcnt lgkmcnt(0)
	v_mfma_f32_16x16x32_bf16 v[60:63], v[128:131], v[188:191], v[60:63]
	v_mfma_f32_16x16x32_bf16 v[56:59], v[136:139], v[188:191], v[56:59]
	v_mfma_f32_16x16x32_bf16 v[44:47], v[128:131], v[200:203], v[44:47]
	v_mfma_f32_16x16x32_bf16 v[40:43], v[136:139], v[200:203], v[40:43]
	v_mfma_f32_16x16x32_bf16 v[28:31], v[128:131], v[208:211], v[28:31]
	v_mfma_f32_16x16x32_bf16 v[24:27], v[136:139], v[208:211], v[24:27]
	v_mfma_f32_16x16x32_bf16 v[12:15], v[128:131], v[216:219], v[12:15]
	v_mfma_f32_16x16x32_bf16 v[8:11], v[136:139], v[216:219], v[8:11]
	v_mfma_f32_16x16x32_bf16 v[60:63], v[132:135], v[196:199], v[60:63]
	v_mfma_f32_16x16x32_bf16 v[56:59], v[156:159], v[196:199], v[56:59]
	v_mfma_f32_16x16x32_bf16 v[44:47], v[132:135], v[204:207], v[44:47]
	v_mfma_f32_16x16x32_bf16 v[40:43], v[156:159], v[204:207], v[40:43]
	v_mfma_f32_16x16x32_bf16 v[28:31], v[132:135], v[212:215], v[28:31]
	v_mfma_f32_16x16x32_bf16 v[24:27], v[156:159], v[212:215], v[24:27]
	v_mfma_f32_16x16x32_bf16 v[12:15], v[132:135], v[220:223], v[12:15]
	v_mfma_f32_16x16x32_bf16 v[8:11], v[156:159], v[220:223], v[8:11]
	v_mfma_f32_16x16x32_bf16 v[52:55], v[172:175], v[188:191], v[52:55]
	v_mfma_f32_16x16x32_bf16 v[48:51], v[180:183], v[188:191], v[48:51]
	v_mfma_f32_16x16x32_bf16 v[36:39], v[172:175], v[200:203], v[36:39]
	v_mfma_f32_16x16x32_bf16 v[32:35], v[180:183], v[200:203], v[32:35]
	v_mfma_f32_16x16x32_bf16 v[20:23], v[172:175], v[208:211], v[20:23]
	v_mfma_f32_16x16x32_bf16 v[16:19], v[180:183], v[208:211], v[16:19]
	v_mfma_f32_16x16x32_bf16 v[4:7], v[172:175], v[216:219], v[4:7]
	v_mfma_f32_16x16x32_bf16 v[0:3], v[180:183], v[216:219], v[0:3]
	v_mfma_f32_16x16x32_bf16 v[52:55], v[176:179], v[196:199], v[52:55]
	v_mfma_f32_16x16x32_bf16 v[48:51], v[184:187], v[196:199], v[48:51]
	v_mfma_f32_16x16x32_bf16 v[36:39], v[176:179], v[204:207], v[36:39]
	v_mfma_f32_16x16x32_bf16 v[32:35], v[184:187], v[204:207], v[32:35]
	v_mfma_f32_16x16x32_bf16 v[20:23], v[176:179], v[212:215], v[20:23]
	v_mfma_f32_16x16x32_bf16 v[16:19], v[184:187], v[212:215], v[16:19]
	v_mfma_f32_16x16x32_bf16 v[4:7], v[176:179], v[220:223], v[4:7]
	v_mfma_f32_16x16x32_bf16 v[0:3], v[184:187], v[220:223], v[0:3]
	s_setprio 0
	s_barrier
	s_add_i32 s55, s55, 2
	s_add_u32 s14, s14, 0x100
	s_addc_u32 s15, s15, 0
	s_add_u32 s53, s53, 0x100
	s_addc_u32 s54, s54, 0
	s_cmp_gt_u32 s55, 41
	s_cbranch_scc1 .Lgemm_kdone_6
.LBB0_891:
	ds_read_b128 v[128:131], v165
	ds_read_b128 v[132:135], v165 offset:1024
	ds_read_b128 v[136:139], v165 offset:2048
	ds_read_b128 v[156:159], v165 offset:3072
	ds_read_b128 v[172:175], v166
	ds_read_b128 v[176:179], v166 offset:1024
	ds_read_b128 v[180:183], v166 offset:2048
	ds_read_b128 v[184:187], v166 offset:3072
	s_add_u32 s2, s14, 0xfff50080
	s_addc_u32 s3, s15, -1
	s_cmp_eq_u32 s55, 40
	s_cselect_b32 s23, s1, s3
	s_cselect_b32 s22, s0, s2
	s_cselect_b32 s3, s21, s54
	s_cselect_b32 s2, s20, s53
	v_lshl_add_u64 v[160:161], s[14:15], 0, v[140:141]
	s_add_i32 m0, s27, 0xc000
	ds_read_b128 v[188:191], v167
	ds_read_b128 v[196:199], v167 offset:1024
	ds_read_b128 v[200:203], v167 offset:2048
	ds_read_b128 v[204:207], v167 offset:3072
	ds_read_b128 v[208:211], v167 offset:4096
	ds_read_b128 v[212:215], v167 offset:5120
	ds_read_b128 v[216:219], v167 offset:6144
	ds_read_b128 v[220:223], v167 offset:7168
	global_load_lds_dwordx4 v[160:161], off
	v_lshl_add_u64 v[160:161], s[14:15], 0, v[142:143]
	s_add_i32 m0, s27, 0xe000
	s_nop 0
	global_load_lds_dwordx4 v[160:161], off
	s_waitcnt vmcnt(8)
	s_waitcnt lgkmcnt(0)
	s_barrier
	s_setprio 1
	s_waitcnt lgkmcnt(0)
	v_mfma_f32_16x16x32_bf16 v[124:127], v[128:131], v[188:191], v[124:127]
	v_mfma_f32_16x16x32_bf16 v[120:123], v[136:139], v[188:191], v[120:123]
	v_mfma_f32_16x16x32_bf16 v[108:111], v[128:131], v[200:203], v[108:111]
	v_mfma_f32_16x16x32_bf16 v[104:107], v[136:139], v[200:203], v[104:107]
	v_mfma_f32_16x16x32_bf16 v[92:95], v[128:131], v[208:211], v[92:95]
	v_mfma_f32_16x16x32_bf16 v[88:91], v[136:139], v[208:211], v[88:91]
	v_mfma_f32_16x16x32_bf16 v[76:79], v[128:131], v[216:219], v[76:79]
	v_mfma_f32_16x16x32_bf16 v[72:75], v[136:139], v[216:219], v[72:75]
	v_mfma_f32_16x16x32_bf16 v[124:127], v[132:135], v[196:199], v[124:127]
	v_mfma_f32_16x16x32_bf16 v[120:123], v[156:159], v[196:199], v[120:123]
	v_mfma_f32_16x16x32_bf16 v[108:111], v[132:135], v[204:207], v[108:111]
	v_mfma_f32_16x16x32_bf16 v[104:107], v[156:159], v[204:207], v[104:107]
	v_mfma_f32_16x16x32_bf16 v[92:95], v[132:135], v[212:215], v[92:95]
	v_mfma_f32_16x16x32_bf16 v[88:91], v[156:159], v[212:215], v[88:91]
	v_mfma_f32_16x16x32_bf16 v[76:79], v[132:135], v[220:223], v[76:79]
	v_mfma_f32_16x16x32_bf16 v[72:75], v[156:159], v[220:223], v[72:75]
	v_mfma_f32_16x16x32_bf16 v[116:119], v[172:175], v[188:191], v[116:119]
	v_mfma_f32_16x16x32_bf16 v[112:115], v[180:183], v[188:191], v[112:115]
	v_mfma_f32_16x16x32_bf16 v[100:103], v[172:175], v[200:203], v[100:103]
	v_mfma_f32_16x16x32_bf16 v[96:99], v[180:183], v[200:203], v[96:99]
	v_mfma_f32_16x16x32_bf16 v[84:87], v[172:175], v[208:211], v[84:87]
	v_mfma_f32_16x16x32_bf16 v[80:83], v[180:183], v[208:211], v[80:83]
	v_mfma_f32_16x16x32_bf16 v[68:71], v[172:175], v[216:219], v[68:71]
	v_mfma_f32_16x16x32_bf16 v[64:67], v[180:183], v[216:219], v[64:67]
	v_mfma_f32_16x16x32_bf16 v[116:119], v[176:179], v[196:199], v[116:119]
	v_mfma_f32_16x16x32_bf16 v[112:115], v[184:187], v[196:199], v[112:115]
	v_mfma_f32_16x16x32_bf16 v[100:103], v[176:179], v[204:207], v[100:103]
	v_mfma_f32_16x16x32_bf16 v[96:99], v[184:187], v[204:207], v[96:99]
	v_mfma_f32_16x16x32_bf16 v[84:87], v[176:179], v[212:215], v[84:87]
	v_mfma_f32_16x16x32_bf16 v[80:83], v[184:187], v[212:215], v[80:83]
	v_mfma_f32_16x16x32_bf16 v[68:71], v[176:179], v[220:223], v[68:71]
	v_mfma_f32_16x16x32_bf16 v[64:67], v[184:187], v[220:223], v[64:67]
	s_setprio 0
	s_barrier
	s_add_i32 s56, s43, s26
	v_lshl_add_u64 v[160:161], s[2:3], 0, v[150:151]
	s_mov_b32 m0, s56
	ds_read_b128 v[188:191], v167 offset:16384
	ds_read_b128 v[196:199], v167 offset:17408
	ds_read_b128 v[200:203], v167 offset:18432
	ds_read_b128 v[204:207], v167 offset:19456
	ds_read_b128 v[208:211], v167 offset:20480
	ds_read_b128 v[212:215], v167 offset:21504
	ds_read_b128 v[216:219], v167 offset:22528
	ds_read_b128 v[220:223], v167 offset:23552
	global_load_lds_dwordx4 v[160:161], off
	s_add_i32 m0, s56, 0x2000
	s_add_u32 s56, s2, 0xb0000
	v_lshl_add_u64 v[192:193], s[2:3], 0, v[154:155]
	s_addc_u32 s57, s3, 0
	s_add_i32 s58, s44, s26
	global_load_lds_dwordx4 v[192:193], off
	v_lshl_add_u64 v[224:225], s[56:57], 0, v[150:151]
	s_mov_b32 m0, s58
	v_lshl_add_u64 v[226:227], s[22:23], 0, v[152:153]
	global_load_lds_dwordx4 v[224:225], off
	v_lshl_add_u64 v[224:225], s[56:57], 0, v[154:155]
	s_add_i32 m0, s58, 0x2000
	s_nop 0
	global_load_lds_dwordx4 v[224:225], off
	v_lshl_add_u64 v[224:225], s[22:23], 0, v[148:149]
	s_mov_b32 m0, s27
	s_nop 0
	global_load_lds_dwordx4 v[224:225], off
	s_mov_b32 m0, s28
	s_nop 0
	global_load_lds_dwordx4 v[226:227], off
	s_waitcnt vmcnt(8)
	s_waitcnt lgkmcnt(0)
	s_barrier
	s_setprio 1
	s_waitcnt lgkmcnt(0)
	v_mfma_f32_16x16x32_bf16 v[60:63], v[128:131], v[188:191], v[60:63]
	v_mfma_f32_16x16x32_bf16 v[56:59], v[136:139], v[188:191], v[56:59]
	v_mfma_f32_16x16x32_bf16 v[44:47], v[128:131], v[200:203], v[44:47]
	v_mfma_f32_16x16x32_bf16 v[40:43], v[136:139], v[200:203], v[40:43]
	v_mfma_f32_16x16x32_bf16 v[28:31], v[128:131], v[208:211], v[28:31]
	v_mfma_f32_16x16x32_bf16 v[24:27], v[136:139], v[208:211], v[24:27]
	v_mfma_f32_16x16x32_bf16 v[12:15], v[128:131], v[216:219], v[12:15]
	v_mfma_f32_16x16x32_bf16 v[8:11], v[136:139], v[216:219], v[8:11]
	v_mfma_f32_16x16x32_bf16 v[60:63], v[132:135], v[196:199], v[60:63]
	v_mfma_f32_16x16x32_bf16 v[56:59], v[156:159], v[196:199], v[56:59]
	v_mfma_f32_16x16x32_bf16 v[44:47], v[132:135], v[204:207], v[44:47]
	v_mfma_f32_16x16x32_bf16 v[40:43], v[156:159], v[204:207], v[40:43]
	v_mfma_f32_16x16x32_bf16 v[28:31], v[132:135], v[212:215], v[28:31]
	v_mfma_f32_16x16x32_bf16 v[24:27], v[156:159], v[212:215], v[24:27]
	v_mfma_f32_16x16x32_bf16 v[12:15], v[132:135], v[220:223], v[12:15]
	v_mfma_f32_16x16x32_bf16 v[8:11], v[156:159], v[220:223], v[8:11]
	v_mfma_f32_16x16x32_bf16 v[52:55], v[172:175], v[188:191], v[52:55]
	v_mfma_f32_16x16x32_bf16 v[48:51], v[180:183], v[188:191], v[48:51]
	v_mfma_f32_16x16x32_bf16 v[36:39], v[172:175], v[200:203], v[36:39]
	v_mfma_f32_16x16x32_bf16 v[32:35], v[180:183], v[200:203], v[32:35]
	v_mfma_f32_16x16x32_bf16 v[20:23], v[172:175], v[208:211], v[20:23]
	v_mfma_f32_16x16x32_bf16 v[16:19], v[180:183], v[208:211], v[16:19]
	v_mfma_f32_16x16x32_bf16 v[4:7], v[172:175], v[216:219], v[4:7]
	v_mfma_f32_16x16x32_bf16 v[0:3], v[180:183], v[216:219], v[0:3]
	v_mfma_f32_16x16x32_bf16 v[52:55], v[176:179], v[196:199], v[52:55]
	v_mfma_f32_16x16x32_bf16 v[48:51], v[184:187], v[196:199], v[48:51]
	v_mfma_f32_16x16x32_bf16 v[36:39], v[176:179], v[204:207], v[36:39]
	v_mfma_f32_16x16x32_bf16 v[32:35], v[184:187], v[204:207], v[32:35]
	v_mfma_f32_16x16x32_bf16 v[20:23], v[176:179], v[212:215], v[20:23]
	v_mfma_f32_16x16x32_bf16 v[16:19], v[184:187], v[212:215], v[16:19]
	v_mfma_f32_16x16x32_bf16 v[4:7], v[176:179], v[220:223], v[4:7]
	v_mfma_f32_16x16x32_bf16 v[0:3], v[184:187], v[220:223], v[0:3]
	s_setprio 0
	s_barrier
	s_add_i32 s56, 0, 0x18000
	s_add_i32 s57, 0, 0x1c000
	v_add_u32_e32 v156, s56, v162
	v_add_u32_e32 v169, s57, v162
	ds_read_b128 v[128:131], v156
	ds_read_b128 v[132:135], v156 offset:1024
	ds_read_b128 v[136:139], v156 offset:2048
	ds_read_b128 v[156:159], v156 offset:3072
	ds_read_b128 v[172:175], v169
	ds_read_b128 v[176:179], v169 offset:1024
	ds_read_b128 v[180:183], v169 offset:2048
	ds_read_b128 v[184:187], v169 offset:3072
	s_add_u32 s22, s22, 0xb0000
	s_addc_u32 s23, s23, 0
	s_mov_b32 m0, s29
	v_lshl_add_u64 v[228:229], s[22:23], 0, v[148:149]
	ds_read_b128 v[188:191], v167 offset:32768
	ds_read_b128 v[196:199], v167 offset:33792
	ds_read_b128 v[200:203], v167 offset:34816
	ds_read_b128 v[204:207], v167 offset:35840
	ds_read_b128 v[208:211], v167 offset:36864
	ds_read_b128 v[212:215], v167 offset:37888
	ds_read_b128 v[216:219], v167 offset:38912
	ds_read_b128 v[220:223], v167 offset:39936
	global_load_lds_dwordx4 v[228:229], off
	v_lshl_add_u64 v[228:229], s[22:23], 0, v[152:153]
	s_mov_b32 m0, s30
	s_nop 0
	global_load_lds_dwordx4 v[228:229], off
	s_waitcnt vmcnt(8)
	s_waitcnt lgkmcnt(0)
	s_barrier
	s_setprio 1
	s_waitcnt lgkmcnt(0)
	v_mfma_f32_16x16x32_bf16 v[124:127], v[128:131], v[188:191], v[124:127]
	v_mfma_f32_16x16x32_bf16 v[120:123], v[136:139], v[188:191], v[120:123]
	v_mfma_f32_16x16x32_bf16 v[108:111], v[128:131], v[200:203], v[108:111]
	v_mfma_f32_16x16x32_bf16 v[104:107], v[136:139], v[200:203], v[104:107]
	v_mfma_f32_16x16x32_bf16 v[92:95], v[128:131], v[208:211], v[92:95]
	v_mfma_f32_16x16x32_bf16 v[88:91], v[136:139], v[208:211], v[88:91]
	v_mfma_f32_16x16x32_bf16 v[76:79], v[128:131], v[216:219], v[76:79]
	v_mfma_f32_16x16x32_bf16 v[72:75], v[136:139], v[216:219], v[72:75]
	v_mfma_f32_16x16x32_bf16 v[124:127], v[132:135], v[196:199], v[124:127]
	v_mfma_f32_16x16x32_bf16 v[120:123], v[156:159], v[196:199], v[120:123]
	v_mfma_f32_16x16x32_bf16 v[108:111], v[132:135], v[204:207], v[108:111]
	v_mfma_f32_16x16x32_bf16 v[104:107], v[156:159], v[204:207], v[104:107]
	v_mfma_f32_16x16x32_bf16 v[92:95], v[132:135], v[212:215], v[92:95]
	v_mfma_f32_16x16x32_bf16 v[88:91], v[156:159], v[212:215], v[88:91]
	v_mfma_f32_16x16x32_bf16 v[76:79], v[132:135], v[220:223], v[76:79]
	v_mfma_f32_16x16x32_bf16 v[72:75], v[156:159], v[220:223], v[72:75]
	v_mfma_f32_16x16x32_bf16 v[116:119], v[172:175], v[188:191], v[116:119]
	v_mfma_f32_16x16x32_bf16 v[112:115], v[180:183], v[188:191], v[112:115]
	v_mfma_f32_16x16x32_bf16 v[100:103], v[172:175], v[200:203], v[100:103]
	v_mfma_f32_16x16x32_bf16 v[96:99], v[180:183], v[200:203], v[96:99]
	v_mfma_f32_16x16x32_bf16 v[84:87], v[172:175], v[208:211], v[84:87]
	v_mfma_f32_16x16x32_bf16 v[80:83], v[180:183], v[208:211], v[80:83]
	v_mfma_f32_16x16x32_bf16 v[68:71], v[172:175], v[216:219], v[68:71]
	v_mfma_f32_16x16x32_bf16 v[64:67], v[180:183], v[216:219], v[64:67]
	v_mfma_f32_16x16x32_bf16 v[116:119], v[176:179], v[196:199], v[116:119]
	v_mfma_f32_16x16x32_bf16 v[112:115], v[184:187], v[196:199], v[112:115]
	v_mfma_f32_16x16x32_bf16 v[100:103], v[176:179], v[204:207], v[100:103]
	v_mfma_f32_16x16x32_bf16 v[96:99], v[184:187], v[204:207], v[96:99]
	v_mfma_f32_16x16x32_bf16 v[84:87], v[176:179], v[212:215], v[84:87]
	v_mfma_f32_16x16x32_bf16 v[80:83], v[184:187], v[212:215], v[80:83]
	v_mfma_f32_16x16x32_bf16 v[68:71], v[176:179], v[220:223], v[68:71]
	v_mfma_f32_16x16x32_bf16 v[64:67], v[184:187], v[220:223], v[64:67]
	s_setprio 0
	s_barrier
	s_add_i32 s22, s56, s26
	v_lshl_add_u64 v[160:161], v[160:161], 0, s[12:13]
	s_mov_b32 m0, s22
	ds_read_b128 v[188:191], v167 offset:49152
	ds_read_b128 v[196:199], v167 offset:50176
	ds_read_b128 v[200:203], v167 offset:51200
	ds_read_b128 v[204:207], v167 offset:52224
	ds_read_b128 v[208:211], v167 offset:53248
	ds_read_b128 v[212:215], v167 offset:54272
	ds_read_b128 v[216:219], v167 offset:55296
	ds_read_b128 v[220:223], v167 offset:56320
	global_load_lds_dwordx4 v[160:161], off
	s_add_i32 m0, s22, 0x2000
	s_add_u32 s2, s2, 0xb0080
	v_lshl_add_u64 v[160:161], v[192:193], 0, s[12:13]
	s_addc_u32 s3, s3, 0
	s_add_i32 s22, s57, s26
	global_load_lds_dwordx4 v[160:161], off
	v_lshl_add_u64 v[160:161], s[2:3], 0, v[150:151]
	s_mov_b32 m0, s22
	s_nop 0
	global_load_lds_dwordx4 v[160:161], off
	v_lshl_add_u64 v[160:161], s[2:3], 0, v[154:155]
	s_add_i32 m0, s22, 0x2000
	s_nop 0
	global_load_lds_dwordx4 v[160:161], off
	v_lshl_add_u64 v[160:161], v[224:225], 0, s[12:13]
	s_mov_b32 m0, s36
	s_nop 0
	global_load_lds_dwordx4 v[160:161], off
	v_lshl_add_u64 v[160:161], v[226:227], 0, s[12:13]
	s_mov_b32 m0, s37
	s_nop 0
	global_load_lds_dwordx4 v[160:161], off
	s_waitcnt vmcnt(8)
	s_waitcnt lgkmcnt(0)
	s_barrier
	s_setprio 1
	s_waitcnt lgkmcnt(0)
	v_mfma_f32_16x16x32_bf16 v[60:63], v[128:131], v[188:191], v[60:63]
	v_mfma_f32_16x16x32_bf16 v[56:59], v[136:139], v[188:191], v[56:59]
	v_mfma_f32_16x16x32_bf16 v[44:47], v[128:131], v[200:203], v[44:47]
	v_mfma_f32_16x16x32_bf16 v[40:43], v[136:139], v[200:203], v[40:43]
	v_mfma_f32_16x16x32_bf16 v[28:31], v[128:131], v[208:211], v[28:31]
	v_mfma_f32_16x16x32_bf16 v[24:27], v[136:139], v[208:211], v[24:27]
	v_mfma_f32_16x16x32_bf16 v[12:15], v[128:131], v[216:219], v[12:15]
	v_mfma_f32_16x16x32_bf16 v[8:11], v[136:139], v[216:219], v[8:11]
	v_mfma_f32_16x16x32_bf16 v[60:63], v[132:135], v[196:199], v[60:63]
	v_mfma_f32_16x16x32_bf16 v[56:59], v[156:159], v[196:199], v[56:59]
	v_mfma_f32_16x16x32_bf16 v[44:47], v[132:135], v[204:207], v[44:47]
	v_mfma_f32_16x16x32_bf16 v[40:43], v[156:159], v[204:207], v[40:43]
	v_mfma_f32_16x16x32_bf16 v[28:31], v[132:135], v[212:215], v[28:31]
	v_mfma_f32_16x16x32_bf16 v[24:27], v[156:159], v[212:215], v[24:27]
	v_mfma_f32_16x16x32_bf16 v[12:15], v[132:135], v[220:223], v[12:15]
	v_mfma_f32_16x16x32_bf16 v[8:11], v[156:159], v[220:223], v[8:11]
	v_mfma_f32_16x16x32_bf16 v[52:55], v[172:175], v[188:191], v[52:55]
	v_mfma_f32_16x16x32_bf16 v[48:51], v[180:183], v[188:191], v[48:51]
	v_mfma_f32_16x16x32_bf16 v[36:39], v[172:175], v[200:203], v[36:39]
	v_mfma_f32_16x16x32_bf16 v[32:35], v[180:183], v[200:203], v[32:35]
	v_mfma_f32_16x16x32_bf16 v[20:23], v[172:175], v[208:211], v[20:23]
	v_mfma_f32_16x16x32_bf16 v[16:19], v[180:183], v[208:211], v[16:19]
	v_mfma_f32_16x16x32_bf16 v[4:7], v[172:175], v[216:219], v[4:7]
	v_mfma_f32_16x16x32_bf16 v[0:3], v[180:183], v[216:219], v[0:3]
	v_mfma_f32_16x16x32_bf16 v[52:55], v[176:179], v[196:199], v[52:55]
	v_mfma_f32_16x16x32_bf16 v[48:51], v[184:187], v[196:199], v[48:51]
	v_mfma_f32_16x16x32_bf16 v[36:39], v[176:179], v[204:207], v[36:39]
	v_mfma_f32_16x16x32_bf16 v[32:35], v[184:187], v[204:207], v[32:35]
	v_mfma_f32_16x16x32_bf16 v[20:23], v[176:179], v[212:215], v[20:23]
	v_mfma_f32_16x16x32_bf16 v[16:19], v[184:187], v[212:215], v[16:19]
	v_mfma_f32_16x16x32_bf16 v[4:7], v[176:179], v[220:223], v[4:7]
	v_mfma_f32_16x16x32_bf16 v[0:3], v[184:187], v[220:223], v[0:3]
	s_setprio 0
	s_barrier
	s_add_i32 s55, s55, 2
	s_add_u32 s14, s14, 0x100
	s_addc_u32 s15, s15, 0
	s_add_u32 s53, s53, 0x100
	s_addc_u32 s54, s54, 0
	s_cmp_gt_u32 s55, 41
	s_cbranch_scc0 .LBB0_891
